# stack on v056: P9 LDS-staged coalesced epilogue + P2 branch-free epilogue + attention back-edge rotation + P10 k-tile boundary rotation + P2 low-rank tiles last with dedicated cheap tile
# baseline (speedup 1.0000x reference)
; template <bool SWAP>
; DI void gemm_tile(const bf16_t* __restrict__ A, int lda, const bf16_t* __restrict__ Bt, int ldb, int K, f32x16 (&acc)[2][2], bf16_t* As, bf16_t* Bs_unused) {
;     ...
;   const int nk = K >> 6;
;   load_stage(ra0, rb0, 0); load_stage(ra1, rb1, 1);
;   __syncthreads();
;   write_stage(ra0, rb0, 0);
;   load_stage(ra0, rb0, 2);
;   __syncthreads();
; DI void phase_down(const Params& p, int g, char* smem, int bid, int nb) {
;     ...
;     f32x16 acc[2][2]; zero_acc(acc);
;     gemm_tile<false>(U + (size_t)mt * 128 * 4096, 4096, WD + (size_t)nt * 128 * 4096, 4096, 4096, acc, As, Bs);
.LBB0_177:
	s_ashr_i32 s7, s6, 31
	s_lshl_b64 s[8:9], s[6:7], 20
	v_mov_b32_e32 v54, v195
	s_add_u32 s16, s94, s8
	s_addc_u32 s17, s95, s9
	v_ashrrev_i32_e32 v32, 3, v54
	s_ashr_i32 s1, s0, 31
	v_ashrrev_i32_e32 v33, 31, v32
	s_lshl_b64 s[10:11], s[0:1], 20
	v_readlane_b32 s1, v235, 50
	v_lshlrev_b64 v[34:35], 13, v[32:33]
	v_lshlrev_b32_e32 v2, 4, v54
	s_add_u32 s18, s1, s10
	v_readlane_b32 s1, v235, 51
	v_lshl_add_u64 v[0:1], s[16:17], 0, v[34:35]
	v_and_b32_e32 v192, 0x70, v2
	s_addc_u32 s19, s1, s11
	v_lshl_add_u64 v[36:37], v[0:1], 0, v[192:193]
	s_mov_b32 s1, 0x40000
	v_lshl_add_u64 v[0:1], s[18:19], 0, v[34:35]
	v_add_co_u32_e32 v40, vcc, s1, v36
	v_lshl_add_u64 v[38:39], v[0:1], 0, v[192:193]
	s_nop 0
	v_addc_co_u32_e32 v41, vcc, 0, v37, vcc
	v_add_co_u32_e32 v42, vcc, s1, v38
	s_mov_b32 s1, 0x80000
	s_nop 0
	v_addc_co_u32_e32 v43, vcc, 0, v39, vcc
	v_add_co_u32_e32 v44, vcc, s1, v36
	s_waitcnt lgkmcnt(1)
	global_load_dwordx4 v[0:3], v[36:37], off
	s_waitcnt lgkmcnt(0)
	global_load_dwordx4 v[4:7], v[38:39], off
	v_addc_co_u32_e32 v45, vcc, 0, v37, vcc
	v_add_co_u32_e32 v46, vcc, s1, v38
	s_mov_b32 s1, 0xc0000
	s_nop 0
	v_addc_co_u32_e32 v47, vcc, 0, v39, vcc
	v_add_co_u32_e32 v48, vcc, s1, v36
	global_load_dwordx4 v[8:11], v[40:41], off
	global_load_dwordx4 v[12:15], v[42:43], off
	v_addc_co_u32_e32 v49, vcc, 0, v37, vcc
	v_add_co_u32_e32 v50, vcc, s1, v38
	global_load_dwordx4 v[16:19], v[44:45], off
	global_load_dwordx4 v[20:23], v[46:47], off
	v_addc_co_u32_e32 v51, vcc, 0, v39, vcc
	global_load_dwordx4 v[24:27], v[48:49], off
	global_load_dwordx4 v[28:31], v[50:51], off
	global_load_dwordx4 v[64:67], v[36:37], off offset:128
	global_load_dwordx4 v[76:79], v[40:41], off offset:128
	global_load_dwordx4 v[92:95], v[44:45], off offset:128
	global_load_dwordx4 v[108:111], v[48:49], off offset:128
	global_load_dwordx4 v[72:75], v[38:39], off offset:128
	global_load_dwordx4 v[88:91], v[42:43], off offset:128
	global_load_dwordx4 v[104:107], v[46:47], off offset:128
	global_load_dwordx4 v[120:123], v[50:51], off offset:128
	s_barrier
	global_load_dwordx4 v[68:71], v[36:37], off offset:256
	global_load_dwordx4 v[80:83], v[38:39], off offset:256
	global_load_dwordx4 v[84:87], v[40:41], off offset:256
	global_load_dwordx4 v[96:99], v[42:43], off offset:256
	global_load_dwordx4 v[100:103], v[44:45], off offset:256
	global_load_dwordx4 v[112:115], v[46:47], off offset:256
	global_load_dwordx4 v[116:119], v[48:49], off offset:256
	global_load_dwordx4 v[124:127], v[50:51], off offset:256
	v_lshrrev_b32_e32 v52, 2, v54
	v_mul_lo_u32 v56, v32, s71
	v_and_b32_e32 v33, 0x5f, v54
	v_and_b32_e32 v32, 8, v52
	v_add3_u32 v164, 32, v56, v192
	s_add_u32 s10, s96, s10
	v_lshrrev_b32_e32 v53, 1, v54
	v_and_b32_e32 v55, 31, v54
	s_addc_u32 s11, s97, s11
	v_and_or_b32 v52, v53, s80, v55
	s_add_u32 s8, s96, s8
	v_mad_u64_u32 v[52:53], s[16:17], v52, s72, v[32:33]
	s_addc_u32 s9, s97, s9
	v_lshl_add_u32 v165, v52, 1, 32
	v_add_u32_e32 v167, 0xd800, v164
	v_lshl_add_u64 v[152:153], s[10:11], 0, v[34:35]
	v_lshl_add_u64 v[154:155], s[8:9], 0, v[34:35]
	s_mov_b32 s1, -2
	s_waitcnt vmcnt(23)
	ds_write_b128 v164, v[0:3]
	s_waitcnt vmcnt(21)
	ds_write_b128 v164, v[8:11] offset:4608
	s_waitcnt vmcnt(19)
	ds_write_b128 v164, v[16:19] offset:9216
	s_waitcnt vmcnt(17)
	ds_write_b128 v164, v[24:27] offset:13824
	ds_write_b128 v164, v[4:7] offset:18432
	ds_write_b128 v164, v[12:15] offset:23040
	ds_write_b128 v164, v[20:23] offset:27648
	s_waitcnt vmcnt(16)
	ds_write_b128 v164, v[28:31] offset:32256
	v_mad_u32_u24 v0, v33, s72, v32
	v_lshl_add_u32 v166, v0, 1, 32
	v_and_b32_e32 v0, 7, v54
	v_lshlrev_b32_e32 v192, 4, v0
	v_mov_b32_e32 v0, 0
	v_mov_b32_e32 v1, v0
	v_mov_b32_e32 v2, v0
	v_mov_b32_e32 v3, v0
	v_mov_b32_e32 v4, v0
	v_mov_b32_e32 v5, v0
	v_mov_b32_e32 v6, v0
	v_mov_b32_e32 v7, v0
	v_mov_b32_e32 v8, v0
	v_mov_b32_e32 v9, v0
	v_mov_b32_e32 v10, v0
	v_mov_b32_e32 v11, v0
	v_mov_b32_e32 v12, v0
	v_mov_b32_e32 v13, v0
	v_mov_b32_e32 v14, v0
	v_mov_b32_e32 v15, v0
	v_mov_b32_e32 v32, v0
	v_mov_b32_e32 v33, v0
	v_mov_b32_e32 v34, v0
	v_mov_b32_e32 v35, v0
	v_mov_b32_e32 v36, v0
	v_mov_b32_e32 v37, v0
	v_mov_b32_e32 v38, v0
	v_mov_b32_e32 v39, v0
	v_mov_b32_e32 v40, v0
	v_mov_b32_e32 v41, v0
	v_mov_b32_e32 v42, v0
	v_mov_b32_e32 v43, v0
	v_mov_b32_e32 v44, v0
	v_mov_b32_e32 v45, v0
	v_mov_b32_e32 v46, v0
	v_mov_b32_e32 v47, v0
	v_mov_b32_e32 v16, v0
	v_mov_b32_e32 v17, v0
	v_mov_b32_e32 v18, v0
	v_mov_b32_e32 v19, v0
	v_mov_b32_e32 v20, v0
	v_mov_b32_e32 v21, v0
	v_mov_b32_e32 v22, v0
	v_mov_b32_e32 v23, v0
	v_mov_b32_e32 v24, v0
	v_mov_b32_e32 v25, v0
	v_mov_b32_e32 v26, v0
	v_mov_b32_e32 v27, v0
	v_mov_b32_e32 v28, v0
	v_mov_b32_e32 v29, v0
	v_mov_b32_e32 v30, v0
	v_mov_b32_e32 v31, v0
	v_mov_b32_e32 v48, v0
	v_mov_b32_e32 v49, v0
	v_mov_b32_e32 v50, v0
	v_mov_b32_e32 v51, v0
	v_mov_b32_e32 v52, v0
	v_mov_b32_e32 v53, v0
	v_mov_b32_e32 v54, v0
	v_mov_b32_e32 v55, v0
	v_mov_b32_e32 v56, v0
	v_mov_b32_e32 v57, v0
	v_mov_b32_e32 v58, v0
	v_mov_b32_e32 v59, v0
	v_mov_b32_e32 v60, v0
	v_mov_b32_e32 v61, v0
	v_mov_b32_e32 v62, v0
	v_mov_b32_e32 v63, v0
	s_waitcnt lgkmcnt(0)
	s_barrier
	ds_read_b128 v[168:171], v166 offset:18432
	ds_read_b128 v[172:175], v166 offset:23040
	ds_read_b128 v[176:179], v165
	ds_read_b128 v[180:183], v165 offset:4608
	s_branch .LBB0_179
; template <bool SWAP>
; DI void gemm_tile(const bf16_t* __restrict__ A, int lda, const bf16_t* __restrict__ Bt, int ldb, int K, f32x16 (&acc)[2][2], bf16_t* As, bf16_t* Bs_unused) {
;     ...
;   auto step = [&](int buf, u32x4 (&ra)[4], u32x4 (&rb)[4], bool do_write, bool do_load, int tload) __attribute__((always_inline)) {
;     const bf16_t* pa = As + buf * 2 * GT_IMG + pao; const bf16_t* pb = As + buf * 2 * GT_IMG + pbo;
;     bf16_t* Ad = As + (buf ^ 1) * 2 * GT_IMG; bf16_t* Bd = Ad + GT_IMG;
;     bf16x8 F0[4], F1[4];
;     frag_read(F0, pa, pb, 0);
;     __builtin_amdgcn_sched_barrier(0);
;     frag_read(F1, pa, pb, 16);
;     mfma4(F0);
;     __builtin_amdgcn_sched_barrier(0);
;     frag_read(F0, pa, pb, 32);
;     mfma4(F1);
;     if (do_write) {
; #pragma unroll
;       for (int i = 0; i < 4; ++i) *(u32x4*)(Ad + (lr + 32 * i) * 72 + lc) = ra[i];
;     }
;     __builtin_amdgcn_sched_barrier(0);
;     frag_read(F1, pa, pb, 48);
;     mfma4(F0);
;     if (do_write) {
; #pragma unroll
;       for (int i = 0; i < 4; ++i) *(u32x4*)(Bd + (lr + 32 * i) * 72 + lc) = rb[i];
;     }
;     __builtin_amdgcn_sched_barrier(0);
;     mfma4(F1);
;     if (do_load) load_stage(ra, rb, tload);
;     __builtin_amdgcn_sched_barrier(0);
;   };
;     ...
;   for (int kt = 0; kt < nk; kt += 2) {
;     step(0, ra1, rb1, true, kt + 3 < nk, kt + 3);
;     __syncthreads();
;     step(1, ra0, rb0, kt + 2 < nk, kt + 4 < nk, kt + 4);
;     __syncthreads();
.LBB0_178:
	v_lshl_add_u64 v[152:153], v[152:153], 0, s[66:67]
	s_andn2_b64 vcc, exec, s[8:9]
	v_lshl_add_u64 v[154:155], v[154:155], 0, s[66:67]
	s_cbranch_vccnz .LBB0_179
	s_waitcnt lgkmcnt(0)
	s_branch .LBB0_172
.LBB0_179:
	s_add_i32 s1, s1, 2
	s_cmp_gt_u32 s1, 60
	s_waitcnt lgkmcnt(1)
	v_mfma_f32_32x32x16_bf16 v[48:63], v[176:179], v[168:171], v[48:63]
	v_mfma_f32_32x32x16_bf16 v[16:31], v[176:179], v[172:175], v[16:31]
	s_waitcnt lgkmcnt(0)
	v_mfma_f32_32x32x16_bf16 v[32:47], v[180:183], v[168:171], v[32:47]
	ds_read_b128 v[128:131], v166 offset:18464
	ds_read_b128 v[136:139], v166 offset:23072
	ds_read_b128 v[144:147], v165 offset:32
	ds_read_b128 v[148:151], v165 offset:4640
	v_mfma_f32_32x32x16_bf16 v[0:15], v[180:183], v[172:175], v[0:15]
	s_waitcnt lgkmcnt(1)
	v_mfma_f32_32x32x16_bf16 v[48:63], v[144:147], v[128:131], v[48:63]
	v_mfma_f32_32x32x16_bf16 v[16:31], v[144:147], v[136:139], v[16:31]
	s_waitcnt lgkmcnt(0)
	v_mfma_f32_32x32x16_bf16 v[32:47], v[148:151], v[128:131], v[32:47]
	ds_read_b128 v[128:131], v166 offset:18496
	ds_read_b128 v[132:135], v166 offset:23104
	ds_read_b128 v[140:143], v165 offset:64
	ds_read_b128 v[144:147], v165 offset:4672
	s_waitcnt vmcnt(7)
	ds_write_b128 v164, v[64:67] offset:36864
	s_waitcnt vmcnt(5)
	ds_write_b128 v164, v[76:79] offset:41472
	s_waitcnt vmcnt(3)
	ds_write_b128 v164, v[92:95] offset:46080
	s_waitcnt vmcnt(1)
	ds_write_b128 v164, v[108:111] offset:50688
	v_mfma_f32_32x32x16_bf16 v[0:15], v[148:151], v[136:139], v[0:15]
	s_waitcnt lgkmcnt(5)
	v_mfma_f32_32x32x16_bf16 v[48:63], v[140:143], v[128:131], v[48:63]
	v_mfma_f32_32x32x16_bf16 v[16:31], v[140:143], v[132:135], v[16:31]
	s_waitcnt lgkmcnt(4)
	v_mfma_f32_32x32x16_bf16 v[32:47], v[144:147], v[128:131], v[32:47]
	ds_read_b128 v[128:131], v166 offset:18528
	ds_read_b128 v[136:139], v166 offset:23136
	ds_read_b128 v[140:143], v165 offset:96
	ds_read_b128 v[148:151], v165 offset:4704
	s_waitcnt vmcnt(11)
	ds_write_b128 v164, v[72:75] offset:55296
	s_waitcnt vmcnt(10)
	ds_write_b128 v164, v[88:91] offset:59904
	s_waitcnt vmcnt(9)
	ds_write_b128 v164, v[104:107] offset:64512
	s_waitcnt vmcnt(0)
	ds_write_b128 v167, v[120:123] offset:13824
	v_mfma_f32_32x32x16_bf16 v[0:15], v[144:147], v[132:135], v[0:15]
	s_waitcnt lgkmcnt(0)
	s_barrier
	ds_read_b128 v[168:171], v166 offset:55296
	ds_read_b128 v[172:175], v166 offset:59904
	ds_read_b128 v[176:179], v165 offset:36864
	ds_read_b128 v[180:183], v165 offset:41472
	v_mfma_f32_32x32x16_bf16 v[48:63], v[140:143], v[128:131], v[48:63]
	v_lshl_add_u64 v[158:159], v[154:155], 0, v[192:193]
	v_lshl_add_u64 v[156:157], v[152:153], 0, v[192:193]
	v_mfma_f32_32x32x16_bf16 v[16:31], v[140:143], v[136:139], v[16:31]
	v_mfma_f32_32x32x16_bf16 v[32:47], v[148:151], v[128:131], v[32:47]
	v_mfma_f32_32x32x16_bf16 v[0:15], v[148:151], v[136:139], v[0:15]
	s_cbranch_scc1 .LBB0_181
	v_add_co_u32_e32 v64, vcc, 0x46c8000, v158
	s_nop 1
	v_addc_co_u32_e32 v65, vcc, 0, v159, vcc
	v_add_co_u32_e32 v72, vcc, 0x1e40000, v156
	global_load_dwordx4 v[64:67], v[64:65], off offset:384
	s_nop 0
	v_addc_co_u32_e32 v73, vcc, 0, v157, vcc
	v_add_co_u32_e32 v76, vcc, 0x4708000, v158
	global_load_dwordx4 v[72:75], v[72:73], off offset:384
	s_nop 0
	v_addc_co_u32_e32 v77, vcc, 0, v159, vcc
	v_add_co_u32_e32 v88, vcc, 0x1e80000, v156
	global_load_dwordx4 v[76:79], v[76:77], off offset:384
	s_nop 0
	v_addc_co_u32_e32 v89, vcc, 0, v157, vcc
	v_add_co_u32_e32 v92, vcc, 0x4748000, v158
	global_load_dwordx4 v[88:91], v[88:89], off offset:384
	s_nop 0
	v_addc_co_u32_e32 v93, vcc, 0, v159, vcc
	v_add_co_u32_e32 v104, vcc, 0x1ec0000, v156
	global_load_dwordx4 v[92:95], v[92:93], off offset:384
	s_nop 0
	v_addc_co_u32_e32 v105, vcc, 0, v157, vcc
	v_add_co_u32_e32 v108, vcc, 0x4788000, v158
	global_load_dwordx4 v[104:107], v[104:105], off offset:384
	s_nop 0
	v_addc_co_u32_e32 v109, vcc, 0, v159, vcc
	v_add_co_u32_e32 v120, vcc, 0x1f00000, v156
	global_load_dwordx4 v[108:111], v[108:109], off offset:384
	s_nop 0
	v_addc_co_u32_e32 v121, vcc, 0, v157, vcc
	global_load_dwordx4 v[120:123], v[120:121], off offset:384
.LBB0_181:
	s_cmp_lt_u32 s1, 62
	s_cselect_b64 s[10:11], -1, 0
	s_cmp_gt_u32 s1, 61
	s_cselect_b64 s[8:9], -1, 0
	s_waitcnt lgkmcnt(1)
	v_mfma_f32_32x32x16_bf16 v[48:63], v[176:179], v[168:171], v[48:63]
	v_mfma_f32_32x32x16_bf16 v[16:31], v[176:179], v[172:175], v[16:31]
	s_waitcnt lgkmcnt(0)
	v_mfma_f32_32x32x16_bf16 v[32:47], v[180:183], v[168:171], v[32:47]
	ds_read_b128 v[128:131], v166 offset:55328
	ds_read_b128 v[144:147], v166 offset:59936
	ds_read_b128 v[136:139], v165 offset:36896
	ds_read_b128 v[148:151], v165 offset:41504
	v_mfma_f32_32x32x16_bf16 v[0:15], v[180:183], v[172:175], v[0:15]
	s_waitcnt lgkmcnt(1)
	v_mfma_f32_32x32x16_bf16 v[48:63], v[136:139], v[128:131], v[48:63]
	s_and_b64 vcc, exec, s[8:9]
	v_mfma_f32_32x32x16_bf16 v[16:31], v[136:139], v[144:147], v[16:31]
	s_waitcnt lgkmcnt(0)
	v_mfma_f32_32x32x16_bf16 v[32:47], v[148:151], v[128:131], v[32:47]
	ds_read_b128 v[136:139], v166 offset:55360
	ds_read_b128 v[128:131], v166 offset:59968
	ds_read_b128 v[140:143], v165 offset:36928
	ds_read_b128 v[132:135], v165 offset:41536
	v_mfma_f32_32x32x16_bf16 v[0:15], v[148:151], v[144:147], v[0:15]
	s_cbranch_vccnz .LBB0_183
	s_waitcnt vmcnt(7)
	ds_write_b128 v164, v[68:71]
	s_waitcnt vmcnt(5)
	ds_write_b128 v164, v[84:87] offset:4608
	s_waitcnt vmcnt(3)
	ds_write_b128 v164, v[100:103] offset:9216
	s_waitcnt vmcnt(1)
	ds_write_b128 v164, v[116:119] offset:13824

; template <bool SWAP>
; DI void gemm_tile(const bf16_t* __restrict__ A, int lda, const bf16_t* __restrict__ Bt, int ldb, int K, f32x16 (&acc)[2][2], bf16_t* As, bf16_t* Bs_unused) {
;     ...
;     __builtin_amdgcn_sched_barrier(0);
;     frag_read(F1, pa, pb, 48);
;     mfma4(F0);
;     if (do_write) {
; #pragma unroll
;       for (int i = 0; i < 4; ++i) *(u32x4*)(Bd + (lr + 32 * i) * 72 + lc) = rb[i];
;     }
;     __builtin_amdgcn_sched_barrier(0);
;     mfma4(F1);
;     if (do_load) load_stage(ra, rb, tload);
;     __builtin_amdgcn_sched_barrier(0);
;   };
;     ...
;     step(1, ra0, rb0, kt + 2 < nk, kt + 4 < nk, kt + 4);
;     __syncthreads();
.LBB0_185:
	s_cmp_gt_u32 s1, 59
	s_waitcnt lgkmcnt(0)
	s_barrier
	ds_read_b128 v[168:171], v166 offset:18432
	ds_read_b128 v[172:175], v166 offset:23040
	ds_read_b128 v[176:179], v165
	ds_read_b128 v[180:183], v165 offset:4608
	v_mfma_f32_32x32x16_bf16 v[48:63], v[148:151], v[140:143], v[48:63]
	v_mfma_f32_32x32x16_bf16 v[16:31], v[148:151], v[136:139], v[16:31]
	v_mfma_f32_32x32x16_bf16 v[32:47], v[144:147], v[140:143], v[32:47]
	v_mfma_f32_32x32x16_bf16 v[0:15], v[144:147], v[136:139], v[0:15]
	s_cbranch_scc1 .LBB0_178
	s_waitcnt vmcnt(7)
	v_add_co_u32_e32 v68, vcc, 0x46c8000, v158
	s_nop 1
	v_addc_co_u32_e32 v69, vcc, 0, v159, vcc
	s_waitcnt vmcnt(6)
	v_add_co_u32_e32 v80, vcc, 0x1e40000, v156
	global_load_dwordx4 v[68:71], v[68:69], off offset:512
	s_nop 0
	v_addc_co_u32_e32 v81, vcc, 0, v157, vcc
	s_waitcnt vmcnt(6)
	v_add_co_u32_e32 v84, vcc, 0x4708000, v158
	global_load_dwordx4 v[80:83], v[80:81], off offset:512
	s_nop 0
	v_addc_co_u32_e32 v85, vcc, 0, v159, vcc
	s_waitcnt vmcnt(6)
	v_add_co_u32_e32 v96, vcc, 0x1e80000, v156
	global_load_dwordx4 v[84:87], v[84:85], off offset:512
	s_nop 0
	v_addc_co_u32_e32 v97, vcc, 0, v157, vcc
	s_waitcnt vmcnt(6)
	v_add_co_u32_e32 v100, vcc, 0x4748000, v158
	global_load_dwordx4 v[96:99], v[96:97], off offset:512
	s_nop 0
	v_addc_co_u32_e32 v101, vcc, 0, v159, vcc
	s_waitcnt vmcnt(6)
	v_add_co_u32_e32 v112, vcc, 0x1ec0000, v156
	global_load_dwordx4 v[100:103], v[100:101], off offset:512
	s_nop 0
	v_addc_co_u32_e32 v113, vcc, 0, v157, vcc
	s_waitcnt vmcnt(6)
	v_add_co_u32_e32 v116, vcc, 0x4788000, v158
	global_load_dwordx4 v[112:115], v[112:113], off offset:512
	s_nop 0
	v_addc_co_u32_e32 v117, vcc, 0, v159, vcc
	s_waitcnt vmcnt(6)
	v_add_co_u32_e32 v124, vcc, 0x1f00000, v156
	global_load_dwordx4 v[116:119], v[116:117], off offset:512
	s_nop 0
	v_addc_co_u32_e32 v125, vcc, 0, v157, vcc
	global_load_dwordx4 v[124:127], v[124:125], off offset:512
	s_branch .LBB0_178

; #define MFMA32(a, b, c) __builtin_amdgcn_mfma_f32_32x32x16_bf16((a), (b), (c), 0, 0, 0)
; template <bool SWAP>
; DI void gemm_tile(const bf16_t* __restrict__ A, int lda, const bf16_t* __restrict__ Bt, int ldb, int K, f32x16 (&acc)[2][2], bf16_t* As, bf16_t* Bs_unused) {
;     ...
;   auto frag_read = [&](bf16x8 (&f)[4], const bf16_t* pa, const bf16_t* pb, int so) __attribute__((always_inline)) {
;     f[0] = *(const bf16x8*)(pa + so); f[1] = *(const bf16x8*)(pb + so); f[2] = *(const bf16x8*)(pb + 32 * 72 + so); f[3] = *(const bf16x8*)(pa + 32 * 72 + so);
;   };
;   auto mfma4 = [&](const bf16x8 (&f)[4]) __attribute__((always_inline)) {
;     if (SWAP) {
;       acc[0][0] = MFMA32(f[1], f[0], acc[0][0]); acc[0][1] = MFMA32(f[2], f[0], acc[0][1]);
;       acc[1][0] = MFMA32(f[1], f[3], acc[1][0]); acc[1][1] = MFMA32(f[2], f[3], acc[1][1]);
;     } else {
;       acc[0][0] = MFMA32(f[0], f[1], acc[0][0]); acc[0][1] = MFMA32(f[0], f[2], acc[0][1]);
;       acc[1][0] = MFMA32(f[3], f[1], acc[1][0]); acc[1][1] = MFMA32(f[3], f[2], acc[1][1]);
;     }
;   };
;   auto step = [&](int buf, u32x4 (&ra)[4], u32x4 (&rb)[4], bool do_write, bool do_load, int tload) __attribute__((always_inline)) {
;     const bf16_t* pa = As + buf * 2 * GT_IMG + pao; const bf16_t* pb = As + buf * 2 * GT_IMG + pbo;
;     bf16_t* Ad = As + (buf ^ 1) * 2 * GT_IMG; bf16_t* Bd = Ad + GT_IMG;
;     bf16x8 F0[4], F1[4];
;     frag_read(F0, pa, pb, 0);
;     __builtin_amdgcn_sched_barrier(0);
;     frag_read(F1, pa, pb, 16);
;     mfma4(F0);
;     __builtin_amdgcn_sched_barrier(0);
;     frag_read(F0, pa, pb, 32);
;     mfma4(F1);
;     ...
;   const int nk = K >> 6;
;   load_stage(ra0, rb0, 0); load_stage(ra1, rb1, 1);
;   __syncthreads();
;   write_stage(ra0, rb0, 0);
;   load_stage(ra0, rb0, 2);
;   __syncthreads();
.LBB0_193:
	s_ashr_i32 s7, s6, 31
	s_lshl_b64 s[8:9], s[6:7], 18
	v_mov_b32_e32 v34, v195
	s_add_u32 s8, s63, s8
	s_addc_u32 s9, s70, s9
	v_ashrrev_i32_e32 v32, 3, v34
	s_ashr_i32 s1, s0, 31
	v_ashrrev_i32_e32 v33, 31, v32
	s_lshl_b64 s[14:15], s[0:1], 18
	v_readlane_b32 s1, v235, 57
	v_lshlrev_b64 v[0:1], 11, v[32:33]
	s_waitcnt lgkmcnt(0)
	v_lshlrev_b32_e32 v4, 4, v34
	s_add_u32 s14, s1, s14
	v_readlane_b32 s1, v235, 58
	v_lshl_add_u64 v[2:3], s[8:9], 0, v[0:1]
	v_and_b32_e32 v192, 0x70, v4
	s_addc_u32 s15, s1, s15
	v_lshl_add_u64 v[80:81], v[2:3], 0, v[192:193]
	s_mov_b32 s1, 0x10000
	v_lshl_add_u64 v[0:1], s[14:15], 0, v[0:1]
	v_add_co_u32_e32 v84, vcc, s1, v80
	v_lshl_add_u64 v[82:83], v[0:1], 0, v[192:193]
	s_nop 0
	v_addc_co_u32_e32 v85, vcc, 0, v81, vcc
	v_add_co_u32_e32 v86, vcc, s1, v82
	s_mov_b32 s1, 0x20000
	s_nop 0
	v_addc_co_u32_e32 v87, vcc, 0, v83, vcc
	global_load_dwordx4 v[0:3], v[80:81], off
	global_load_dwordx4 v[4:7], v[82:83], off
	v_add_co_u32_e32 v88, vcc, s1, v80
	global_load_dwordx4 v[8:11], v[84:85], off
	global_load_dwordx4 v[12:15], v[86:87], off
	v_addc_co_u32_e32 v89, vcc, 0, v81, vcc
	v_add_co_u32_e32 v90, vcc, s1, v82
	s_mov_b32 s1, 0x30000
	s_nop 0
	v_addc_co_u32_e32 v91, vcc, 0, v83, vcc
	global_load_dwordx4 v[16:19], v[88:89], off
	global_load_dwordx4 v[20:23], v[90:91], off
	v_add_co_u32_e32 v92, vcc, s1, v80
	v_mul_lo_u32 v32, v32, s71
	s_nop 0
	v_addc_co_u32_e32 v93, vcc, 0, v81, vcc
	global_load_dwordx4 v[24:27], v[92:93], off
	v_add_co_u32_e32 v94, vcc, s1, v82
	v_add3_u32 v100, 32, v32, v192
	s_nop 0
	v_addc_co_u32_e32 v95, vcc, 0, v83, vcc
	global_load_dwordx4 v[28:31], v[94:95], off
	global_load_dwordx4 v[104:107], v[80:81], off offset:128
	global_load_dwordx4 v[108:111], v[82:83], off offset:128
	global_load_dwordx4 v[112:115], v[84:85], off offset:128
	global_load_dwordx4 v[116:119], v[86:87], off offset:128
	global_load_dwordx4 v[120:123], v[88:89], off offset:128
	global_load_dwordx4 v[124:127], v[90:91], off offset:128
	global_load_dwordx4 v[128:131], v[92:93], off offset:128
	global_load_dwordx4 v[132:135], v[94:95], off offset:128
	s_barrier
	v_add_u32_e32 v103, 0xd800, v100
	s_waitcnt vmcnt(15)
	ds_write_b128 v100, v[0:3]
	s_waitcnt vmcnt(14)
	ds_write_b128 v100, v[4:7] offset:18432
	s_waitcnt vmcnt(13)
	ds_write_b128 v100, v[8:11] offset:4608
	s_waitcnt vmcnt(12)
	ds_write_b128 v100, v[12:15] offset:23040
	s_waitcnt vmcnt(11)
	ds_write_b128 v100, v[16:19] offset:9216
	s_waitcnt vmcnt(10)
	ds_write_b128 v100, v[20:23] offset:27648
	s_waitcnt vmcnt(9)
	ds_write_b128 v100, v[24:27] offset:13824
	s_waitcnt vmcnt(8)
	ds_write_b128 v100, v[28:31] offset:32256
	global_load_dwordx4 v[136:139], v[80:81], off offset:256
	global_load_dwordx4 v[64:67], v[82:83], off offset:256
	global_load_dwordx4 v[140:143], v[84:85], off offset:256
	global_load_dwordx4 v[68:71], v[86:87], off offset:256
	global_load_dwordx4 v[144:147], v[88:89], off offset:256
	global_load_dwordx4 v[72:75], v[90:91], off offset:256
	global_load_dwordx4 v[148:151], v[92:93], off offset:256
	global_load_dwordx4 v[76:79], v[94:95], off offset:256
	v_lshrrev_b32_e32 v0, 2, v34
	v_lshrrev_b32_e32 v2, 1, v34
	v_and_b32_e32 v3, 31, v34
	v_and_b32_e32 v1, 0x5f, v34
	v_and_b32_e32 v0, 8, v0
	v_and_or_b32 v2, v2, s80, v3
	v_mad_u64_u32 v[2:3], s[8:9], v2, s72, v[0:1]
	v_lshl_add_u32 v101, v2, 1, 32
	v_mad_u32_u24 v0, v1, s72, v0
	s_waitcnt lgkmcnt(0)
	s_barrier
	v_lshl_add_u32 v102, v0, 1, 32
	ds_read_b128 v[0:3], v101
	ds_read_b128 v[4:7], v102 offset:18432
	ds_read_b128 v[8:11], v102 offset:23040
	ds_read_b128 v[12:15], v101 offset:4608
	ds_read_b128 v[152:155], v102 offset:18464
	ds_read_b128 v[156:159], v102 offset:23072
	ds_read_b128 v[160:163], v101 offset:32
	ds_read_b128 v[164:167], v101 offset:4640
	s_waitcnt lgkmcnt(6)
	v_mfma_f32_32x32x16_bf16 v[48:63], v[4:7], v[0:3], 0
	s_waitcnt lgkmcnt(5)
	v_mfma_f32_32x32x16_bf16 v[32:47], v[8:11], v[0:3], 0
	s_waitcnt lgkmcnt(4)
	v_mfma_f32_32x32x16_bf16 v[16:31], v[4:7], v[12:15], 0
	v_mfma_f32_32x32x16_bf16 v[0:15], v[8:11], v[12:15], 0
	s_waitcnt lgkmcnt(1)
	v_mfma_f32_32x32x16_bf16 v[48:63], v[152:155], v[160:163], v[48:63]
	v_mfma_f32_32x32x16_bf16 v[32:47], v[156:159], v[160:163], v[32:47]
	s_waitcnt lgkmcnt(0)
	v_mfma_f32_32x32x16_bf16 v[16:31], v[152:155], v[164:167], v[16:31]
	ds_read_b128 v[152:155], v102 offset:18496
	ds_read_b128 v[160:163], v102 offset:23104
	ds_read_b128 v[168:171], v101 offset:64
	ds_read_b128 v[172:175], v101 offset:4672
	s_waitcnt vmcnt(15)
	ds_write_b128 v100, v[104:107] offset:36864
	s_waitcnt vmcnt(13)
	ds_write_b128 v100, v[112:115] offset:41472
	s_waitcnt vmcnt(11)
	ds_write_b128 v100, v[120:123] offset:46080
	s_waitcnt vmcnt(9)
	ds_write_b128 v100, v[128:131] offset:50688
	v_mfma_f32_32x32x16_bf16 v[0:15], v[156:159], v[164:167], v[0:15]
	ds_read_b128 v[104:107], v102 offset:18528
	ds_read_b128 v[112:115], v102 offset:23136
	ds_read_b128 v[120:123], v101 offset:96
	ds_read_b128 v[128:131], v101 offset:4704
	s_waitcnt lgkmcnt(9)
	v_mfma_f32_32x32x16_bf16 v[48:63], v[152:155], v[168:171], v[48:63]
	ds_write_b128 v100, v[108:111] offset:55296
	ds_write_b128 v100, v[116:119] offset:59904
	ds_write_b128 v100, v[124:127] offset:64512
	s_waitcnt vmcnt(8)
	ds_write_b128 v103, v[132:135] offset:13824
	v_mfma_f32_32x32x16_bf16 v[32:47], v[160:163], v[168:171], v[32:47]
	s_waitcnt lgkmcnt(12)
	v_mfma_f32_32x32x16_bf16 v[16:31], v[152:155], v[172:175], v[16:31]
	v_mfma_f32_32x32x16_bf16 v[0:15], v[160:163], v[172:175], v[0:15]
	s_waitcnt lgkmcnt(0)
	s_barrier
; #define MFMA32(a, b, c) __builtin_amdgcn_mfma_f32_32x32x16_bf16((a), (b), (c), 0, 0, 0)
; template <bool SWAP>
; DI void gemm_tile(const bf16_t* __restrict__ A, int lda, const bf16_t* __restrict__ Bt, int ldb, int K, f32x16 (&acc)[2][2], bf16_t* As, bf16_t* Bs_unused) {
;     ...
;   auto frag_read = [&](bf16x8 (&f)[4], const bf16_t* pa, const bf16_t* pb, int so) __attribute__((always_inline)) {
;     f[0] = *(const bf16x8*)(pa + so); f[1] = *(const bf16x8*)(pb + so); f[2] = *(const bf16x8*)(pb + 32 * 72 + so); f[3] = *(const bf16x8*)(pa + 32 * 72 + so);
;   };
;   auto mfma4 = [&](const bf16x8 (&f)[4]) __attribute__((always_inline)) {
;     if (SWAP) {
;       acc[0][0] = MFMA32(f[1], f[0], acc[0][0]); acc[0][1] = MFMA32(f[2], f[0], acc[0][1]);
;       acc[1][0] = MFMA32(f[1], f[3], acc[1][0]); acc[1][1] = MFMA32(f[2], f[3], acc[1][1]);
;     } else {
;       acc[0][0] = MFMA32(f[0], f[1], acc[0][0]); acc[0][1] = MFMA32(f[0], f[2], acc[0][1]);
;       acc[1][0] = MFMA32(f[3], f[1], acc[1][0]); acc[1][1] = MFMA32(f[3], f[2], acc[1][1]);
;     }
;   };
;   auto step = [&](int buf, u32x4 (&ra)[4], u32x4 (&rb)[4], bool do_write, bool do_load, int tload) __attribute__((always_inline)) {
;     const bf16_t* pa = As + buf * 2 * GT_IMG + pao; const bf16_t* pb = As + buf * 2 * GT_IMG + pbo;
;     bf16_t* Ad = As + (buf ^ 1) * 2 * GT_IMG; bf16_t* Bd = Ad + GT_IMG;
;     bf16x8 F0[4], F1[4];
;     frag_read(F0, pa, pb, 0);
;     __builtin_amdgcn_sched_barrier(0);
;     frag_read(F1, pa, pb, 16);
;     mfma4(F0);
;     __builtin_amdgcn_sched_barrier(0);
;     frag_read(F0, pa, pb, 32);
;     mfma4(F1);
;     if (do_write) {
; #pragma unroll
;       for (int i = 0; i < 4; ++i) *(u32x4*)(Ad + (lr + 32 * i) * 72 + lc) = ra[i];
;     }
;     __builtin_amdgcn_sched_barrier(0);
;     frag_read(F1, pa, pb, 48);
;     mfma4(F0);
;     if (do_write) {
; #pragma unroll
;       for (int i = 0; i < 4; ++i) *(u32x4*)(Bd + (lr + 32 * i) * 72 + lc) = rb[i];
;     }
;     __builtin_amdgcn_sched_barrier(0);
;     mfma4(F1);
;     if (do_load) load_stage(ra, rb, tload);
;     __builtin_amdgcn_sched_barrier(0);
;   };
	ds_read_b128 v[152:155], v102 offset:55296
	ds_read_b128 v[156:159], v102 offset:59904
	ds_read_b128 v[160:163], v101 offset:36864
	ds_read_b128 v[164:167], v101 offset:41472
	v_mfma_f32_32x32x16_bf16 v[48:63], v[104:107], v[120:123], v[48:63]
	v_mfma_f32_32x32x16_bf16 v[32:47], v[112:115], v[120:123], v[32:47]
	v_mfma_f32_32x32x16_bf16 v[16:31], v[104:107], v[128:131], v[16:31]
	v_mfma_f32_32x32x16_bf16 v[0:15], v[112:115], v[128:131], v[0:15]
	global_load_dwordx4 v[104:107], v[80:81], off offset:384
	global_load_dwordx4 v[108:111], v[82:83], off offset:384
	global_load_dwordx4 v[112:115], v[84:85], off offset:384
	global_load_dwordx4 v[116:119], v[86:87], off offset:384
	global_load_dwordx4 v[120:123], v[88:89], off offset:384
	global_load_dwordx4 v[124:127], v[90:91], off offset:384
	global_load_dwordx4 v[128:131], v[92:93], off offset:384
	global_load_dwordx4 v[132:135], v[94:95], off offset:384
	s_waitcnt lgkmcnt(1)
	v_mfma_f32_32x32x16_bf16 v[48:63], v[152:155], v[160:163], v[48:63]
	v_mfma_f32_32x32x16_bf16 v[32:47], v[156:159], v[160:163], v[32:47]
	s_waitcnt lgkmcnt(0)
	v_mfma_f32_32x32x16_bf16 v[16:31], v[152:155], v[164:167], v[16:31]
	ds_read_b128 v[152:155], v102 offset:55328
	ds_read_b128 v[160:163], v102 offset:59936
	ds_read_b128 v[168:171], v101 offset:36896
	ds_read_b128 v[172:175], v101 offset:41504
	v_mfma_f32_32x32x16_bf16 v[0:15], v[156:159], v[164:167], v[0:15]
	s_waitcnt lgkmcnt(1)
	v_mfma_f32_32x32x16_bf16 v[48:63], v[152:155], v[168:171], v[48:63]
	v_mfma_f32_32x32x16_bf16 v[32:47], v[160:163], v[168:171], v[32:47]
	s_waitcnt lgkmcnt(0)
	v_mfma_f32_32x32x16_bf16 v[16:31], v[152:155], v[172:175], v[16:31]
	ds_read_b128 v[152:155], v102 offset:55360
	ds_read_b128 v[156:159], v102 offset:59968
	ds_read_b128 v[164:167], v101 offset:36928
	ds_read_b128 v[168:171], v101 offset:41536
	s_waitcnt vmcnt(15)
	ds_write_b128 v100, v[136:139]
	s_waitcnt vmcnt(13)
	ds_write_b128 v100, v[140:143] offset:4608
	s_waitcnt vmcnt(11)
	ds_write_b128 v100, v[144:147] offset:9216
	s_waitcnt vmcnt(9)
	ds_write_b128 v100, v[148:151] offset:13824
	v_mfma_f32_32x32x16_bf16 v[0:15], v[160:163], v[172:175], v[0:15]
	ds_read_b128 v[136:139], v102 offset:55392
	ds_read_b128 v[140:143], v102 offset:60000
	ds_read_b128 v[144:147], v101 offset:36960
	ds_read_b128 v[148:151], v101 offset:41568
	s_waitcnt lgkmcnt(9)
	v_mfma_f32_32x32x16_bf16 v[48:63], v[152:155], v[164:167], v[48:63]
	ds_write_b128 v100, v[64:67] offset:18432
	ds_write_b128 v100, v[68:71] offset:23040
	ds_write_b128 v100, v[72:75] offset:27648
	s_waitcnt vmcnt(8)
	ds_write_b128 v100, v[76:79] offset:32256
	v_mfma_f32_32x32x16_bf16 v[32:47], v[156:159], v[164:167], v[32:47]
	s_waitcnt lgkmcnt(12)
	v_mfma_f32_32x32x16_bf16 v[16:31], v[152:155], v[168:171], v[16:31]
	v_mfma_f32_32x32x16_bf16 v[0:15], v[156:159], v[168:171], v[0:15]
	s_waitcnt lgkmcnt(0)
	s_barrier
	ds_read_b128 v[152:155], v102 offset:18432
	ds_read_b128 v[156:159], v102 offset:23040
	ds_read_b128 v[160:163], v101
	ds_read_b128 v[164:167], v101 offset:4608
	v_mfma_f32_32x32x16_bf16 v[48:63], v[136:139], v[144:147], v[48:63]
	v_mfma_f32_32x32x16_bf16 v[32:47], v[140:143], v[144:147], v[32:47]
	v_mfma_f32_32x32x16_bf16 v[16:31], v[136:139], v[148:151], v[16:31]
	v_mfma_f32_32x32x16_bf16 v[0:15], v[140:143], v[148:151], v[0:15]
	global_load_dwordx4 v[64:67], v[80:81], off offset:512
	global_load_dwordx4 v[68:71], v[82:83], off offset:512
	global_load_dwordx4 v[72:75], v[84:85], off offset:512
	global_load_dwordx4 v[76:79], v[86:87], off offset:512
	global_load_dwordx4 v[136:139], v[88:89], off offset:512
	global_load_dwordx4 v[140:143], v[90:91], off offset:512
	global_load_dwordx4 v[144:147], v[92:93], off offset:512
	global_load_dwordx4 v[148:151], v[94:95], off offset:512
	s_waitcnt lgkmcnt(1)
	v_mfma_f32_32x32x16_bf16 v[48:63], v[152:155], v[160:163], v[48:63]
	v_mfma_f32_32x32x16_bf16 v[32:47], v[156:159], v[160:163], v[32:47]
	s_waitcnt lgkmcnt(0)
	v_mfma_f32_32x32x16_bf16 v[16:31], v[152:155], v[164:167], v[16:31]
	ds_read_b128 v[152:155], v102 offset:18464
	ds_read_b128 v[160:163], v102 offset:23072
	ds_read_b128 v[168:171], v101 offset:32
	ds_read_b128 v[172:175], v101 offset:4640
	v_mfma_f32_32x32x16_bf16 v[0:15], v[156:159], v[164:167], v[0:15]
	s_waitcnt lgkmcnt(1)
	v_mfma_f32_32x32x16_bf16 v[48:63], v[152:155], v[168:171], v[48:63]
	v_mfma_f32_32x32x16_bf16 v[32:47], v[160:163], v[168:171], v[32:47]
	s_waitcnt lgkmcnt(0)
	v_mfma_f32_32x32x16_bf16 v[16:31], v[152:155], v[172:175], v[16:31]
	ds_read_b128 v[152:155], v102 offset:18496
	ds_read_b128 v[156:159], v102 offset:23104
	ds_read_b128 v[164:167], v101 offset:64
	ds_read_b128 v[168:171], v101 offset:4672
	s_waitcnt vmcnt(15)
	ds_write_b128 v100, v[104:107] offset:36864
	s_waitcnt vmcnt(13)
	ds_write_b128 v100, v[112:115] offset:41472
	s_waitcnt vmcnt(11)
	ds_write_b128 v100, v[120:123] offset:46080
	s_waitcnt vmcnt(9)
	ds_write_b128 v100, v[128:131] offset:50688
	v_mfma_f32_32x32x16_bf16 v[0:15], v[160:163], v[172:175], v[0:15]
	ds_read_b128 v[104:107], v102 offset:18528
	ds_read_b128 v[112:115], v102 offset:23136
	ds_read_b128 v[120:123], v101 offset:96
	ds_read_b128 v[128:131], v101 offset:4704
	s_waitcnt lgkmcnt(9)
	v_mfma_f32_32x32x16_bf16 v[48:63], v[152:155], v[164:167], v[48:63]
	ds_write_b128 v100, v[108:111] offset:55296
	ds_write_b128 v100, v[116:119] offset:59904
	ds_write_b128 v100, v[124:127] offset:64512
	s_waitcnt vmcnt(8)
	ds_write_b128 v103, v[132:135] offset:13824
	v_mfma_f32_32x32x16_bf16 v[32:47], v[156:159], v[164:167], v[32:47]
	s_waitcnt lgkmcnt(12)
	v_mfma_f32_32x32x16_bf16 v[16:31], v[152:155], v[168:171], v[16:31]
	v_mfma_f32_32x32x16_bf16 v[0:15], v[156:159], v[168:171], v[0:15]
	s_waitcnt lgkmcnt(0)
	s_barrier
; #define MFMA32(a, b, c) __builtin_amdgcn_mfma_f32_32x32x16_bf16((a), (b), (c), 0, 0, 0)
; template <bool SWAP>
; DI void gemm_tile(const bf16_t* __restrict__ A, int lda, const bf16_t* __restrict__ Bt, int ldb, int K, f32x16 (&acc)[2][2], bf16_t* As, bf16_t* Bs_unused) {
;     ...
;   auto frag_read = [&](bf16x8 (&f)[4], const bf16_t* pa, const bf16_t* pb, int so) __attribute__((always_inline)) {
;     f[0] = *(const bf16x8*)(pa + so); f[1] = *(const bf16x8*)(pb + so); f[2] = *(const bf16x8*)(pb + 32 * 72 + so); f[3] = *(const bf16x8*)(pa + 32 * 72 + so);
;   };
;   auto mfma4 = [&](const bf16x8 (&f)[4]) __attribute__((always_inline)) {
;     if (SWAP) {
;       acc[0][0] = MFMA32(f[1], f[0], acc[0][0]); acc[0][1] = MFMA32(f[2], f[0], acc[0][1]);
;       acc[1][0] = MFMA32(f[1], f[3], acc[1][0]); acc[1][1] = MFMA32(f[2], f[3], acc[1][1]);
;     } else {
;       acc[0][0] = MFMA32(f[0], f[1], acc[0][0]); acc[0][1] = MFMA32(f[0], f[2], acc[0][1]);
;       acc[1][0] = MFMA32(f[3], f[1], acc[1][0]); acc[1][1] = MFMA32(f[3], f[2], acc[1][1]);
;     }
;   };
;   auto step = [&](int buf, u32x4 (&ra)[4], u32x4 (&rb)[4], bool do_write, bool do_load, int tload) __attribute__((always_inline)) {
;     const bf16_t* pa = As + buf * 2 * GT_IMG + pao; const bf16_t* pb = As + buf * 2 * GT_IMG + pbo;
;     bf16_t* Ad = As + (buf ^ 1) * 2 * GT_IMG; bf16_t* Bd = Ad + GT_IMG;
;     bf16x8 F0[4], F1[4];
;     frag_read(F0, pa, pb, 0);
;     __builtin_amdgcn_sched_barrier(0);
;     frag_read(F1, pa, pb, 16);
;     mfma4(F0);
;     __builtin_amdgcn_sched_barrier(0);
;     frag_read(F0, pa, pb, 32);
;     mfma4(F1);
;     if (do_write) {
; #pragma unroll
;       for (int i = 0; i < 4; ++i) *(u32x4*)(Ad + (lr + 32 * i) * 72 + lc) = ra[i];
;     }
;     __builtin_amdgcn_sched_barrier(0);
;     frag_read(F1, pa, pb, 48);
;     mfma4(F0);
;     if (do_write) {
; #pragma unroll
;       for (int i = 0; i < 4; ++i) *(u32x4*)(Bd + (lr + 32 * i) * 72 + lc) = rb[i];
;     }
;     __builtin_amdgcn_sched_barrier(0);
;     mfma4(F1);
;     if (do_load) load_stage(ra, rb, tload);
;     __builtin_amdgcn_sched_barrier(0);
;   };
	ds_read_b128 v[152:155], v102 offset:55296
	ds_read_b128 v[156:159], v102 offset:59904
	ds_read_b128 v[160:163], v101 offset:36864
	ds_read_b128 v[164:167], v101 offset:41472
	v_mfma_f32_32x32x16_bf16 v[48:63], v[104:107], v[120:123], v[48:63]
	v_mfma_f32_32x32x16_bf16 v[32:47], v[112:115], v[120:123], v[32:47]
	v_mfma_f32_32x32x16_bf16 v[16:31], v[104:107], v[128:131], v[16:31]
	v_mfma_f32_32x32x16_bf16 v[0:15], v[112:115], v[128:131], v[0:15]
	global_load_dwordx4 v[104:107], v[80:81], off offset:640
	global_load_dwordx4 v[108:111], v[82:83], off offset:640
	global_load_dwordx4 v[112:115], v[84:85], off offset:640
	global_load_dwordx4 v[116:119], v[86:87], off offset:640
	global_load_dwordx4 v[120:123], v[88:89], off offset:640
	global_load_dwordx4 v[124:127], v[90:91], off offset:640
	global_load_dwordx4 v[128:131], v[92:93], off offset:640
	global_load_dwordx4 v[132:135], v[94:95], off offset:640
	s_waitcnt lgkmcnt(1)
	v_mfma_f32_32x32x16_bf16 v[48:63], v[152:155], v[160:163], v[48:63]
	v_mfma_f32_32x32x16_bf16 v[32:47], v[156:159], v[160:163], v[32:47]
	s_waitcnt lgkmcnt(0)
	v_mfma_f32_32x32x16_bf16 v[16:31], v[152:155], v[164:167], v[16:31]
	ds_read_b128 v[152:155], v102 offset:55328
	ds_read_b128 v[160:163], v102 offset:59936
	ds_read_b128 v[168:171], v101 offset:36896
	ds_read_b128 v[172:175], v101 offset:41504
	v_mfma_f32_32x32x16_bf16 v[0:15], v[156:159], v[164:167], v[0:15]
	s_waitcnt lgkmcnt(1)
	v_mfma_f32_32x32x16_bf16 v[48:63], v[152:155], v[168:171], v[48:63]
	v_mfma_f32_32x32x16_bf16 v[32:47], v[160:163], v[168:171], v[32:47]
	s_waitcnt lgkmcnt(0)
	v_mfma_f32_32x32x16_bf16 v[16:31], v[152:155], v[172:175], v[16:31]
	ds_read_b128 v[152:155], v102 offset:55360
	ds_read_b128 v[156:159], v102 offset:59968
	ds_read_b128 v[164:167], v101 offset:36928
	ds_read_b128 v[168:171], v101 offset:41536
	s_waitcnt vmcnt(15)
	ds_write_b128 v100, v[64:67]
	s_waitcnt vmcnt(13)
	ds_write_b128 v100, v[72:75] offset:4608
	s_waitcnt vmcnt(11)
	ds_write_b128 v100, v[136:139] offset:9216
	s_waitcnt vmcnt(9)
	ds_write_b128 v100, v[144:147] offset:13824
	v_mfma_f32_32x32x16_bf16 v[0:15], v[160:163], v[172:175], v[0:15]
	ds_read_b128 v[64:67], v102 offset:55392
	ds_read_b128 v[72:75], v102 offset:60000
	ds_read_b128 v[136:139], v101 offset:36960
	ds_read_b128 v[144:147], v101 offset:41568
	s_waitcnt lgkmcnt(9)
	v_mfma_f32_32x32x16_bf16 v[48:63], v[152:155], v[164:167], v[48:63]
	ds_write_b128 v100, v[68:71] offset:18432
	ds_write_b128 v100, v[76:79] offset:23040
	ds_write_b128 v100, v[140:143] offset:27648
	s_waitcnt vmcnt(8)
	ds_write_b128 v100, v[148:151] offset:32256
	v_mfma_f32_32x32x16_bf16 v[32:47], v[156:159], v[164:167], v[32:47]
	s_waitcnt lgkmcnt(12)
	v_mfma_f32_32x32x16_bf16 v[16:31], v[152:155], v[168:171], v[16:31]
	v_mfma_f32_32x32x16_bf16 v[0:15], v[156:159], v[168:171], v[0:15]
	s_waitcnt lgkmcnt(0)
	s_barrier
	ds_read_b128 v[152:155], v102 offset:18432
	ds_read_b128 v[156:159], v102 offset:23040
	ds_read_b128 v[160:163], v101
	ds_read_b128 v[164:167], v101 offset:4608
	v_mfma_f32_32x32x16_bf16 v[48:63], v[64:67], v[136:139], v[48:63]
	v_mfma_f32_32x32x16_bf16 v[32:47], v[72:75], v[136:139], v[32:47]
	v_mfma_f32_32x32x16_bf16 v[16:31], v[64:67], v[144:147], v[16:31]
	v_mfma_f32_32x32x16_bf16 v[0:15], v[72:75], v[144:147], v[0:15]
	global_load_dwordx4 v[64:67], v[80:81], off offset:768
	global_load_dwordx4 v[68:71], v[82:83], off offset:768
	global_load_dwordx4 v[72:75], v[84:85], off offset:768
	global_load_dwordx4 v[76:79], v[86:87], off offset:768
	global_load_dwordx4 v[136:139], v[88:89], off offset:768
	global_load_dwordx4 v[140:143], v[90:91], off offset:768
	global_load_dwordx4 v[144:147], v[92:93], off offset:768
	global_load_dwordx4 v[148:151], v[94:95], off offset:768
	s_waitcnt lgkmcnt(1)
	v_mfma_f32_32x32x16_bf16 v[48:63], v[152:155], v[160:163], v[48:63]
	v_mfma_f32_32x32x16_bf16 v[32:47], v[156:159], v[160:163], v[32:47]
	s_waitcnt lgkmcnt(0)
	v_mfma_f32_32x32x16_bf16 v[16:31], v[152:155], v[164:167], v[16:31]
	ds_read_b128 v[152:155], v102 offset:18464
	ds_read_b128 v[160:163], v102 offset:23072
	ds_read_b128 v[168:171], v101 offset:32
	ds_read_b128 v[172:175], v101 offset:4640
	v_mfma_f32_32x32x16_bf16 v[0:15], v[156:159], v[164:167], v[0:15]
	s_waitcnt lgkmcnt(1)
	v_mfma_f32_32x32x16_bf16 v[48:63], v[152:155], v[168:171], v[48:63]
	v_mfma_f32_32x32x16_bf16 v[32:47], v[160:163], v[168:171], v[32:47]
	s_waitcnt lgkmcnt(0)
	v_mfma_f32_32x32x16_bf16 v[16:31], v[152:155], v[172:175], v[16:31]
	ds_read_b128 v[152:155], v102 offset:18496
	ds_read_b128 v[156:159], v102 offset:23104
	ds_read_b128 v[164:167], v101 offset:64
	ds_read_b128 v[168:171], v101 offset:4672
	s_waitcnt vmcnt(15)
	ds_write_b128 v100, v[104:107] offset:36864
	s_waitcnt vmcnt(13)
	ds_write_b128 v100, v[112:115] offset:41472
	s_waitcnt vmcnt(11)
	ds_write_b128 v100, v[120:123] offset:46080
	s_waitcnt vmcnt(9)
	ds_write_b128 v100, v[128:131] offset:50688
	v_mfma_f32_32x32x16_bf16 v[0:15], v[160:163], v[172:175], v[0:15]
	ds_read_b128 v[104:107], v102 offset:18528
	ds_read_b128 v[112:115], v102 offset:23136
	ds_read_b128 v[120:123], v101 offset:96
	ds_read_b128 v[128:131], v101 offset:4704
	s_waitcnt lgkmcnt(9)
	v_mfma_f32_32x32x16_bf16 v[48:63], v[152:155], v[164:167], v[48:63]
	ds_write_b128 v100, v[108:111] offset:55296
	ds_write_b128 v100, v[116:119] offset:59904
	ds_write_b128 v100, v[124:127] offset:64512
	s_waitcnt vmcnt(8)
	ds_write_b128 v103, v[132:135] offset:13824
	v_mfma_f32_32x32x16_bf16 v[32:47], v[156:159], v[164:167], v[32:47]
	s_waitcnt lgkmcnt(12)
	v_mfma_f32_32x32x16_bf16 v[16:31], v[152:155], v[168:171], v[16:31]
	v_mfma_f32_32x32x16_bf16 v[0:15], v[156:159], v[168:171], v[0:15]
	s_waitcnt lgkmcnt(0)
	s_barrier
; #define MFMA32(a, b, c) __builtin_amdgcn_mfma_f32_32x32x16_bf16((a), (b), (c), 0, 0, 0)
; template <bool SWAP>
; DI void gemm_tile(const bf16_t* __restrict__ A, int lda, const bf16_t* __restrict__ Bt, int ldb, int K, f32x16 (&acc)[2][2], bf16_t* As, bf16_t* Bs_unused) {
;     ...
;   auto frag_read = [&](bf16x8 (&f)[4], const bf16_t* pa, const bf16_t* pb, int so) __attribute__((always_inline)) {
;     f[0] = *(const bf16x8*)(pa + so); f[1] = *(const bf16x8*)(pb + so); f[2] = *(const bf16x8*)(pb + 32 * 72 + so); f[3] = *(const bf16x8*)(pa + 32 * 72 + so);
;   };
;   auto mfma4 = [&](const bf16x8 (&f)[4]) __attribute__((always_inline)) {
;     if (SWAP) {
;       acc[0][0] = MFMA32(f[1], f[0], acc[0][0]); acc[0][1] = MFMA32(f[2], f[0], acc[0][1]);
;       acc[1][0] = MFMA32(f[1], f[3], acc[1][0]); acc[1][1] = MFMA32(f[2], f[3], acc[1][1]);
;     } else {
;       acc[0][0] = MFMA32(f[0], f[1], acc[0][0]); acc[0][1] = MFMA32(f[0], f[2], acc[0][1]);
;       acc[1][0] = MFMA32(f[3], f[1], acc[1][0]); acc[1][1] = MFMA32(f[3], f[2], acc[1][1]);
;     }
;   };
;   auto step = [&](int buf, u32x4 (&ra)[4], u32x4 (&rb)[4], bool do_write, bool do_load, int tload) __attribute__((always_inline)) {
;     const bf16_t* pa = As + buf * 2 * GT_IMG + pao; const bf16_t* pb = As + buf * 2 * GT_IMG + pbo;
;     bf16_t* Ad = As + (buf ^ 1) * 2 * GT_IMG; bf16_t* Bd = Ad + GT_IMG;
;     bf16x8 F0[4], F1[4];
;     frag_read(F0, pa, pb, 0);
;     __builtin_amdgcn_sched_barrier(0);
;     frag_read(F1, pa, pb, 16);
;     mfma4(F0);
;     __builtin_amdgcn_sched_barrier(0);
;     frag_read(F0, pa, pb, 32);
;     mfma4(F1);
;     if (do_write) {
; #pragma unroll
;       for (int i = 0; i < 4; ++i) *(u32x4*)(Ad + (lr + 32 * i) * 72 + lc) = ra[i];
;     }
;     __builtin_amdgcn_sched_barrier(0);
;     frag_read(F1, pa, pb, 48);
;     mfma4(F0);
;     if (do_write) {
; #pragma unroll
;       for (int i = 0; i < 4; ++i) *(u32x4*)(Bd + (lr + 32 * i) * 72 + lc) = rb[i];
;     }
;     __builtin_amdgcn_sched_barrier(0);
;     mfma4(F1);
;     if (do_load) load_stage(ra, rb, tload);
;     __builtin_amdgcn_sched_barrier(0);
;   };
	ds_read_b128 v[152:155], v102 offset:55296
	ds_read_b128 v[156:159], v102 offset:59904
	ds_read_b128 v[160:163], v101 offset:36864
	ds_read_b128 v[164:167], v101 offset:41472
	v_mfma_f32_32x32x16_bf16 v[48:63], v[104:107], v[120:123], v[48:63]
	v_mfma_f32_32x32x16_bf16 v[32:47], v[112:115], v[120:123], v[32:47]
	v_mfma_f32_32x32x16_bf16 v[16:31], v[104:107], v[128:131], v[16:31]
	v_mfma_f32_32x32x16_bf16 v[0:15], v[112:115], v[128:131], v[0:15]
	global_load_dwordx4 v[104:107], v[80:81], off offset:896
	global_load_dwordx4 v[108:111], v[82:83], off offset:896
	global_load_dwordx4 v[112:115], v[84:85], off offset:896
	global_load_dwordx4 v[116:119], v[86:87], off offset:896
	global_load_dwordx4 v[120:123], v[88:89], off offset:896
	global_load_dwordx4 v[124:127], v[90:91], off offset:896
	global_load_dwordx4 v[128:131], v[92:93], off offset:896
	global_load_dwordx4 v[132:135], v[94:95], off offset:896
	s_waitcnt lgkmcnt(1)
	v_mfma_f32_32x32x16_bf16 v[48:63], v[152:155], v[160:163], v[48:63]
	v_mfma_f32_32x32x16_bf16 v[32:47], v[156:159], v[160:163], v[32:47]
	s_waitcnt lgkmcnt(0)
	v_mfma_f32_32x32x16_bf16 v[16:31], v[152:155], v[164:167], v[16:31]
	ds_read_b128 v[152:155], v102 offset:55328
	ds_read_b128 v[160:163], v102 offset:59936
	ds_read_b128 v[168:171], v101 offset:36896
	ds_read_b128 v[172:175], v101 offset:41504
	v_mfma_f32_32x32x16_bf16 v[0:15], v[156:159], v[164:167], v[0:15]
	s_waitcnt lgkmcnt(1)
	v_mfma_f32_32x32x16_bf16 v[48:63], v[152:155], v[168:171], v[48:63]
	v_mfma_f32_32x32x16_bf16 v[32:47], v[160:163], v[168:171], v[32:47]
	s_waitcnt lgkmcnt(0)
	v_mfma_f32_32x32x16_bf16 v[16:31], v[152:155], v[172:175], v[16:31]
	ds_read_b128 v[152:155], v102 offset:55360
	ds_read_b128 v[156:159], v102 offset:59968
	ds_read_b128 v[164:167], v101 offset:36928
	ds_read_b128 v[168:171], v101 offset:41536
	s_waitcnt vmcnt(15)
	ds_write_b128 v100, v[64:67]
	s_waitcnt vmcnt(13)
	ds_write_b128 v100, v[72:75] offset:4608
	s_waitcnt vmcnt(11)
	ds_write_b128 v100, v[136:139] offset:9216
	s_waitcnt vmcnt(9)
	ds_write_b128 v100, v[144:147] offset:13824
	v_mfma_f32_32x32x16_bf16 v[0:15], v[160:163], v[172:175], v[0:15]
	ds_read_b128 v[64:67], v102 offset:55392
	ds_read_b128 v[72:75], v102 offset:60000
	ds_read_b128 v[136:139], v101 offset:36960
	ds_read_b128 v[144:147], v101 offset:41568
	s_waitcnt lgkmcnt(9)
	v_mfma_f32_32x32x16_bf16 v[48:63], v[152:155], v[164:167], v[48:63]
	ds_write_b128 v100, v[68:71] offset:18432
	ds_write_b128 v100, v[76:79] offset:23040
	ds_write_b128 v100, v[140:143] offset:27648
	s_waitcnt vmcnt(8)
	ds_write_b128 v100, v[148:151] offset:32256
	v_mfma_f32_32x32x16_bf16 v[32:47], v[156:159], v[164:167], v[32:47]
	s_waitcnt lgkmcnt(12)
	v_mfma_f32_32x32x16_bf16 v[16:31], v[152:155], v[168:171], v[16:31]
	v_mfma_f32_32x32x16_bf16 v[0:15], v[156:159], v[168:171], v[0:15]
	s_waitcnt lgkmcnt(0)
	s_barrier
	ds_read_b128 v[152:155], v102 offset:18432
	ds_read_b128 v[156:159], v102 offset:23040
	ds_read_b128 v[160:163], v101
	ds_read_b128 v[164:167], v101 offset:4608
	v_mfma_f32_32x32x16_bf16 v[48:63], v[64:67], v[136:139], v[48:63]
	v_mfma_f32_32x32x16_bf16 v[32:47], v[72:75], v[136:139], v[32:47]
	v_mfma_f32_32x32x16_bf16 v[16:31], v[64:67], v[144:147], v[16:31]
	v_mfma_f32_32x32x16_bf16 v[0:15], v[72:75], v[144:147], v[0:15]
	global_load_dwordx4 v[64:67], v[80:81], off offset:1024
	global_load_dwordx4 v[68:71], v[82:83], off offset:1024
	global_load_dwordx4 v[72:75], v[84:85], off offset:1024
	global_load_dwordx4 v[76:79], v[86:87], off offset:1024
	global_load_dwordx4 v[136:139], v[88:89], off offset:1024
	global_load_dwordx4 v[140:143], v[90:91], off offset:1024
	global_load_dwordx4 v[144:147], v[92:93], off offset:1024
	global_load_dwordx4 v[148:151], v[94:95], off offset:1024
	s_waitcnt lgkmcnt(1)
	v_mfma_f32_32x32x16_bf16 v[48:63], v[152:155], v[160:163], v[48:63]
	v_mfma_f32_32x32x16_bf16 v[32:47], v[156:159], v[160:163], v[32:47]
	s_waitcnt lgkmcnt(0)
	v_mfma_f32_32x32x16_bf16 v[16:31], v[152:155], v[164:167], v[16:31]
	ds_read_b128 v[152:155], v102 offset:18464
	ds_read_b128 v[160:163], v102 offset:23072
	ds_read_b128 v[168:171], v101 offset:32
	ds_read_b128 v[172:175], v101 offset:4640
	v_mfma_f32_32x32x16_bf16 v[0:15], v[156:159], v[164:167], v[0:15]
	s_waitcnt lgkmcnt(1)
	v_mfma_f32_32x32x16_bf16 v[48:63], v[152:155], v[168:171], v[48:63]
	v_mfma_f32_32x32x16_bf16 v[32:47], v[160:163], v[168:171], v[32:47]
	s_waitcnt lgkmcnt(0)
	v_mfma_f32_32x32x16_bf16 v[16:31], v[152:155], v[172:175], v[16:31]
	ds_read_b128 v[152:155], v102 offset:18496
	ds_read_b128 v[156:159], v102 offset:23104
	ds_read_b128 v[164:167], v101 offset:64
	ds_read_b128 v[168:171], v101 offset:4672
	s_waitcnt vmcnt(15)
	ds_write_b128 v100, v[104:107] offset:36864
	s_waitcnt vmcnt(13)
	ds_write_b128 v100, v[112:115] offset:41472
	s_waitcnt vmcnt(11)
	ds_write_b128 v100, v[120:123] offset:46080
	s_waitcnt vmcnt(9)
	ds_write_b128 v100, v[128:131] offset:50688
	v_mfma_f32_32x32x16_bf16 v[0:15], v[160:163], v[172:175], v[0:15]
	ds_read_b128 v[104:107], v102 offset:18528
	ds_read_b128 v[112:115], v102 offset:23136
	ds_read_b128 v[120:123], v101 offset:96
	ds_read_b128 v[128:131], v101 offset:4704
	s_waitcnt lgkmcnt(9)
	v_mfma_f32_32x32x16_bf16 v[48:63], v[152:155], v[164:167], v[48:63]
	ds_write_b128 v100, v[108:111] offset:55296
	ds_write_b128 v100, v[116:119] offset:59904
	ds_write_b128 v100, v[124:127] offset:64512
	s_waitcnt vmcnt(8)
	ds_write_b128 v103, v[132:135] offset:13824
	v_mfma_f32_32x32x16_bf16 v[32:47], v[156:159], v[164:167], v[32:47]
	s_waitcnt lgkmcnt(12)
	v_mfma_f32_32x32x16_bf16 v[16:31], v[152:155], v[168:171], v[16:31]
	v_mfma_f32_32x32x16_bf16 v[0:15], v[156:159], v[168:171], v[0:15]
	s_waitcnt lgkmcnt(0)
	s_barrier
; #define MFMA32(a, b, c) __builtin_amdgcn_mfma_f32_32x32x16_bf16((a), (b), (c), 0, 0, 0)
; template <bool SWAP>
; DI void gemm_tile(const bf16_t* __restrict__ A, int lda, const bf16_t* __restrict__ Bt, int ldb, int K, f32x16 (&acc)[2][2], bf16_t* As, bf16_t* Bs_unused) {
;     ...
;   auto frag_read = [&](bf16x8 (&f)[4], const bf16_t* pa, const bf16_t* pb, int so) __attribute__((always_inline)) {
;     f[0] = *(const bf16x8*)(pa + so); f[1] = *(const bf16x8*)(pb + so); f[2] = *(const bf16x8*)(pb + 32 * 72 + so); f[3] = *(const bf16x8*)(pa + 32 * 72 + so);
;   };
;   auto mfma4 = [&](const bf16x8 (&f)[4]) __attribute__((always_inline)) {
;     if (SWAP) {
;       acc[0][0] = MFMA32(f[1], f[0], acc[0][0]); acc[0][1] = MFMA32(f[2], f[0], acc[0][1]);
;       acc[1][0] = MFMA32(f[1], f[3], acc[1][0]); acc[1][1] = MFMA32(f[2], f[3], acc[1][1]);
;     } else {
;       acc[0][0] = MFMA32(f[0], f[1], acc[0][0]); acc[0][1] = MFMA32(f[0], f[2], acc[0][1]);
;       acc[1][0] = MFMA32(f[3], f[1], acc[1][0]); acc[1][1] = MFMA32(f[3], f[2], acc[1][1]);
;     }
;   };
;   auto step = [&](int buf, u32x4 (&ra)[4], u32x4 (&rb)[4], bool do_write, bool do_load, int tload) __attribute__((always_inline)) {
;     const bf16_t* pa = As + buf * 2 * GT_IMG + pao; const bf16_t* pb = As + buf * 2 * GT_IMG + pbo;
;     bf16_t* Ad = As + (buf ^ 1) * 2 * GT_IMG; bf16_t* Bd = Ad + GT_IMG;
;     bf16x8 F0[4], F1[4];
;     frag_read(F0, pa, pb, 0);
;     __builtin_amdgcn_sched_barrier(0);
;     frag_read(F1, pa, pb, 16);
;     mfma4(F0);
;     __builtin_amdgcn_sched_barrier(0);
;     frag_read(F0, pa, pb, 32);
;     mfma4(F1);
;     if (do_write) {
; #pragma unroll
;       for (int i = 0; i < 4; ++i) *(u32x4*)(Ad + (lr + 32 * i) * 72 + lc) = ra[i];
;     }
;     __builtin_amdgcn_sched_barrier(0);
;     frag_read(F1, pa, pb, 48);
;     mfma4(F0);
;     if (do_write) {
; #pragma unroll
;       for (int i = 0; i < 4; ++i) *(u32x4*)(Bd + (lr + 32 * i) * 72 + lc) = rb[i];
;     }
;     __builtin_amdgcn_sched_barrier(0);
;     mfma4(F1);
;     if (do_load) load_stage(ra, rb, tload);
;     __builtin_amdgcn_sched_barrier(0);
;   };
	ds_read_b128 v[152:155], v102 offset:55296
	ds_read_b128 v[156:159], v102 offset:59904
	ds_read_b128 v[160:163], v101 offset:36864
	ds_read_b128 v[164:167], v101 offset:41472
	v_mfma_f32_32x32x16_bf16 v[48:63], v[104:107], v[120:123], v[48:63]
	v_mfma_f32_32x32x16_bf16 v[32:47], v[112:115], v[120:123], v[32:47]
	v_mfma_f32_32x32x16_bf16 v[16:31], v[104:107], v[128:131], v[16:31]
	v_mfma_f32_32x32x16_bf16 v[0:15], v[112:115], v[128:131], v[0:15]
	global_load_dwordx4 v[104:107], v[80:81], off offset:1152
	global_load_dwordx4 v[108:111], v[82:83], off offset:1152
	global_load_dwordx4 v[112:115], v[84:85], off offset:1152
	global_load_dwordx4 v[116:119], v[86:87], off offset:1152
	global_load_dwordx4 v[120:123], v[88:89], off offset:1152
	global_load_dwordx4 v[124:127], v[90:91], off offset:1152
	global_load_dwordx4 v[128:131], v[92:93], off offset:1152
	global_load_dwordx4 v[132:135], v[94:95], off offset:1152
	s_waitcnt lgkmcnt(1)
	v_mfma_f32_32x32x16_bf16 v[48:63], v[152:155], v[160:163], v[48:63]
	v_mfma_f32_32x32x16_bf16 v[32:47], v[156:159], v[160:163], v[32:47]
	s_waitcnt lgkmcnt(0)
	v_mfma_f32_32x32x16_bf16 v[16:31], v[152:155], v[164:167], v[16:31]
	ds_read_b128 v[152:155], v102 offset:55328
	ds_read_b128 v[160:163], v102 offset:59936
	ds_read_b128 v[168:171], v101 offset:36896
	ds_read_b128 v[172:175], v101 offset:41504
	v_mfma_f32_32x32x16_bf16 v[0:15], v[156:159], v[164:167], v[0:15]
	s_waitcnt lgkmcnt(1)
	v_mfma_f32_32x32x16_bf16 v[48:63], v[152:155], v[168:171], v[48:63]
	v_mfma_f32_32x32x16_bf16 v[32:47], v[160:163], v[168:171], v[32:47]
	s_waitcnt lgkmcnt(0)
	v_mfma_f32_32x32x16_bf16 v[16:31], v[152:155], v[172:175], v[16:31]
	ds_read_b128 v[152:155], v102 offset:55360
	ds_read_b128 v[156:159], v102 offset:59968
	ds_read_b128 v[164:167], v101 offset:36928
	ds_read_b128 v[168:171], v101 offset:41536
	s_waitcnt vmcnt(15)
	ds_write_b128 v100, v[64:67]
	s_waitcnt vmcnt(13)
	ds_write_b128 v100, v[72:75] offset:4608
	s_waitcnt vmcnt(11)
	ds_write_b128 v100, v[136:139] offset:9216
	s_waitcnt vmcnt(9)
	ds_write_b128 v100, v[144:147] offset:13824
	v_mfma_f32_32x32x16_bf16 v[0:15], v[160:163], v[172:175], v[0:15]
	ds_read_b128 v[64:67], v102 offset:55392
	ds_read_b128 v[72:75], v102 offset:60000
	ds_read_b128 v[136:139], v101 offset:36960
	ds_read_b128 v[144:147], v101 offset:41568
	s_waitcnt lgkmcnt(9)
	v_mfma_f32_32x32x16_bf16 v[48:63], v[152:155], v[164:167], v[48:63]
	ds_write_b128 v100, v[68:71] offset:18432
	ds_write_b128 v100, v[76:79] offset:23040
	ds_write_b128 v100, v[140:143] offset:27648
	s_waitcnt vmcnt(8)
	ds_write_b128 v100, v[148:151] offset:32256
	v_mfma_f32_32x32x16_bf16 v[32:47], v[156:159], v[164:167], v[32:47]
	s_waitcnt lgkmcnt(12)
	v_mfma_f32_32x32x16_bf16 v[16:31], v[152:155], v[168:171], v[16:31]
	v_mfma_f32_32x32x16_bf16 v[0:15], v[156:159], v[168:171], v[0:15]
	s_waitcnt lgkmcnt(0)
	s_barrier
	ds_read_b128 v[152:155], v102 offset:18432
	ds_read_b128 v[156:159], v102 offset:23040
	ds_read_b128 v[160:163], v101
	ds_read_b128 v[164:167], v101 offset:4608
	v_mfma_f32_32x32x16_bf16 v[48:63], v[64:67], v[136:139], v[48:63]
	v_mfma_f32_32x32x16_bf16 v[32:47], v[72:75], v[136:139], v[32:47]
	v_mfma_f32_32x32x16_bf16 v[16:31], v[64:67], v[144:147], v[16:31]
	v_mfma_f32_32x32x16_bf16 v[0:15], v[72:75], v[144:147], v[0:15]
	global_load_dwordx4 v[64:67], v[80:81], off offset:1280
	global_load_dwordx4 v[68:71], v[82:83], off offset:1280
	global_load_dwordx4 v[72:75], v[84:85], off offset:1280
	global_load_dwordx4 v[76:79], v[86:87], off offset:1280
	global_load_dwordx4 v[136:139], v[88:89], off offset:1280
	global_load_dwordx4 v[140:143], v[90:91], off offset:1280
	global_load_dwordx4 v[144:147], v[92:93], off offset:1280
	global_load_dwordx4 v[148:151], v[94:95], off offset:1280
	s_waitcnt lgkmcnt(1)
	v_mfma_f32_32x32x16_bf16 v[48:63], v[152:155], v[160:163], v[48:63]
	v_mfma_f32_32x32x16_bf16 v[32:47], v[156:159], v[160:163], v[32:47]
	s_waitcnt lgkmcnt(0)
	v_mfma_f32_32x32x16_bf16 v[16:31], v[152:155], v[164:167], v[16:31]
	ds_read_b128 v[152:155], v102 offset:18464
	ds_read_b128 v[160:163], v102 offset:23072
	ds_read_b128 v[168:171], v101 offset:32
	ds_read_b128 v[172:175], v101 offset:4640
	v_mfma_f32_32x32x16_bf16 v[0:15], v[156:159], v[164:167], v[0:15]
	s_waitcnt lgkmcnt(1)
	v_mfma_f32_32x32x16_bf16 v[48:63], v[152:155], v[168:171], v[48:63]
	v_mfma_f32_32x32x16_bf16 v[32:47], v[160:163], v[168:171], v[32:47]
	s_waitcnt lgkmcnt(0)
	v_mfma_f32_32x32x16_bf16 v[16:31], v[152:155], v[172:175], v[16:31]
	ds_read_b128 v[152:155], v102 offset:18496
	ds_read_b128 v[156:159], v102 offset:23104
	ds_read_b128 v[164:167], v101 offset:64
	ds_read_b128 v[168:171], v101 offset:4672
	s_waitcnt vmcnt(15)
	ds_write_b128 v100, v[104:107] offset:36864
	s_waitcnt vmcnt(13)
	ds_write_b128 v100, v[112:115] offset:41472
	s_waitcnt vmcnt(11)
	ds_write_b128 v100, v[120:123] offset:46080
	s_waitcnt vmcnt(9)
	ds_write_b128 v100, v[128:131] offset:50688
	v_mfma_f32_32x32x16_bf16 v[0:15], v[160:163], v[172:175], v[0:15]
	ds_read_b128 v[104:107], v102 offset:18528
	ds_read_b128 v[112:115], v102 offset:23136
	ds_read_b128 v[120:123], v101 offset:96
	ds_read_b128 v[128:131], v101 offset:4704
	s_waitcnt lgkmcnt(9)
	v_mfma_f32_32x32x16_bf16 v[48:63], v[152:155], v[164:167], v[48:63]
	ds_write_b128 v100, v[108:111] offset:55296
	ds_write_b128 v100, v[116:119] offset:59904
	ds_write_b128 v100, v[124:127] offset:64512
	s_waitcnt vmcnt(8)
	ds_write_b128 v103, v[132:135] offset:13824
	v_mfma_f32_32x32x16_bf16 v[32:47], v[156:159], v[164:167], v[32:47]
	s_waitcnt lgkmcnt(12)
	v_mfma_f32_32x32x16_bf16 v[16:31], v[152:155], v[168:171], v[16:31]
	v_mfma_f32_32x32x16_bf16 v[0:15], v[156:159], v[168:171], v[0:15]
	s_waitcnt lgkmcnt(0)
	s_barrier
; #define MFMA32(a, b, c) __builtin_amdgcn_mfma_f32_32x32x16_bf16((a), (b), (c), 0, 0, 0)
; template <bool SWAP>
; DI void gemm_tile(const bf16_t* __restrict__ A, int lda, const bf16_t* __restrict__ Bt, int ldb, int K, f32x16 (&acc)[2][2], bf16_t* As, bf16_t* Bs_unused) {
;     ...
;   auto frag_read = [&](bf16x8 (&f)[4], const bf16_t* pa, const bf16_t* pb, int so) __attribute__((always_inline)) {
;     f[0] = *(const bf16x8*)(pa + so); f[1] = *(const bf16x8*)(pb + so); f[2] = *(const bf16x8*)(pb + 32 * 72 + so); f[3] = *(const bf16x8*)(pa + 32 * 72 + so);
;   };
;   auto mfma4 = [&](const bf16x8 (&f)[4]) __attribute__((always_inline)) {
;     if (SWAP) {
;       acc[0][0] = MFMA32(f[1], f[0], acc[0][0]); acc[0][1] = MFMA32(f[2], f[0], acc[0][1]);
;       acc[1][0] = MFMA32(f[1], f[3], acc[1][0]); acc[1][1] = MFMA32(f[2], f[3], acc[1][1]);
;     } else {
;       acc[0][0] = MFMA32(f[0], f[1], acc[0][0]); acc[0][1] = MFMA32(f[0], f[2], acc[0][1]);
;       acc[1][0] = MFMA32(f[3], f[1], acc[1][0]); acc[1][1] = MFMA32(f[3], f[2], acc[1][1]);
;     }
;   };
;   auto step = [&](int buf, u32x4 (&ra)[4], u32x4 (&rb)[4], bool do_write, bool do_load, int tload) __attribute__((always_inline)) {
;     const bf16_t* pa = As + buf * 2 * GT_IMG + pao; const bf16_t* pb = As + buf * 2 * GT_IMG + pbo;
;     bf16_t* Ad = As + (buf ^ 1) * 2 * GT_IMG; bf16_t* Bd = Ad + GT_IMG;
;     bf16x8 F0[4], F1[4];
;     frag_read(F0, pa, pb, 0);
;     __builtin_amdgcn_sched_barrier(0);
;     frag_read(F1, pa, pb, 16);
;     mfma4(F0);
;     __builtin_amdgcn_sched_barrier(0);
;     frag_read(F0, pa, pb, 32);
;     mfma4(F1);
;     if (do_write) {
; #pragma unroll
;       for (int i = 0; i < 4; ++i) *(u32x4*)(Ad + (lr + 32 * i) * 72 + lc) = ra[i];
;     }
;     __builtin_amdgcn_sched_barrier(0);
;     frag_read(F1, pa, pb, 48);
;     mfma4(F0);
;     if (do_write) {
; #pragma unroll
;       for (int i = 0; i < 4; ++i) *(u32x4*)(Bd + (lr + 32 * i) * 72 + lc) = rb[i];
;     }
;     __builtin_amdgcn_sched_barrier(0);
;     mfma4(F1);
;     if (do_load) load_stage(ra, rb, tload);
;     __builtin_amdgcn_sched_barrier(0);
;   };
	ds_read_b128 v[152:155], v102 offset:55296
	ds_read_b128 v[156:159], v102 offset:59904
	ds_read_b128 v[160:163], v101 offset:36864
	ds_read_b128 v[164:167], v101 offset:41472
	v_mfma_f32_32x32x16_bf16 v[48:63], v[104:107], v[120:123], v[48:63]
	v_mfma_f32_32x32x16_bf16 v[32:47], v[112:115], v[120:123], v[32:47]
	v_mfma_f32_32x32x16_bf16 v[16:31], v[104:107], v[128:131], v[16:31]
	v_mfma_f32_32x32x16_bf16 v[0:15], v[112:115], v[128:131], v[0:15]
	global_load_dwordx4 v[104:107], v[80:81], off offset:1408
	global_load_dwordx4 v[108:111], v[82:83], off offset:1408
	global_load_dwordx4 v[112:115], v[84:85], off offset:1408
	global_load_dwordx4 v[116:119], v[86:87], off offset:1408
	global_load_dwordx4 v[120:123], v[88:89], off offset:1408
	global_load_dwordx4 v[124:127], v[90:91], off offset:1408
	global_load_dwordx4 v[128:131], v[92:93], off offset:1408
	global_load_dwordx4 v[132:135], v[94:95], off offset:1408
	s_waitcnt lgkmcnt(1)
	v_mfma_f32_32x32x16_bf16 v[48:63], v[152:155], v[160:163], v[48:63]
	v_mfma_f32_32x32x16_bf16 v[32:47], v[156:159], v[160:163], v[32:47]
	s_waitcnt lgkmcnt(0)
	v_mfma_f32_32x32x16_bf16 v[16:31], v[152:155], v[164:167], v[16:31]
	ds_read_b128 v[152:155], v102 offset:55328
	ds_read_b128 v[160:163], v102 offset:59936
	ds_read_b128 v[168:171], v101 offset:36896
	ds_read_b128 v[172:175], v101 offset:41504
	v_mfma_f32_32x32x16_bf16 v[0:15], v[156:159], v[164:167], v[0:15]
	s_waitcnt lgkmcnt(1)
	v_mfma_f32_32x32x16_bf16 v[48:63], v[152:155], v[168:171], v[48:63]
	v_mfma_f32_32x32x16_bf16 v[32:47], v[160:163], v[168:171], v[32:47]
	s_waitcnt lgkmcnt(0)
	v_mfma_f32_32x32x16_bf16 v[16:31], v[152:155], v[172:175], v[16:31]
	ds_read_b128 v[152:155], v102 offset:55360
	ds_read_b128 v[156:159], v102 offset:59968
	ds_read_b128 v[164:167], v101 offset:36928
	ds_read_b128 v[168:171], v101 offset:41536
	s_waitcnt vmcnt(15)
	ds_write_b128 v100, v[64:67]
	s_waitcnt vmcnt(13)
	ds_write_b128 v100, v[72:75] offset:4608
	s_waitcnt vmcnt(11)
	ds_write_b128 v100, v[136:139] offset:9216
	s_waitcnt vmcnt(9)
	ds_write_b128 v100, v[144:147] offset:13824
	v_mfma_f32_32x32x16_bf16 v[0:15], v[160:163], v[172:175], v[0:15]
	ds_read_b128 v[64:67], v102 offset:55392
	ds_read_b128 v[72:75], v102 offset:60000
	ds_read_b128 v[136:139], v101 offset:36960
	ds_read_b128 v[144:147], v101 offset:41568
	s_waitcnt lgkmcnt(9)
	v_mfma_f32_32x32x16_bf16 v[48:63], v[152:155], v[164:167], v[48:63]
	ds_write_b128 v100, v[68:71] offset:18432
	ds_write_b128 v100, v[76:79] offset:23040
	ds_write_b128 v100, v[140:143] offset:27648
	s_waitcnt vmcnt(8)
	ds_write_b128 v100, v[148:151] offset:32256
	v_mfma_f32_32x32x16_bf16 v[32:47], v[156:159], v[164:167], v[32:47]
	s_waitcnt lgkmcnt(12)
	v_mfma_f32_32x32x16_bf16 v[16:31], v[152:155], v[168:171], v[16:31]
	v_mfma_f32_32x32x16_bf16 v[0:15], v[156:159], v[168:171], v[0:15]
	s_waitcnt lgkmcnt(0)
	s_barrier
	ds_read_b128 v[152:155], v102 offset:18432
	ds_read_b128 v[156:159], v102 offset:23040
	ds_read_b128 v[160:163], v101
	ds_read_b128 v[164:167], v101 offset:4608
	v_mfma_f32_32x32x16_bf16 v[48:63], v[64:67], v[136:139], v[48:63]
	v_mfma_f32_32x32x16_bf16 v[32:47], v[72:75], v[136:139], v[32:47]
	v_mfma_f32_32x32x16_bf16 v[16:31], v[64:67], v[144:147], v[16:31]
	v_mfma_f32_32x32x16_bf16 v[0:15], v[72:75], v[144:147], v[0:15]
	global_load_dwordx4 v[64:67], v[80:81], off offset:1536
	global_load_dwordx4 v[68:71], v[82:83], off offset:1536
	global_load_dwordx4 v[72:75], v[84:85], off offset:1536
	global_load_dwordx4 v[76:79], v[86:87], off offset:1536
	global_load_dwordx4 v[136:139], v[88:89], off offset:1536
	global_load_dwordx4 v[140:143], v[90:91], off offset:1536
	global_load_dwordx4 v[144:147], v[92:93], off offset:1536
	global_load_dwordx4 v[148:151], v[94:95], off offset:1536
	s_waitcnt lgkmcnt(1)
	v_mfma_f32_32x32x16_bf16 v[48:63], v[152:155], v[160:163], v[48:63]
	v_mfma_f32_32x32x16_bf16 v[32:47], v[156:159], v[160:163], v[32:47]
	s_waitcnt lgkmcnt(0)
	v_mfma_f32_32x32x16_bf16 v[16:31], v[152:155], v[164:167], v[16:31]
	ds_read_b128 v[152:155], v102 offset:18464
	ds_read_b128 v[160:163], v102 offset:23072
	ds_read_b128 v[168:171], v101 offset:32
	ds_read_b128 v[172:175], v101 offset:4640
	v_mfma_f32_32x32x16_bf16 v[0:15], v[156:159], v[164:167], v[0:15]
	s_waitcnt lgkmcnt(1)
	v_mfma_f32_32x32x16_bf16 v[48:63], v[152:155], v[168:171], v[48:63]
	v_mfma_f32_32x32x16_bf16 v[32:47], v[160:163], v[168:171], v[32:47]
	s_waitcnt lgkmcnt(0)
	v_mfma_f32_32x32x16_bf16 v[16:31], v[152:155], v[172:175], v[16:31]
	ds_read_b128 v[152:155], v102 offset:18496
	ds_read_b128 v[156:159], v102 offset:23104
	ds_read_b128 v[164:167], v101 offset:64
	ds_read_b128 v[168:171], v101 offset:4672
	s_waitcnt vmcnt(15)
	ds_write_b128 v100, v[104:107] offset:36864
	s_waitcnt vmcnt(13)
	ds_write_b128 v100, v[112:115] offset:41472
	s_waitcnt vmcnt(11)
	ds_write_b128 v100, v[120:123] offset:46080
	s_waitcnt vmcnt(9)
	ds_write_b128 v100, v[128:131] offset:50688
	v_mfma_f32_32x32x16_bf16 v[0:15], v[160:163], v[172:175], v[0:15]
	ds_read_b128 v[104:107], v102 offset:18528
	ds_read_b128 v[112:115], v102 offset:23136
	ds_read_b128 v[120:123], v101 offset:96
	ds_read_b128 v[128:131], v101 offset:4704
	s_waitcnt lgkmcnt(9)
	v_mfma_f32_32x32x16_bf16 v[48:63], v[152:155], v[164:167], v[48:63]
	ds_write_b128 v100, v[108:111] offset:55296
	ds_write_b128 v100, v[116:119] offset:59904
	ds_write_b128 v100, v[124:127] offset:64512
	s_waitcnt vmcnt(8)
	ds_write_b128 v103, v[132:135] offset:13824
	v_mfma_f32_32x32x16_bf16 v[32:47], v[156:159], v[164:167], v[32:47]
	s_waitcnt lgkmcnt(12)
	v_mfma_f32_32x32x16_bf16 v[16:31], v[152:155], v[168:171], v[16:31]
	v_mfma_f32_32x32x16_bf16 v[0:15], v[156:159], v[168:171], v[0:15]
	s_waitcnt lgkmcnt(0)
	s_barrier
; #define MFMA32(a, b, c) __builtin_amdgcn_mfma_f32_32x32x16_bf16((a), (b), (c), 0, 0, 0)
; template <bool SWAP>
; DI void gemm_tile(const bf16_t* __restrict__ A, int lda, const bf16_t* __restrict__ Bt, int ldb, int K, f32x16 (&acc)[2][2], bf16_t* As, bf16_t* Bs_unused) {
;     ...
;   auto frag_read = [&](bf16x8 (&f)[4], const bf16_t* pa, const bf16_t* pb, int so) __attribute__((always_inline)) {
;     f[0] = *(const bf16x8*)(pa + so); f[1] = *(const bf16x8*)(pb + so); f[2] = *(const bf16x8*)(pb + 32 * 72 + so); f[3] = *(const bf16x8*)(pa + 32 * 72 + so);
;   };
;   auto mfma4 = [&](const bf16x8 (&f)[4]) __attribute__((always_inline)) {
;     if (SWAP) {
;       acc[0][0] = MFMA32(f[1], f[0], acc[0][0]); acc[0][1] = MFMA32(f[2], f[0], acc[0][1]);
;       acc[1][0] = MFMA32(f[1], f[3], acc[1][0]); acc[1][1] = MFMA32(f[2], f[3], acc[1][1]);
;     } else {
;       acc[0][0] = MFMA32(f[0], f[1], acc[0][0]); acc[0][1] = MFMA32(f[0], f[2], acc[0][1]);
;       acc[1][0] = MFMA32(f[3], f[1], acc[1][0]); acc[1][1] = MFMA32(f[3], f[2], acc[1][1]);
;     }
;   };
;   auto step = [&](int buf, u32x4 (&ra)[4], u32x4 (&rb)[4], bool do_write, bool do_load, int tload) __attribute__((always_inline)) {
;     const bf16_t* pa = As + buf * 2 * GT_IMG + pao; const bf16_t* pb = As + buf * 2 * GT_IMG + pbo;
;     bf16_t* Ad = As + (buf ^ 1) * 2 * GT_IMG; bf16_t* Bd = Ad + GT_IMG;
;     bf16x8 F0[4], F1[4];
;     frag_read(F0, pa, pb, 0);
;     __builtin_amdgcn_sched_barrier(0);
;     frag_read(F1, pa, pb, 16);
;     mfma4(F0);
;     __builtin_amdgcn_sched_barrier(0);
;     frag_read(F0, pa, pb, 32);
;     mfma4(F1);
;     if (do_write) {
; #pragma unroll
;       for (int i = 0; i < 4; ++i) *(u32x4*)(Ad + (lr + 32 * i) * 72 + lc) = ra[i];
;     }
;     __builtin_amdgcn_sched_barrier(0);
;     frag_read(F1, pa, pb, 48);
;     mfma4(F0);
;     if (do_write) {
; #pragma unroll
;       for (int i = 0; i < 4; ++i) *(u32x4*)(Bd + (lr + 32 * i) * 72 + lc) = rb[i];
;     }
;     __builtin_amdgcn_sched_barrier(0);
;     mfma4(F1);
;     if (do_load) load_stage(ra, rb, tload);
;     __builtin_amdgcn_sched_barrier(0);
;   };
	ds_read_b128 v[152:155], v102 offset:55296
	ds_read_b128 v[156:159], v102 offset:59904
	ds_read_b128 v[160:163], v101 offset:36864
	ds_read_b128 v[164:167], v101 offset:41472
	v_mfma_f32_32x32x16_bf16 v[48:63], v[104:107], v[120:123], v[48:63]
	v_mfma_f32_32x32x16_bf16 v[32:47], v[112:115], v[120:123], v[32:47]
	v_mfma_f32_32x32x16_bf16 v[16:31], v[104:107], v[128:131], v[16:31]
	v_mfma_f32_32x32x16_bf16 v[0:15], v[112:115], v[128:131], v[0:15]
	global_load_dwordx4 v[104:107], v[80:81], off offset:1664
	global_load_dwordx4 v[108:111], v[82:83], off offset:1664
	global_load_dwordx4 v[112:115], v[84:85], off offset:1664
	global_load_dwordx4 v[116:119], v[86:87], off offset:1664
	global_load_dwordx4 v[120:123], v[88:89], off offset:1664
	global_load_dwordx4 v[124:127], v[90:91], off offset:1664
	global_load_dwordx4 v[128:131], v[92:93], off offset:1664
	global_load_dwordx4 v[132:135], v[94:95], off offset:1664
	s_waitcnt lgkmcnt(1)
	v_mfma_f32_32x32x16_bf16 v[48:63], v[152:155], v[160:163], v[48:63]
	v_mfma_f32_32x32x16_bf16 v[32:47], v[156:159], v[160:163], v[32:47]
	s_waitcnt lgkmcnt(0)
	v_mfma_f32_32x32x16_bf16 v[16:31], v[152:155], v[164:167], v[16:31]
	ds_read_b128 v[152:155], v102 offset:55328
	ds_read_b128 v[160:163], v102 offset:59936
	ds_read_b128 v[168:171], v101 offset:36896
	ds_read_b128 v[172:175], v101 offset:41504
	v_mfma_f32_32x32x16_bf16 v[0:15], v[156:159], v[164:167], v[0:15]
	s_waitcnt lgkmcnt(1)
	v_mfma_f32_32x32x16_bf16 v[48:63], v[152:155], v[168:171], v[48:63]
	v_mfma_f32_32x32x16_bf16 v[32:47], v[160:163], v[168:171], v[32:47]
	s_waitcnt lgkmcnt(0)
	v_mfma_f32_32x32x16_bf16 v[16:31], v[152:155], v[172:175], v[16:31]
	ds_read_b128 v[152:155], v102 offset:55360
	ds_read_b128 v[156:159], v102 offset:59968
	ds_read_b128 v[164:167], v101 offset:36928
	ds_read_b128 v[168:171], v101 offset:41536
	s_waitcnt vmcnt(15)
	ds_write_b128 v100, v[64:67]
	s_waitcnt vmcnt(13)
	ds_write_b128 v100, v[72:75] offset:4608
	s_waitcnt vmcnt(11)
	ds_write_b128 v100, v[136:139] offset:9216
	s_waitcnt vmcnt(9)
	ds_write_b128 v100, v[144:147] offset:13824
	v_mfma_f32_32x32x16_bf16 v[0:15], v[160:163], v[172:175], v[0:15]
	ds_read_b128 v[64:67], v102 offset:55392
	ds_read_b128 v[72:75], v102 offset:60000
	ds_read_b128 v[136:139], v101 offset:36960
	ds_read_b128 v[144:147], v101 offset:41568
	s_waitcnt lgkmcnt(9)
	v_mfma_f32_32x32x16_bf16 v[48:63], v[152:155], v[164:167], v[48:63]
	ds_write_b128 v100, v[68:71] offset:18432
	ds_write_b128 v100, v[76:79] offset:23040
	ds_write_b128 v100, v[140:143] offset:27648
	s_waitcnt vmcnt(8)
	ds_write_b128 v100, v[148:151] offset:32256
	v_mfma_f32_32x32x16_bf16 v[32:47], v[156:159], v[164:167], v[32:47]
	s_waitcnt lgkmcnt(12)
	v_mfma_f32_32x32x16_bf16 v[16:31], v[152:155], v[168:171], v[16:31]
	v_mfma_f32_32x32x16_bf16 v[0:15], v[156:159], v[168:171], v[0:15]
	s_waitcnt lgkmcnt(0)
	s_barrier
	ds_read_b128 v[152:155], v102 offset:18432
	ds_read_b128 v[156:159], v102 offset:23040
	ds_read_b128 v[160:163], v101
	ds_read_b128 v[164:167], v101 offset:4608
	v_mfma_f32_32x32x16_bf16 v[48:63], v[64:67], v[136:139], v[48:63]
	v_mfma_f32_32x32x16_bf16 v[32:47], v[72:75], v[136:139], v[32:47]
	v_mfma_f32_32x32x16_bf16 v[16:31], v[64:67], v[144:147], v[16:31]
	v_mfma_f32_32x32x16_bf16 v[0:15], v[72:75], v[144:147], v[0:15]
	global_load_dwordx4 v[64:67], v[80:81], off offset:1792
	global_load_dwordx4 v[68:71], v[82:83], off offset:1792
	global_load_dwordx4 v[72:75], v[84:85], off offset:1792
	global_load_dwordx4 v[76:79], v[86:87], off offset:1792
	global_load_dwordx4 v[136:139], v[88:89], off offset:1792
	global_load_dwordx4 v[140:143], v[90:91], off offset:1792
	global_load_dwordx4 v[144:147], v[92:93], off offset:1792
	global_load_dwordx4 v[148:151], v[94:95], off offset:1792
	s_waitcnt lgkmcnt(1)
	v_mfma_f32_32x32x16_bf16 v[48:63], v[152:155], v[160:163], v[48:63]
	v_mfma_f32_32x32x16_bf16 v[32:47], v[156:159], v[160:163], v[32:47]
	s_waitcnt lgkmcnt(0)
	v_mfma_f32_32x32x16_bf16 v[16:31], v[152:155], v[164:167], v[16:31]
	ds_read_b128 v[152:155], v102 offset:18464
	ds_read_b128 v[160:163], v102 offset:23072
	ds_read_b128 v[168:171], v101 offset:32
	ds_read_b128 v[172:175], v101 offset:4640
	v_mfma_f32_32x32x16_bf16 v[0:15], v[156:159], v[164:167], v[0:15]
	s_waitcnt lgkmcnt(1)
	v_mfma_f32_32x32x16_bf16 v[48:63], v[152:155], v[168:171], v[48:63]
	v_mfma_f32_32x32x16_bf16 v[32:47], v[160:163], v[168:171], v[32:47]
	s_waitcnt lgkmcnt(0)
	v_mfma_f32_32x32x16_bf16 v[16:31], v[152:155], v[172:175], v[16:31]
	ds_read_b128 v[152:155], v102 offset:18496
	ds_read_b128 v[156:159], v102 offset:23104
	ds_read_b128 v[164:167], v101 offset:64
	ds_read_b128 v[168:171], v101 offset:4672
	s_waitcnt vmcnt(15)
	ds_write_b128 v100, v[104:107] offset:36864
	s_waitcnt vmcnt(13)
	ds_write_b128 v100, v[112:115] offset:41472
	s_waitcnt vmcnt(11)
	ds_write_b128 v100, v[120:123] offset:46080
	s_waitcnt vmcnt(9)
	ds_write_b128 v100, v[128:131] offset:50688
	v_mfma_f32_32x32x16_bf16 v[0:15], v[160:163], v[172:175], v[0:15]
	ds_read_b128 v[104:107], v102 offset:18528
	ds_read_b128 v[112:115], v102 offset:23136
	ds_read_b128 v[120:123], v101 offset:96
	ds_read_b128 v[128:131], v101 offset:4704
	s_waitcnt lgkmcnt(9)
	v_mfma_f32_32x32x16_bf16 v[48:63], v[152:155], v[164:167], v[48:63]
	ds_write_b128 v100, v[108:111] offset:55296
	ds_write_b128 v100, v[116:119] offset:59904
	ds_write_b128 v100, v[124:127] offset:64512
	s_waitcnt vmcnt(8)
	ds_write_b128 v103, v[132:135] offset:13824
	v_mfma_f32_32x32x16_bf16 v[32:47], v[156:159], v[164:167], v[32:47]
	s_waitcnt lgkmcnt(12)
	v_mfma_f32_32x32x16_bf16 v[16:31], v[152:155], v[168:171], v[16:31]
	v_mfma_f32_32x32x16_bf16 v[0:15], v[156:159], v[168:171], v[0:15]
	s_waitcnt lgkmcnt(5)
	v_mfma_f32_32x32x16_bf16 v[48:63], v[104:107], v[120:123], v[48:63]
	v_mfma_f32_32x32x16_bf16 v[32:47], v[112:115], v[120:123], v[32:47]
	s_waitcnt lgkmcnt(4)
	v_mfma_f32_32x32x16_bf16 v[16:31], v[104:107], v[128:131], v[16:31]
	v_mfma_f32_32x32x16_bf16 v[0:15], v[112:115], v[128:131], v[0:15]
	global_load_dwordx4 v[104:107], v[80:81], off offset:1920
	s_nop 0
	global_load_dwordx4 v[80:83], v[82:83], off offset:1920
	s_nop 0
	global_load_dwordx4 v[108:111], v[84:85], off offset:1920
	s_nop 0
	global_load_dwordx4 v[84:87], v[86:87], off offset:1920
	s_nop 0
	global_load_dwordx4 v[112:115], v[88:89], off offset:1920
	s_nop 0
	global_load_dwordx4 v[88:91], v[90:91], off offset:1920
	s_nop 0
	global_load_dwordx4 v[116:119], v[92:93], off offset:1920
	s_nop 0
	global_load_dwordx4 v[92:95], v[94:95], off offset:1920
	s_waitcnt lgkmcnt(0)
	s_barrier
; #define MFMA32(a, b, c) __builtin_amdgcn_mfma_f32_32x32x16_bf16((a), (b), (c), 0, 0, 0)
; template <bool SWAP>
; DI void gemm_tile(const bf16_t* __restrict__ A, int lda, const bf16_t* __restrict__ Bt, int ldb, int K, f32x16 (&acc)[2][2], bf16_t* As, bf16_t* Bs_unused) {
;     ...
;   auto frag_read = [&](bf16x8 (&f)[4], const bf16_t* pa, const bf16_t* pb, int so) __attribute__((always_inline)) {
;     f[0] = *(const bf16x8*)(pa + so); f[1] = *(const bf16x8*)(pb + so); f[2] = *(const bf16x8*)(pb + 32 * 72 + so); f[3] = *(const bf16x8*)(pa + 32 * 72 + so);
;   };
;   auto mfma4 = [&](const bf16x8 (&f)[4]) __attribute__((always_inline)) {
;     if (SWAP) {
;       acc[0][0] = MFMA32(f[1], f[0], acc[0][0]); acc[0][1] = MFMA32(f[2], f[0], acc[0][1]);
;       acc[1][0] = MFMA32(f[1], f[3], acc[1][0]); acc[1][1] = MFMA32(f[2], f[3], acc[1][1]);
;     } else {
;       acc[0][0] = MFMA32(f[0], f[1], acc[0][0]); acc[0][1] = MFMA32(f[0], f[2], acc[0][1]);
;       acc[1][0] = MFMA32(f[3], f[1], acc[1][0]); acc[1][1] = MFMA32(f[3], f[2], acc[1][1]);
;     }
;   };
;   auto step = [&](int buf, u32x4 (&ra)[4], u32x4 (&rb)[4], bool do_write, bool do_load, int tload) __attribute__((always_inline)) {
;     const bf16_t* pa = As + buf * 2 * GT_IMG + pao; const bf16_t* pb = As + buf * 2 * GT_IMG + pbo;
;     bf16_t* Ad = As + (buf ^ 1) * 2 * GT_IMG; bf16_t* Bd = Ad + GT_IMG;
;     bf16x8 F0[4], F1[4];
;     frag_read(F0, pa, pb, 0);
;     __builtin_amdgcn_sched_barrier(0);
;     frag_read(F1, pa, pb, 16);
;     mfma4(F0);
;     __builtin_amdgcn_sched_barrier(0);
;     frag_read(F0, pa, pb, 32);
;     mfma4(F1);
;     if (do_write) {
; #pragma unroll
;       for (int i = 0; i < 4; ++i) *(u32x4*)(Ad + (lr + 32 * i) * 72 + lc) = ra[i];
;     }
;     __builtin_amdgcn_sched_barrier(0);
;     frag_read(F1, pa, pb, 48);
;     mfma4(F0);
;     if (do_write) {
; #pragma unroll
;       for (int i = 0; i < 4; ++i) *(u32x4*)(Bd + (lr + 32 * i) * 72 + lc) = rb[i];
;     }
;     __builtin_amdgcn_sched_barrier(0);
;     mfma4(F1);
;     if (do_load) load_stage(ra, rb, tload);
;     __builtin_amdgcn_sched_barrier(0);
;   };
	ds_read_b128 v[120:123], v102 offset:55296
	ds_read_b128 v[124:127], v102 offset:59904
	ds_read_b128 v[128:131], v101 offset:36864
	ds_read_b128 v[132:135], v101 offset:41472
	s_waitcnt lgkmcnt(1)
	v_mfma_f32_32x32x16_bf16 v[48:63], v[120:123], v[128:131], v[48:63]
	v_mfma_f32_32x32x16_bf16 v[32:47], v[124:127], v[128:131], v[32:47]
	s_waitcnt lgkmcnt(0)
	v_mfma_f32_32x32x16_bf16 v[16:31], v[120:123], v[132:135], v[16:31]
	ds_read_b128 v[120:123], v102 offset:55328
	ds_read_b128 v[128:131], v102 offset:59936
	ds_read_b128 v[152:155], v101 offset:36896
	ds_read_b128 v[156:159], v101 offset:41504
	v_mfma_f32_32x32x16_bf16 v[0:15], v[124:127], v[132:135], v[0:15]
	s_waitcnt lgkmcnt(1)
	v_mfma_f32_32x32x16_bf16 v[48:63], v[120:123], v[152:155], v[48:63]
	v_mfma_f32_32x32x16_bf16 v[32:47], v[128:131], v[152:155], v[32:47]
	s_waitcnt lgkmcnt(0)
	v_mfma_f32_32x32x16_bf16 v[16:31], v[120:123], v[156:159], v[16:31]
	ds_read_b128 v[120:123], v102 offset:55360
	ds_read_b128 v[124:127], v102 offset:59968
	ds_read_b128 v[132:135], v101 offset:36928
	ds_read_b128 v[152:155], v101 offset:41536
	s_waitcnt vmcnt(15)
	ds_write_b128 v100, v[64:67]
	s_waitcnt vmcnt(13)
	ds_write_b128 v100, v[72:75] offset:4608
	s_waitcnt vmcnt(11)
	ds_write_b128 v100, v[136:139] offset:9216
	s_waitcnt vmcnt(9)
	ds_write_b128 v100, v[144:147] offset:13824
	v_mfma_f32_32x32x16_bf16 v[0:15], v[128:131], v[156:159], v[0:15]
	s_waitcnt lgkmcnt(5)
	v_mfma_f32_32x32x16_bf16 v[48:63], v[120:123], v[132:135], v[48:63]
	s_waitcnt lgkmcnt(4)
	v_mfma_f32_32x32x16_bf16 v[16:31], v[120:123], v[152:155], v[16:31]
	ds_read_b128 v[64:67], v102 offset:55392
	ds_read_b128 v[72:75], v102 offset:60000
	ds_read_b128 v[120:123], v101 offset:36960
	ds_read_b128 v[128:131], v101 offset:41568
	ds_write_b128 v100, v[68:71] offset:18432
	ds_write_b128 v100, v[76:79] offset:23040
	ds_write_b128 v100, v[140:143] offset:27648
	s_waitcnt vmcnt(8)
	ds_write_b128 v100, v[148:151] offset:32256
	v_mfma_f32_32x32x16_bf16 v[32:47], v[124:127], v[132:135], v[32:47]
	v_mfma_f32_32x32x16_bf16 v[0:15], v[124:127], v[152:155], v[0:15]
	s_waitcnt lgkmcnt(5)
	v_mfma_f32_32x32x16_bf16 v[48:63], v[64:67], v[120:123], v[48:63]
	v_mfma_f32_32x32x16_bf16 v[32:47], v[72:75], v[120:123], v[32:47]
	s_waitcnt lgkmcnt(4)
	v_mfma_f32_32x32x16_bf16 v[16:31], v[64:67], v[128:131], v[16:31]
	v_mfma_f32_32x32x16_bf16 v[0:15], v[72:75], v[128:131], v[0:15]
	s_waitcnt lgkmcnt(0)
	s_barrier
	ds_read_b128 v[64:67], v102 offset:18432
	ds_read_b128 v[68:71], v102 offset:23040
	ds_read_b128 v[72:75], v101
	ds_read_b128 v[76:79], v101 offset:4608
	s_waitcnt lgkmcnt(1)
	v_mfma_f32_32x32x16_bf16 v[48:63], v[64:67], v[72:75], v[48:63]
	v_mfma_f32_32x32x16_bf16 v[32:47], v[68:71], v[72:75], v[32:47]
	s_waitcnt lgkmcnt(0)
	v_mfma_f32_32x32x16_bf16 v[16:31], v[64:67], v[76:79], v[16:31]
	ds_read_b128 v[64:67], v102 offset:18464
	ds_read_b128 v[72:75], v102 offset:23072
	ds_read_b128 v[120:123], v101 offset:32
	ds_read_b128 v[124:127], v101 offset:4640
	v_mfma_f32_32x32x16_bf16 v[0:15], v[68:71], v[76:79], v[0:15]
	s_waitcnt lgkmcnt(1)
	v_mfma_f32_32x32x16_bf16 v[48:63], v[64:67], v[120:123], v[48:63]
	v_mfma_f32_32x32x16_bf16 v[32:47], v[72:75], v[120:123], v[32:47]
	s_waitcnt lgkmcnt(0)
	v_mfma_f32_32x32x16_bf16 v[16:31], v[64:67], v[124:127], v[16:31]
	ds_read_b128 v[64:67], v102 offset:18496
	ds_read_b128 v[68:71], v102 offset:23104
	ds_read_b128 v[76:79], v101 offset:64
	ds_read_b128 v[120:123], v101 offset:4672
	s_waitcnt vmcnt(7)
	ds_write_b128 v100, v[104:107] offset:36864
	s_waitcnt vmcnt(5)
	ds_write_b128 v100, v[108:111] offset:41472
	s_waitcnt vmcnt(3)
	ds_write_b128 v100, v[112:115] offset:46080
	s_waitcnt vmcnt(1)
	ds_write_b128 v100, v[116:119] offset:50688
	v_mfma_f32_32x32x16_bf16 v[0:15], v[72:75], v[124:127], v[0:15]
	s_waitcnt lgkmcnt(5)
	v_mfma_f32_32x32x16_bf16 v[48:63], v[64:67], v[76:79], v[48:63]
	v_mfma_f32_32x32x16_bf16 v[32:47], v[68:71], v[76:79], v[32:47]
	s_waitcnt lgkmcnt(4)
	v_mfma_f32_32x32x16_bf16 v[16:31], v[64:67], v[120:123], v[16:31]
	ds_read_b128 v[64:67], v102 offset:18528
	ds_read_b128 v[72:75], v102 offset:23136
	ds_read_b128 v[76:79], v101 offset:96
	ds_read_b128 v[104:107], v101 offset:4704
	ds_write_b128 v100, v[80:83] offset:55296
	ds_write_b128 v100, v[84:87] offset:59904
	ds_write_b128 v100, v[88:91] offset:64512
	s_waitcnt vmcnt(0)
	ds_write_b128 v103, v[92:95] offset:13824
	v_mfma_f32_32x32x16_bf16 v[0:15], v[68:71], v[120:123], v[0:15]
	s_waitcnt lgkmcnt(5)
	v_mfma_f32_32x32x16_bf16 v[48:63], v[64:67], v[76:79], v[48:63]
	v_mfma_f32_32x32x16_bf16 v[32:47], v[72:75], v[76:79], v[32:47]
	s_waitcnt lgkmcnt(4)
	v_mfma_f32_32x32x16_bf16 v[16:31], v[64:67], v[104:107], v[16:31]
	v_mfma_f32_32x32x16_bf16 v[0:15], v[72:75], v[104:107], v[0:15]
	s_waitcnt lgkmcnt(0)
	s_barrier
; DI bf16_t f2bf(float x) { return (bf16_t)(pk_bf16(x, 0.f) & 0xffffu); }
; DI int crow(int r, int h) { return (r & 3) + 8 * (r >> 2) + 4 * h; }
; template <bool SWAP>
; DI void gemm_tile(const bf16_t* __restrict__ A, int lda, const bf16_t* __restrict__ Bt, int ldb, int K, f32x16 (&acc)[2][2], bf16_t* As, bf16_t* Bs_unused) {
;     ...
;   auto step = [&](int buf, u32x4 (&ra)[4], u32x4 (&rb)[4], bool do_write, bool do_load, int tload) __attribute__((always_inline)) {
;     const bf16_t* pa = As + buf * 2 * GT_IMG + pao; const bf16_t* pb = As + buf * 2 * GT_IMG + pbo;
;     bf16_t* Ad = As + (buf ^ 1) * 2 * GT_IMG; bf16_t* Bd = Ad + GT_IMG;
;     bf16x8 F0[4], F1[4];
;     frag_read(F0, pa, pb, 0);
;     __builtin_amdgcn_sched_barrier(0);
;     frag_read(F1, pa, pb, 16);
;     mfma4(F0);
;     __builtin_amdgcn_sched_barrier(0);
;     frag_read(F0, pa, pb, 32);
;     mfma4(F1);
;     if (do_write) {
; #pragma unroll
;       for (int i = 0; i < 4; ++i) *(u32x4*)(Ad + (lr + 32 * i) * 72 + lc) = ra[i];
;     }
;     __builtin_amdgcn_sched_barrier(0);
;     frag_read(F1, pa, pb, 48);
;     mfma4(F0);
;     if (do_write) {
; #pragma unroll
;       for (int i = 0; i < 4; ++i) *(u32x4*)(Bd + (lr + 32 * i) * 72 + lc) = rb[i];
;     }
;     __builtin_amdgcn_sched_barrier(0);
;     mfma4(F1);
;     if (do_load) load_stage(ra, rb, tload);
;     __builtin_amdgcn_sched_barrier(0);
;   };
; DI void phase_up(const Params& p, int g, char* smem, int bid, int nb) {
;     ...
; #pragma unroll
;     for (int mi = 0; mi < 2; ++mi)
; #pragma unroll
;       for (int ni = 0; ni < 2; ++ni)
; #pragma unroll
;         for (int r = 0; r < 16; ++r) {
;           const float v = fmaxf(acc[mi][ni][r], 0.f);
;           (U + (size_t)mt * 128 * 4096)[(wm * 64 + mi * 32 + crow(r, h)) * 4096 + nt * 128 + wn * 64 + ni * 32 + l31] = f2bf(v * v);
;         }
	ds_read_b128 v[64:67], v102 offset:55296
	ds_read_b128 v[68:71], v102 offset:59904
	ds_read_b128 v[72:75], v101 offset:36864
	ds_read_b128 v[76:79], v101 offset:41472
	s_waitcnt lgkmcnt(1)
	v_mfma_f32_32x32x16_bf16 v[48:63], v[64:67], v[72:75], v[48:63]
	v_mfma_f32_32x32x16_bf16 v[32:47], v[68:71], v[72:75], v[32:47]
	s_waitcnt lgkmcnt(0)
	v_mfma_f32_32x32x16_bf16 v[16:31], v[64:67], v[76:79], v[16:31]
	ds_read_b128 v[64:67], v102 offset:55328
	ds_read_b128 v[72:75], v102 offset:59936
	ds_read_b128 v[80:83], v101 offset:36896
	ds_read_b128 v[84:87], v101 offset:41504
	v_mfma_f32_32x32x16_bf16 v[0:15], v[68:71], v[76:79], v[0:15]
	s_waitcnt lgkmcnt(1)
	v_mfma_f32_32x32x16_bf16 v[48:63], v[64:67], v[80:83], v[48:63]
	v_mfma_f32_32x32x16_bf16 v[32:47], v[72:75], v[80:83], v[32:47]
	s_waitcnt lgkmcnt(0)
	v_mfma_f32_32x32x16_bf16 v[16:31], v[64:67], v[84:87], v[16:31]
	v_mfma_f32_32x32x16_bf16 v[0:15], v[72:75], v[84:87], v[0:15]
	ds_read_b128 v[64:67], v101 offset:41536
	ds_read_b128 v[68:71], v102 offset:59968
	ds_read_b128 v[72:75], v102 offset:55360
	ds_read_b128 v[76:79], v101 offset:36928
	s_waitcnt lgkmcnt(0)
	v_mfma_f32_32x32x16_bf16 v[48:63], v[72:75], v[76:79], v[48:63]
	v_mfma_f32_32x32x16_bf16 v[32:47], v[68:71], v[76:79], v[32:47]
	v_mfma_f32_32x32x16_bf16 v[16:31], v[72:75], v[64:67], v[16:31]
	v_mfma_f32_32x32x16_bf16 v[0:15], v[68:71], v[64:67], v[0:15]
	ds_read_b128 v[64:67], v101 offset:41568
	ds_read_b128 v[68:71], v102 offset:60000
	ds_read_b128 v[72:75], v102 offset:55392
	ds_read_b128 v[76:79], v101 offset:36960
	s_waitcnt lgkmcnt(0)
	v_mfma_f32_32x32x16_bf16 v[48:63], v[72:75], v[76:79], v[48:63]
	v_mfma_f32_32x32x16_bf16 v[32:47], v[68:71], v[76:79], v[32:47]
	v_mfma_f32_32x32x16_bf16 v[16:31], v[72:75], v[64:67], v[16:31]
	v_mfma_f32_32x32x16_bf16 v[0:15], v[68:71], v[64:67], v[0:15]
	s_lshl_b64 s[6:7], s[6:7], 20
	s_barrier
	s_add_u32 s6, s94, s6
	s_addc_u32 s7, s95, s7
	s_lshl_b32 s0, s0, 8
	s_movk_i32 s1, 0x90
	v_and_b32_e32 v64, 63, v195
	v_lshrrev_b32_e32 v65, 6, v195
	v_and_b32_e32 v66, 31, v64
	v_lshrrev_b32_e32 v67, 5, v64
	v_mul_u32_u24_e32 v68, 0x2400, v65
	v_lshrrev_b32_e32 v70, 3, v64
	v_and_b32_e32 v71, 7, v64
	v_mad_u32_u24 v69, v66, s1, v68
	v_mad_u32_u24 v72, v70, s1, v68
	v_lshl_add_u32 v69, v67, 3, v69
	v_lshl_add_u32 v72, v71, 4, v72
	v_add_u32_e32 v69, 32, v69
	v_add_u32_e32 v72, 32, v72
	v_lshl_add_u32 v73, v96, 6, v70
	v_lshlrev_b32_e32 v73, 13, v73
	v_lshl_add_u32 v73, v97, 7, v73
	v_lshl_add_u32 v73, v71, 4, v73
	v_add_u32_e32 v76, s0, v73
	v_mov_b32_e32 v77, 0
	s_mov_b64 s[8:9], 0x10000
	v_lshl_add_u64 v[136:137], s[6:7], 0, v[76:77]
	v_lshl_add_u64 v[138:139], v[136:137], 0, s[8:9]
	v_lshl_add_u64 v[140:141], v[138:139], 0, s[8:9]
	v_lshl_add_u64 v[142:143], v[140:141], 0, s[8:9]
	v_lshl_add_u64 v[144:145], v[142:143], 0, s[8:9]
	v_lshl_add_u64 v[146:147], v[144:145], 0, s[8:9]
	v_lshl_add_u64 v[148:149], v[146:147], 0, s[8:9]
	v_lshl_add_u64 v[150:151], v[148:149], 0, s[8:9]
	v_max_f32_e32 v48, 0, v48
	v_max_f32_e32 v49, 0, v49
	v_max_f32_e32 v50, 0, v50
	v_max_f32_e32 v51, 0, v51
	v_mul_f32_e32 v48, v48, v48
	v_mul_f32_e32 v49, v49, v49
	v_mul_f32_e32 v50, v50, v50
	v_mul_f32_e32 v51, v51, v51
	v_cvt_pk_bf16_f32 v48, v48, v49
	v_cvt_pk_bf16_f32 v49, v50, v51
	ds_write_b64 v69, v[48:49]
	v_max_f32_e32 v52, 0, v52
	v_max_f32_e32 v53, 0, v53
	v_max_f32_e32 v54, 0, v54
	v_max_f32_e32 v55, 0, v55
	v_mul_f32_e32 v52, v52, v52
	v_mul_f32_e32 v53, v53, v53
	v_mul_f32_e32 v54, v54, v54
	v_mul_f32_e32 v55, v55, v55
	v_cvt_pk_bf16_f32 v52, v52, v53
	v_cvt_pk_bf16_f32 v53, v54, v55
	ds_write_b64 v69, v[52:53] offset:16
	v_max_f32_e32 v56, 0, v56
	v_max_f32_e32 v57, 0, v57
	v_max_f32_e32 v58, 0, v58
	v_max_f32_e32 v59, 0, v59
	v_mul_f32_e32 v56, v56, v56
	v_mul_f32_e32 v57, v57, v57
	v_mul_f32_e32 v58, v58, v58
	v_mul_f32_e32 v59, v59, v59
	v_cvt_pk_bf16_f32 v56, v56, v57
	v_cvt_pk_bf16_f32 v57, v58, v59
	ds_write_b64 v69, v[56:57] offset:32
	v_max_f32_e32 v60, 0, v60
	v_max_f32_e32 v61, 0, v61
	v_max_f32_e32 v62, 0, v62
	v_max_f32_e32 v63, 0, v63
	v_mul_f32_e32 v60, v60, v60
	v_mul_f32_e32 v61, v61, v61
	v_mul_f32_e32 v62, v62, v62
	v_mul_f32_e32 v63, v63, v63
	v_cvt_pk_bf16_f32 v60, v60, v61
	v_cvt_pk_bf16_f32 v61, v62, v63
	ds_write_b64 v69, v[60:61] offset:48
	v_max_f32_e32 v32, 0, v32
	v_max_f32_e32 v33, 0, v33
	v_max_f32_e32 v34, 0, v34
	v_max_f32_e32 v35, 0, v35
	v_mul_f32_e32 v32, v32, v32
	v_mul_f32_e32 v33, v33, v33
	v_mul_f32_e32 v34, v34, v34
	v_mul_f32_e32 v35, v35, v35
	v_cvt_pk_bf16_f32 v32, v32, v33
	v_cvt_pk_bf16_f32 v33, v34, v35
	ds_write_b64 v69, v[32:33] offset:64
	v_max_f32_e32 v36, 0, v36
	v_max_f32_e32 v37, 0, v37
	v_max_f32_e32 v38, 0, v38
	v_max_f32_e32 v39, 0, v39
	v_mul_f32_e32 v36, v36, v36
	v_mul_f32_e32 v37, v37, v37
	v_mul_f32_e32 v38, v38, v38
	v_mul_f32_e32 v39, v39, v39
	v_cvt_pk_bf16_f32 v36, v36, v37
	v_cvt_pk_bf16_f32 v37, v38, v39
	ds_write_b64 v69, v[36:37] offset:80
	v_max_f32_e32 v40, 0, v40
	v_max_f32_e32 v41, 0, v41
	v_max_f32_e32 v42, 0, v42
	v_max_f32_e32 v43, 0, v43
	v_mul_f32_e32 v40, v40, v40
	v_mul_f32_e32 v41, v41, v41
	v_mul_f32_e32 v42, v42, v42
	v_mul_f32_e32 v43, v43, v43
	v_cvt_pk_bf16_f32 v40, v40, v41
	v_cvt_pk_bf16_f32 v41, v42, v43
	ds_write_b64 v69, v[40:41] offset:96
	v_max_f32_e32 v44, 0, v44
	v_max_f32_e32 v45, 0, v45
	v_max_f32_e32 v46, 0, v46
	v_max_f32_e32 v47, 0, v47
	v_mul_f32_e32 v44, v44, v44
	v_mul_f32_e32 v45, v45, v45
	v_mul_f32_e32 v46, v46, v46
	v_mul_f32_e32 v47, v47, v47
	v_cvt_pk_bf16_f32 v44, v44, v45
	v_cvt_pk_bf16_f32 v45, v46, v47
	ds_write_b64 v69, v[44:45] offset:112
	v_max_f32_e32 v16, 0, v16
	v_max_f32_e32 v17, 0, v17
	v_max_f32_e32 v18, 0, v18
	v_max_f32_e32 v19, 0, v19
	v_mul_f32_e32 v16, v16, v16
	v_mul_f32_e32 v17, v17, v17
	v_mul_f32_e32 v18, v18, v18
	v_mul_f32_e32 v19, v19, v19
	v_cvt_pk_bf16_f32 v16, v16, v17
	v_cvt_pk_bf16_f32 v17, v18, v19
	s_waitcnt lgkmcnt(4)
; DI bf16_t f2bf(float x) { return (bf16_t)(pk_bf16(x, 0.f) & 0xffffu); }
; DI int crow(int r, int h) { return (r & 3) + 8 * (r >> 2) + 4 * h; }
; DI void phase_up(const Params& p, int g, char* smem, int bid, int nb) {
;     ...
; #pragma unroll
;     for (int mi = 0; mi < 2; ++mi)
; #pragma unroll
;       for (int ni = 0; ni < 2; ++ni)
; #pragma unroll
;         for (int r = 0; r < 16; ++r) {
;           const float v = fmaxf(acc[mi][ni][r], 0.f);
;           (U + (size_t)mt * 128 * 4096)[(wm * 64 + mi * 32 + crow(r, h)) * 4096 + nt * 128 + wn * 64 + ni * 32 + l31] = f2bf(v * v);
;         }
	ds_write_b64 v69, v[16:17] offset:4608
	v_max_f32_e32 v20, 0, v20
	v_max_f32_e32 v21, 0, v21
	v_max_f32_e32 v22, 0, v22
	v_max_f32_e32 v23, 0, v23
	v_mul_f32_e32 v20, v20, v20
	v_mul_f32_e32 v21, v21, v21
	v_mul_f32_e32 v22, v22, v22
	v_mul_f32_e32 v23, v23, v23
	v_cvt_pk_bf16_f32 v20, v20, v21
	v_cvt_pk_bf16_f32 v21, v22, v23
	ds_write_b64 v69, v[20:21] offset:4624
	v_max_f32_e32 v24, 0, v24
	v_max_f32_e32 v25, 0, v25
	v_max_f32_e32 v26, 0, v26
	v_max_f32_e32 v27, 0, v27
	v_mul_f32_e32 v24, v24, v24
	v_mul_f32_e32 v25, v25, v25
	v_mul_f32_e32 v26, v26, v26
	v_mul_f32_e32 v27, v27, v27
	v_cvt_pk_bf16_f32 v24, v24, v25
	v_cvt_pk_bf16_f32 v25, v26, v27
	ds_write_b64 v69, v[24:25] offset:4640
	v_max_f32_e32 v28, 0, v28
	v_max_f32_e32 v29, 0, v29
	v_max_f32_e32 v30, 0, v30
	v_max_f32_e32 v31, 0, v31
	v_mul_f32_e32 v28, v28, v28
	v_mul_f32_e32 v29, v29, v29
	v_mul_f32_e32 v30, v30, v30
	v_mul_f32_e32 v31, v31, v31
	v_cvt_pk_bf16_f32 v28, v28, v29
	v_cvt_pk_bf16_f32 v29, v30, v31
	ds_write_b64 v69, v[28:29] offset:4656
	v_max_f32_e32 v0, 0, v0
	v_max_f32_e32 v1, 0, v1
	v_max_f32_e32 v2, 0, v2
	v_max_f32_e32 v3, 0, v3
	v_mul_f32_e32 v0, v0, v0
	v_mul_f32_e32 v1, v1, v1
	v_mul_f32_e32 v2, v2, v2
	v_mul_f32_e32 v3, v3, v3
	v_cvt_pk_bf16_f32 v0, v0, v1
	v_cvt_pk_bf16_f32 v1, v2, v3
	s_waitcnt lgkmcnt(4)
	ds_write_b64 v69, v[0:1] offset:4672
	v_max_f32_e32 v4, 0, v4
	v_max_f32_e32 v5, 0, v5
	v_max_f32_e32 v6, 0, v6
	v_max_f32_e32 v7, 0, v7
	v_mul_f32_e32 v4, v4, v4
	v_mul_f32_e32 v5, v5, v5
	v_mul_f32_e32 v6, v6, v6
	v_mul_f32_e32 v7, v7, v7
	v_cvt_pk_bf16_f32 v4, v4, v5
	v_cvt_pk_bf16_f32 v5, v6, v7
	ds_write_b64 v69, v[4:5] offset:4688
	v_max_f32_e32 v8, 0, v8
	v_max_f32_e32 v9, 0, v9
	v_max_f32_e32 v10, 0, v10
	v_max_f32_e32 v11, 0, v11
	v_mul_f32_e32 v8, v8, v8
	v_mul_f32_e32 v9, v9, v9
	v_mul_f32_e32 v10, v10, v10
	v_mul_f32_e32 v11, v11, v11
	v_cvt_pk_bf16_f32 v8, v8, v9
	v_cvt_pk_bf16_f32 v9, v10, v11
	ds_write_b64 v69, v[8:9] offset:4704
	v_max_f32_e32 v12, 0, v12
	v_max_f32_e32 v13, 0, v13
	v_max_f32_e32 v14, 0, v14
	v_max_f32_e32 v15, 0, v15
	v_mul_f32_e32 v12, v12, v12
	v_mul_f32_e32 v13, v13, v13
	v_mul_f32_e32 v14, v14, v14
	v_mul_f32_e32 v15, v15, v15
	v_cvt_pk_bf16_f32 v12, v12, v13
	v_cvt_pk_bf16_f32 v13, v14, v15
	ds_write_b64 v69, v[12:13] offset:4720
	s_waitcnt lgkmcnt(0)
	ds_read_b128 v[104:107], v72
	ds_read_b128 v[108:111], v72 offset:1152
	ds_read_b128 v[112:115], v72 offset:2304
	ds_read_b128 v[116:119], v72 offset:3456
	ds_read_b128 v[120:123], v72 offset:4608
	ds_read_b128 v[124:127], v72 offset:5760
	ds_read_b128 v[128:131], v72 offset:6912
	ds_read_b128 v[132:135], v72 offset:8064
	s_waitcnt lgkmcnt(7)
	global_store_dwordx4 v[136:137], v[104:107], off
	s_waitcnt lgkmcnt(6)
	global_store_dwordx4 v[138:139], v[108:111], off
	s_waitcnt lgkmcnt(5)
	global_store_dwordx4 v[140:141], v[112:115], off
	s_waitcnt lgkmcnt(4)
	global_store_dwordx4 v[142:143], v[116:119], off
	s_waitcnt lgkmcnt(3)
	global_store_dwordx4 v[144:145], v[120:123], off
	s_waitcnt lgkmcnt(2)
	global_store_dwordx4 v[146:147], v[124:127], off
	s_waitcnt lgkmcnt(1)
	global_store_dwordx4 v[148:149], v[128:131], off
	s_waitcnt lgkmcnt(0)
	global_store_dwordx4 v[150:151], v[132:135], off
	s_add_i32 s11, s11, s12
	s_cmp_ge_i32 s11, s13
	s_cbranch_scc1 .LBB0_198

; __device__ __forceinline__ int TID() { int t = threadIdx.x; asm volatile("" : "+v"(t)); return t; }
; DI void attn_item(const Params& p, int g, int seq, int hd, int qt, int m, char* smem, int split_j, int sub) {
;     ...
;   const int tid = TID(), lane = tid & 63, wave = __builtin_amdgcn_readfirstlane(tid >> 6), h_ = lane >> 5, l31_ = lane & 31;
;   __syncthreads();
;   for (int i = tid; i < 257; i += 256) tab[i] = p.rel_bias[t5_bucket(i - 128) * 8 + hd] * LOG2E;
;   const float cneg = p.rel_bias[15 * 8 + hd] * LOG2E, cpos = p.rel_bias[31 * 8 + hd] * LOG2E;
;   const bf16_t* qrow = proj + (size_t)(sb + q0 + wave * 32 + l31_) * NPROJ + hd * 128 + h_ * 8;
;   const int kr0 = tid >> 3, kc = (tid & 7) * 8;
;   const int vr0 = tid >> 2, vc = (tid & 3) * 8;
;   const bf16_t* vsrc = vaT + (size_t)(hd * 512 + (sb >> 5)) * 4096 + tid * 8;
;   const int npairs = (split_j < 0) ? (S >> 6) : (S >> 6) / SPLIT_SP;
;   const int tbase = (split_j < 0) ? 0 : split_j * npairs * 2;
;   const int qw0 = q0 + wave * 32;
;   bf16x8 qf[4];
; #pragma unroll
;   for (int s = 0; s < 4; ++s) qf[s] = *(const bf16x8*)(qrow + m * 64 + s * 16);
;   f32x16 O[4];
; #pragma unroll
;   for (int dt = 0; dt < 4; ++dt)
; #pragma unroll
;     for (int r = 0; r < 16; ++r) O[dt][r] = 0.f;
;   f32x2 ls2 = {0.f, 0.f};
;   int region = 0;
;   const bf16_t* ksrc = (const bf16_t*)(p.ws + OFF_KBLK) + (size_t)((hd * 2 + m) * 512 + (sb >> 5)) * 2048 + tid * 8;
;   u32x4 rkA, rvA0, rvA1, rkB, rvB0, rvB1;
;   auto load_tile = [&](int t, u32x4& k, u32x4& v0, u32x4& v1) __attribute__((always_inline)) {
;     k = *(const u32x4*)(ksrc + (size_t)(tbase + t) * 2048);
;     v0 = *(const u32x4*)(vsrc + (size_t)(tbase + t) * 4096); v1 = *(const u32x4*)(vsrc + (size_t)(tbase + t) * 4096 + 2048);
;   };
;     ...
;   load_tile(0, rkA, rvA0, rvA1);
;   load_tile(1, rkB, rvB0, rvB1);
;   __syncthreads();
;   store_tile(0, rkA, rvA0, rvA1);
;   store_tile(1, rkB, rvB0, rvB1);
;   __syncthreads();
;   for (int it = 0; it < npairs; ++it) {
;     const int set = it & 1;
;     if (it + 1 < npairs) { load_tile(2 * it + 2, rkA, rvA0, rvA1); load_tile(2 * it + 3, rkB, rvB0, rvB1); }
.LBB0_264:
	s_or_b64 exec, exec, s[6:7]
	v_readlane_b32 s0, v231, 30
	s_sub_i32 s1, s12, s0
	s_lshr_b32 s0, s1, 2
	v_readlane_b32 s6, v231, 29
	s_add_i32 s0, s0, s6
	s_lshr_b32 s0, s0, 1
	v_readlane_b32 s6, v231, 32
	v_readlane_b32 s7, v231, 33
	s_lshr_b32 s6, s0, s6
	s_and_b32 s0, s0, s7
	v_readlane_b32 s7, v231, 37
	s_lshl_b32 s9, s6, s7
	v_readlane_b32 s6, v233, 14
	s_lshl_b32 s14, s0, 7
	v_readlane_b32 s7, v233, 15
	v_and_b32_e32 v168, 31, v0
	s_nop 3
	global_load_dword v1, v193, s[6:7] offset:480
	global_load_dword v10, v193, s[6:7] offset:992
	s_add_i32 s6, s14, s9
	s_ashr_i32 s0, s13, 1
	v_or_b32_e32 v2, s6, v168
	v_readlane_b32 s6, v233, 16
	s_andn2_b32 s0, s0, 31
	v_readlane_b32 s7, v233, 17
	v_add_u32_e32 v4, s0, v2
	s_bfe_u32 s8, s1, 0x10002
	v_mov_b64_e32 v[2:3], s[6:7]
	v_mad_i64_i32 v[2:3], s[6:7], v4, s2, v[2:3]
	s_lshl_b32 s7, s12, 1
	s_lshl_b32 s6, s9, 8
	v_readlane_b32 s11, v233, 13
	s_and_b32 s7, s7, 6
	v_readlane_b32 s10, v231, 38
	v_lshlrev_b32_e32 v4, 3, v0
	s_add_i32 s6, s6, s11
	s_lshl_b32 s10, s7, s10
	s_lshl_b32 s50, s8, 7
	v_ashrrev_i32_e32 v5, 31, v4
	s_add_u32 s6, s60, s6
	s_addc_u32 s7, s61, 0
	v_lshlrev_b64 v[6:7], 1, v[4:5]
	v_lshl_add_u64 v[176:177], s[6:7], 0, v[6:7]
	s_lshl_b32 s6, s8, 21
	s_lshl_b32 s7, s9, 7
	s_or_b32 s6, s6, s11
	v_bfe_u32 v188, v0, 5, 1
	s_add_i32 s6, s6, s7
	v_readlane_b32 s8, v233, 18
	v_lshlrev_b32_e32 v192, 4, v188
	v_readlane_b32 s9, v233, 19
	s_add_u32 s6, s8, s6
	v_lshl_add_u64 v[2:3], v[2:3], 0, v[192:193]
	s_addc_u32 s7, s9, 0
	v_lshl_add_u64 v[2:3], v[2:3], 0, s[50:51]
	v_lshl_add_u64 v[178:179], s[6:7], 0, v[6:7]
	s_lshl_b32 s50, s10, 12
	v_lshl_add_u64 v[6:7], v[178:179], 0, s[50:51]
	s_lshl_b32 s50, s10, 13
	v_lshl_add_u64 v[8:9], v[176:177], 0, s[50:51]
	global_load_dwordx4 v[96:99], v[6:7], off
	global_load_dwordx4 v[100:103], v[8:9], off
	v_add_co_u32_e32 v6, vcc, s81, v8
	s_or_b32 s6, s10, 1
	s_nop 0
	v_addc_co_u32_e32 v7, vcc, 0, v9, vcc
	s_lshl_b32 s50, s6, 12
	v_lshl_add_u64 v[8:9], v[178:179], 0, s[50:51]
	global_load_dwordx4 v[120:123], v[6:7], off
	global_load_dwordx4 v[124:127], v[8:9], off
	s_lshl_b32 s50, s6, 13
	v_lshl_add_u64 v[6:7], v[176:177], 0, s[50:51]
	v_add_co_u32_e32 v8, vcc, s81, v6
	v_and_b32_e32 v4, 24, v4
	s_nop 0
	v_addc_co_u32_e32 v9, vcc, 0, v7, vcc
	global_load_dwordx4 v[128:131], v[6:7], off
	global_load_dwordx4 v[132:135], v[8:9], off
	global_load_dwordx4 v[104:107], v[2:3], off
	global_load_dwordx4 v[108:111], v[2:3], off offset:32
	global_load_dwordx4 v[112:115], v[2:3], off offset:64
	global_load_dwordx4 v[116:119], v[2:3], off offset:96
	v_lshrrev_b32_e32 v2, 2, v0
	v_lshrrev_b32_e32 v3, 3, v0
	v_lshlrev_b32_e32 v0, 4, v0
	v_mul_lo_u32 v3, v3, s22
	v_and_b32_e32 v0, 0x70, v0
	v_mul_lo_u32 v2, v2, 40
	v_mul_u32_u24_e32 v5, 40, v168
	v_add3_u32 v189, 32, v3, v0
	v_lshlrev_b32_e32 v190, 1, v2
	v_lshlrev_b32_e32 v191, 1, v4
	v_add_u32_e32 v0, 32, v192
	s_add_i32 s14, s14, s0
	v_add3_u32 v2, 32, v190, v191
	v_mad_u32_u24 v196, v168, s22, v0
	v_lshl_add_u32 v197, v5, 1, v0
	v_or_b32_e32 v0, s14, v168
	v_mov_b32_e32 v14, v193
	v_mov_b32_e32 v15, v193
	s_waitcnt vmcnt(11) lgkmcnt(0)
	v_mul_f32_e32 v1, 0x3fb8aa3b, v1
	s_waitcnt vmcnt(10)
	v_mul_f32_e32 v169, 0x3fb8aa3b, v10
	v_exp_f32_e32 v170, v1
	v_exp_f32_e64 v180, -v169
	v_lshlrev_b32_e32 v1, 2, v188
	s_barrier
	v_sub_u32_e32 v198, v1, v0
	v_mov_b32_e32 v192, v193
	v_mov_b32_e32 v0, v193
	v_mov_b32_e32 v1, v193
	v_mov_b32_e32 v3, v193
	v_mov_b32_e32 v4, v193
	s_waitcnt vmcnt(9)
	ds_write_b128 v189, v[96:99]
	s_waitcnt vmcnt(8)
	ds_write_b128 v2, v[100:103] offset:18432
	s_waitcnt vmcnt(7)
	ds_write_b128 v2, v[120:123] offset:23552
	s_waitcnt vmcnt(6)
	ds_write_b128 v189, v[124:127] offset:4608
	s_waitcnt vmcnt(5)
	ds_write_b128 v2, v[128:131] offset:28672
	s_waitcnt vmcnt(4)
	ds_write_b128 v2, v[132:135] offset:33792
	v_mov_b32_e32 v2, v193
	v_mov_b32_e32 v5, v193
	v_mov_b32_e32 v6, v193
	v_mov_b32_e32 v7, v193
	v_mov_b32_e32 v8, v193
	v_mov_b32_e32 v9, v193
	v_mov_b32_e32 v10, v193
	v_mov_b32_e32 v11, v193
	v_mov_b32_e32 v12, v193
	v_mov_b32_e32 v13, v193
	v_mov_b64_e32 v[62:63], v[14:15]
	v_mov_b64_e32 v[46:47], v[14:15]
	v_mov_b64_e32 v[30:31], v[14:15]
	s_mov_b32 s11, 0
	v_mov_b32_e32 v172, v170
	v_mov_b32_e32 v173, v170
	v_mov_b32_e32 v182, v180
	v_mov_b32_e32 v183, v180
	v_mov_b32_e32 v174, v170
	v_mov_b32_e32 v175, v170
	v_mov_b32_e32 v184, v180
	v_mov_b32_e32 v185, v180
	s_lshl_b32 s13, s10, 5
	s_sub_i32 s14, 0, s14
	v_mov_b64_e32 v[60:61], v[12:13]
	v_mov_b64_e32 v[58:59], v[10:11]
	v_mov_b64_e32 v[56:57], v[8:9]
	v_mov_b64_e32 v[54:55], v[6:7]
	v_mov_b64_e32 v[52:53], v[4:5]
	v_mov_b64_e32 v[50:51], v[2:3]
	v_mov_b64_e32 v[48:49], v[0:1]
	v_mov_b64_e32 v[44:45], v[12:13]
	v_mov_b64_e32 v[42:43], v[10:11]
	v_mov_b64_e32 v[40:41], v[8:9]
	v_mov_b64_e32 v[38:39], v[6:7]
	v_mov_b64_e32 v[36:37], v[4:5]
	v_mov_b64_e32 v[34:35], v[2:3]
	v_mov_b64_e32 v[32:33], v[0:1]
	v_mov_b64_e32 v[28:29], v[12:13]
	v_mov_b64_e32 v[26:27], v[10:11]
	v_mov_b64_e32 v[24:25], v[8:9]
	v_mov_b64_e32 v[22:23], v[6:7]
	v_mov_b64_e32 v[20:21], v[4:5]
	v_mov_b64_e32 v[18:19], v[2:3]
	v_mov_b64_e32 v[16:17], v[0:1]
	s_mov_b32 s15, 0
	s_mov_b32 s16, 0
	v_mov_b64_e32 v[186:187], v[192:193]
	s_waitcnt vmcnt(0) lgkmcnt(0)
	s_add_i32 s15, s15, 1
	s_cmp_lt_u32 s15, s77
	s_cselect_b64 s[6:7], -1, 0
	s_cmp_ge_u32 s15, s77
	s_cbranch_scc1 .Lar_p
	s_add_i32 s17, s10, s11
	s_add_i32 s50, s17, 2
	s_lshl_b64 s[8:9], s[50:51], 12
	v_lshl_add_u64 v[236:237], v[178:179], 0, s[8:9]
	s_lshl_b64 s[8:9], s[50:51], 13
	v_lshl_add_u64 v[238:239], v[176:177], 0, s[8:9]
	s_add_i32 s50, s17, 3
	global_load_dwordx4 v[96:99], v[236:237], off
	global_load_dwordx4 v[100:103], v[238:239], off
	v_add_co_u32_e32 v236, vcc, 0x1000, v238
	s_lshl_b64 s[8:9], s[50:51], 12
	s_nop 0
	v_addc_co_u32_e32 v237, vcc, 0, v239, vcc
	v_lshl_add_u64 v[238:239], v[178:179], 0, s[8:9]
	s_lshl_b64 s[8:9], s[50:51], 13
	global_load_dwordx4 v[120:123], v[236:237], off
	global_load_dwordx4 v[124:127], v[238:239], off
	v_lshl_add_u64 v[236:237], v[176:177], 0, s[8:9]
	v_add_co_u32_e32 v238, vcc, 0x1000, v236
	s_nop 1
	v_addc_co_u32_e32 v239, vcc, 0, v237, vcc
	global_load_dwordx4 v[128:131], v[236:237], off
	global_load_dwordx4 v[132:135], v[238:239], off
; #define MFMA32(a, b, c) __builtin_amdgcn_mfma_f32_32x32x16_bf16((a), (b), (c), 0, 0, 0)
; DI unsigned pk_bf16(float lo, float hi) { f32x2 v = {lo, hi}; bf16v2 b = __builtin_convertvector(v, bf16v2); return __builtin_bit_cast(unsigned, b); }
; DI void attn_item(const Params& p, int g, int seq, int hd, int qt, int m, char* smem, int split_j, int sub) {
;     ...
;     for (int s2 = 0; s2 < 2; ++s2) {
;       u32x4 w; w.x = pk_bf16(X[8 * s2], X[8 * s2 + 1]); w.y = pk_bf16(X[8 * s2 + 2], X[8 * s2 + 3]); w.z = pk_bf16(X[8 * s2 + 4], X[8 * s2 + 5]); w.w = pk_bf16(X[8 * s2 + 6], X[8 * s2 + 7]);
;       ls2 += (f32x2){X[8 * s2], X[8 * s2 + 1]}; ls2 += (f32x2){X[8 * s2 + 2], X[8 * s2 + 3]};
;       ls2 += (f32x2){X[8 * s2 + 4], X[8 * s2 + 5]}; ls2 += (f32x2){X[8 * s2 + 6], X[8 * s2 + 7]};
;       pf[s2] = __builtin_bit_cast(bf16x8, w);
;     }
; #pragma unroll
;     for (int s2 = 0; s2 < 2; ++s2)
; #pragma unroll
;       for (int dt = 0; dt < 4; ++dt) O[dt] = MFMA32(pf[s2], vf[s2][dt], O[dt]);
;   };
;   load_tile(0, rkA, rvA0, rvA1);
;   load_tile(1, rkB, rvB0, rvB1);
;   __syncthreads();
;   store_tile(0, rkA, rvA0, rvA1);
;   store_tile(1, rkB, rvB0, rvB1);
;   __syncthreads();
;   for (int it = 0; it < npairs; ++it) {
;     const int set = it & 1;
;     if (it + 1 < npairs) { load_tile(2 * it + 2, rkA, rvA0, rvA1); load_tile(2 * it + 3, rkB, rvB0, rvB1); }
;     compute(2 * it, 2 * set);
;     compute(2 * it + 1, 2 * set + 1);
;     if (it + 1 < npairs) { store_tile(2 * (set ^ 1), rkA, rvA0, rvA1); store_tile(2 * (set ^ 1) + 1, rkB, rvB0, rvB1); }
;     __syncthreads();
.Lar_p:
	s_barrier
	s_branch .LBB0_268
.LBB0_265:
	v_pk_add_f32 v[64:65], v[186:187], v[64:65]
	s_add_i32 s11, s11, 2
	v_pk_add_f32 v[64:65], v[66:67], v[64:65]
	s_add_i32 s14, s14, 64
	v_pk_add_f32 v[64:65], v[68:69], v[64:65]
	v_add_u32_e32 v198, 64, v198
	v_pk_add_f32 v[64:65], v[70:71], v[64:65]
	v_pk_add_f32 v[64:65], v[72:73], v[64:65]
	v_pk_add_f32 v[64:65], v[74:75], v[64:65]
	v_pk_add_f32 v[64:65], v[76:77], v[64:65]
	s_nop 0
	v_pk_add_f32 v[186:187], v[78:79], v[64:65]
	s_cmp_lg_u32 s77, s15
	s_cbranch_scc0 .Lar_exit
	s_add_i32 s15, s15, 1
	s_cmp_lt_u32 s15, s77
	s_cselect_b64 s[6:7], -1, 0
	s_cmp_ge_u32 s15, s77
	s_cbranch_scc1 .Lar_t
	s_add_i32 s17, s10, s11
	s_add_i32 s50, s17, 2
	s_lshl_b64 s[8:9], s[50:51], 12
	v_lshl_add_u64 v[236:237], v[178:179], 0, s[8:9]
	s_lshl_b64 s[8:9], s[50:51], 13
	v_lshl_add_u64 v[238:239], v[176:177], 0, s[8:9]
	s_add_i32 s50, s17, 3
	global_load_dwordx4 v[96:99], v[236:237], off
	global_load_dwordx4 v[100:103], v[238:239], off
	v_add_co_u32_e32 v236, vcc, 0x1000, v238
	s_lshl_b64 s[8:9], s[50:51], 12
	s_nop 0
	v_addc_co_u32_e32 v237, vcc, 0, v239, vcc
	v_lshl_add_u64 v[238:239], v[178:179], 0, s[8:9]
	s_lshl_b64 s[8:9], s[50:51], 13
	global_load_dwordx4 v[120:123], v[236:237], off
	global_load_dwordx4 v[124:127], v[238:239], off
	v_lshl_add_u64 v[236:237], v[176:177], 0, s[8:9]
	v_add_co_u32_e32 v238, vcc, 0x1000, v236
	s_nop 1
	v_addc_co_u32_e32 v239, vcc, 0, v237, vcc
	global_load_dwordx4 v[128:131], v[236:237], off
	global_load_dwordx4 v[132:135], v[238:239], off
.Lar_t:
	s_waitcnt lgkmcnt(0)
	s_barrier
	s_branch .LBB0_268

; DI int crow(int r, int h) { return (r & 3) + 8 * (r >> 2) + 4 * h; }
;   DI bool next(int& mt, int& nt) {
;     if (j >= total) return false;
;     if (simple) { mt = j & 127; nt = j >> 7; }
;     else { const int half = j / (8 * NT), jj = j - half * 8 * NT; mt = xcd * 16 + half * 8 + (jj & 7); nt = jj >> 3; }
;     j += step; return true;
;   }
; DI void phase_gemm1(const Params& p, int g, char* smem, int bid, int nb) {
;     ...
;     } else {
;       if (wn == 0) {
; #pragma unroll
;         for (int mi = 0; mi < 2; ++mi)
; #pragma unroll
;           for (int r = 0; r < 16; ++r) (lrb + (size_t)row0 * 32)[(wm * 64 + mi * 32 + crow(r, h)) * 32 + l31] = acc[mi][0][r];
;       }
.LBB0_360:
	s_andn2_b64 vcc, exec, s[6:7]
	s_cbranch_vccnz .LBB0_362
	s_cmp_ge_i32 s35, 0x400
	s_cbranch_scc1 .Lp2_lr
	s_lshr_b32 s6, s35, 9
	s_lshl_b32 s7, s6, 3
	s_add_i32 s7, s7, s34
	s_and_b32 s8, s35, 7
	s_or_b32 s10, s7, s8
	s_bfe_u32 s12, s35, 0x60003
	s_branch .Lp2_dec
.Lp2_lr:
	s_add_i32 s10, s35, 0xfffffc00
	s_add_i32 s10, s10, s34
	s_movk_i32 s12, 64
.Lp2_dec:
.LBB0_362:
	s_add_i32 s35, s35, s36
	s_andn2_b64 vcc, exec, s[0:1]
	s_mov_b64 s[0:1], -1
	s_cbranch_vccnz .LBB0_355
.LBB0_363:
	s_ashr_i32 s11, s10, 31
	s_and_b32 s22, s12, -8
	s_lshl_b64 s[0:1], s[10:11], 18
	s_add_u32 s0, s63, s0
	s_addc_u32 s1, s70, s1
	s_ashr_i32 s13, s12, 31
	s_lshl_b64 s[6:7], s[12:13], 18
	s_add_u32 s6, s96, s6
	s_addc_u32 s7, s97, s7
	s_cmp_lg_u32 s12, 64
	s_cbranch_scc1 .Llr_skip
	v_lshrrev_b32_e32 v88, 6, v195
	v_and_b32_e32 v89, 31, v195
	v_bfe_u32 v90, v195, 5, 1
	v_lshlrev_b32_e32 v86, 11, v89
	v_lshl_add_u32 v86, v90, 4, v86
	v_lshl_add_u32 v84, v88, 16, v86
	v_mov_b32_e32 v85, 0
	v_mov_b32_e32 v87, 0
	v_lshl_add_u64 v[84:85], s[0:1], 0, v[84:85]
	v_lshl_add_u64 v[86:87], s[6:7], 0, v[86:87]
	s_lshl_b32 s8, s10, 14
	s_add_u32 s8, s8, 0x146c8000
	s_addc_u32 s9, 0, 0
	s_add_u32 s8, s96, s8
	s_addc_u32 s9, s97, s9
	v_lshlrev_b32_e32 v92, 2, v89
	v_lshl_add_u32 v92, v90, 9, v92
	v_lshl_add_u32 v92, v88, 12, v92
	global_load_dwordx4 v[16:19], v[84:85], off
	global_load_dwordx4 v[32:35], v[86:87], off
	global_load_dwordx4 v[20:23], v[84:85], off offset:32
	global_load_dwordx4 v[36:39], v[86:87], off offset:32
	global_load_dwordx4 v[24:27], v[84:85], off offset:64
	global_load_dwordx4 v[40:43], v[86:87], off offset:64
	global_load_dwordx4 v[28:31], v[84:85], off offset:96
	global_load_dwordx4 v[44:47], v[86:87], off offset:96
	global_load_dwordx4 v[48:51], v[84:85], off offset:128
	global_load_dwordx4 v[104:107], v[86:87], off offset:128
	global_load_dwordx4 v[52:55], v[84:85], off offset:160
	global_load_dwordx4 v[108:111], v[86:87], off offset:160
	global_load_dwordx4 v[56:59], v[84:85], off offset:192
	global_load_dwordx4 v[112:115], v[86:87], off offset:192
	global_load_dwordx4 v[60:63], v[84:85], off offset:224
	global_load_dwordx4 v[116:119], v[86:87], off offset:224
	s_waitcnt vmcnt(8)
	v_mfma_f32_32x32x16_bf16 v[0:15], v[16:19], v[32:35], 0
	v_mfma_f32_32x32x16_bf16 v[0:15], v[20:23], v[36:39], v[0:15]
	v_mfma_f32_32x32x16_bf16 v[0:15], v[24:27], v[40:43], v[0:15]
	v_mfma_f32_32x32x16_bf16 v[0:15], v[28:31], v[44:47], v[0:15]
	global_load_dwordx4 v[16:19], v[84:85], off offset:256
	global_load_dwordx4 v[32:35], v[86:87], off offset:256
	global_load_dwordx4 v[20:23], v[84:85], off offset:288
	global_load_dwordx4 v[36:39], v[86:87], off offset:288
	global_load_dwordx4 v[24:27], v[84:85], off offset:320
	global_load_dwordx4 v[40:43], v[86:87], off offset:320
	global_load_dwordx4 v[28:31], v[84:85], off offset:352
	global_load_dwordx4 v[44:47], v[86:87], off offset:352
	s_waitcnt vmcnt(8)
	v_mfma_f32_32x32x16_bf16 v[0:15], v[48:51], v[104:107], v[0:15]
	v_mfma_f32_32x32x16_bf16 v[0:15], v[52:55], v[108:111], v[0:15]
	v_mfma_f32_32x32x16_bf16 v[0:15], v[56:59], v[112:115], v[0:15]
	v_mfma_f32_32x32x16_bf16 v[0:15], v[60:63], v[116:119], v[0:15]
	global_load_dwordx4 v[48:51], v[84:85], off offset:384
	global_load_dwordx4 v[104:107], v[86:87], off offset:384
	global_load_dwordx4 v[52:55], v[84:85], off offset:416
	global_load_dwordx4 v[108:111], v[86:87], off offset:416
	global_load_dwordx4 v[56:59], v[84:85], off offset:448
	global_load_dwordx4 v[112:115], v[86:87], off offset:448
	global_load_dwordx4 v[60:63], v[84:85], off offset:480
	global_load_dwordx4 v[116:119], v[86:87], off offset:480
	s_waitcnt vmcnt(8)
	v_mfma_f32_32x32x16_bf16 v[0:15], v[16:19], v[32:35], v[0:15]
	v_mfma_f32_32x32x16_bf16 v[0:15], v[20:23], v[36:39], v[0:15]
	v_mfma_f32_32x32x16_bf16 v[0:15], v[24:27], v[40:43], v[0:15]
	v_mfma_f32_32x32x16_bf16 v[0:15], v[28:31], v[44:47], v[0:15]
	global_load_dwordx4 v[16:19], v[84:85], off offset:512
	global_load_dwordx4 v[32:35], v[86:87], off offset:512
	global_load_dwordx4 v[20:23], v[84:85], off offset:544
	global_load_dwordx4 v[36:39], v[86:87], off offset:544
	global_load_dwordx4 v[24:27], v[84:85], off offset:576
	global_load_dwordx4 v[40:43], v[86:87], off offset:576
	global_load_dwordx4 v[28:31], v[84:85], off offset:608
	global_load_dwordx4 v[44:47], v[86:87], off offset:608
	s_waitcnt vmcnt(8)
	v_mfma_f32_32x32x16_bf16 v[0:15], v[48:51], v[104:107], v[0:15]
	v_mfma_f32_32x32x16_bf16 v[0:15], v[52:55], v[108:111], v[0:15]
	v_mfma_f32_32x32x16_bf16 v[0:15], v[56:59], v[112:115], v[0:15]
	v_mfma_f32_32x32x16_bf16 v[0:15], v[60:63], v[116:119], v[0:15]
	global_load_dwordx4 v[48:51], v[84:85], off offset:640
	global_load_dwordx4 v[104:107], v[86:87], off offset:640
	global_load_dwordx4 v[52:55], v[84:85], off offset:672
	global_load_dwordx4 v[108:111], v[86:87], off offset:672
	global_load_dwordx4 v[56:59], v[84:85], off offset:704
	global_load_dwordx4 v[112:115], v[86:87], off offset:704
	global_load_dwordx4 v[60:63], v[84:85], off offset:736
	global_load_dwordx4 v[116:119], v[86:87], off offset:736
	s_waitcnt vmcnt(8)
	v_mfma_f32_32x32x16_bf16 v[0:15], v[16:19], v[32:35], v[0:15]
	v_mfma_f32_32x32x16_bf16 v[0:15], v[20:23], v[36:39], v[0:15]
	v_mfma_f32_32x32x16_bf16 v[0:15], v[24:27], v[40:43], v[0:15]
	v_mfma_f32_32x32x16_bf16 v[0:15], v[28:31], v[44:47], v[0:15]
	global_load_dwordx4 v[16:19], v[84:85], off offset:768
	global_load_dwordx4 v[32:35], v[86:87], off offset:768
	global_load_dwordx4 v[20:23], v[84:85], off offset:800
	global_load_dwordx4 v[36:39], v[86:87], off offset:800
	global_load_dwordx4 v[24:27], v[84:85], off offset:832
	global_load_dwordx4 v[40:43], v[86:87], off offset:832
	global_load_dwordx4 v[28:31], v[84:85], off offset:864
	global_load_dwordx4 v[44:47], v[86:87], off offset:864
	s_waitcnt vmcnt(8)
; DI int crow(int r, int h) { return (r & 3) + 8 * (r >> 2) + 4 * h; }
; DI void phase_gemm1(const Params& p, int g, char* smem, int bid, int nb) {
;     ...
;     f32x16 acc[2][2]; zero_acc(acc);
;     const bool swp = (nt >= 16 && nt < 24) || (nt >= 32 && nt < 40);
;     const bf16_t* A = H + (size_t)mt * 128 * 1024; const bf16_t* B = W + (size_t)nt * 128 * 1024;
;     if (swp) gemm_tile<true>(A, 1024, B, 1024, 1024, acc, As, Bs); else gemm_tile<false>(A, 1024, B, 1024, 1024, acc, As, Bs);
;     ...
;     } else {
;       if (wn == 0) {
; #pragma unroll
;         for (int mi = 0; mi < 2; ++mi)
; #pragma unroll
;           for (int r = 0; r < 16; ++r) (lrb + (size_t)row0 * 32)[(wm * 64 + mi * 32 + crow(r, h)) * 32 + l31] = acc[mi][0][r];
;       }
	v_mfma_f32_32x32x16_bf16 v[0:15], v[48:51], v[104:107], v[0:15]
	v_mfma_f32_32x32x16_bf16 v[0:15], v[52:55], v[108:111], v[0:15]
	v_mfma_f32_32x32x16_bf16 v[0:15], v[56:59], v[112:115], v[0:15]
	v_mfma_f32_32x32x16_bf16 v[0:15], v[60:63], v[116:119], v[0:15]
	global_load_dwordx4 v[48:51], v[84:85], off offset:896
	global_load_dwordx4 v[104:107], v[86:87], off offset:896
	global_load_dwordx4 v[52:55], v[84:85], off offset:928
	global_load_dwordx4 v[108:111], v[86:87], off offset:928
	global_load_dwordx4 v[56:59], v[84:85], off offset:960
	global_load_dwordx4 v[112:115], v[86:87], off offset:960
	global_load_dwordx4 v[60:63], v[84:85], off offset:992
	global_load_dwordx4 v[116:119], v[86:87], off offset:992
	s_waitcnt vmcnt(8)
	v_mfma_f32_32x32x16_bf16 v[0:15], v[16:19], v[32:35], v[0:15]
	v_mfma_f32_32x32x16_bf16 v[0:15], v[20:23], v[36:39], v[0:15]
	v_mfma_f32_32x32x16_bf16 v[0:15], v[24:27], v[40:43], v[0:15]
	v_mfma_f32_32x32x16_bf16 v[0:15], v[28:31], v[44:47], v[0:15]
	global_load_dwordx4 v[16:19], v[84:85], off offset:1024
	global_load_dwordx4 v[32:35], v[86:87], off offset:1024
	global_load_dwordx4 v[20:23], v[84:85], off offset:1056
	global_load_dwordx4 v[36:39], v[86:87], off offset:1056
	global_load_dwordx4 v[24:27], v[84:85], off offset:1088
	global_load_dwordx4 v[40:43], v[86:87], off offset:1088
	global_load_dwordx4 v[28:31], v[84:85], off offset:1120
	global_load_dwordx4 v[44:47], v[86:87], off offset:1120
	s_waitcnt vmcnt(8)
	v_mfma_f32_32x32x16_bf16 v[0:15], v[48:51], v[104:107], v[0:15]
	v_mfma_f32_32x32x16_bf16 v[0:15], v[52:55], v[108:111], v[0:15]
	v_mfma_f32_32x32x16_bf16 v[0:15], v[56:59], v[112:115], v[0:15]
	v_mfma_f32_32x32x16_bf16 v[0:15], v[60:63], v[116:119], v[0:15]
	global_load_dwordx4 v[48:51], v[84:85], off offset:1152
	global_load_dwordx4 v[104:107], v[86:87], off offset:1152
	global_load_dwordx4 v[52:55], v[84:85], off offset:1184
	global_load_dwordx4 v[108:111], v[86:87], off offset:1184
	global_load_dwordx4 v[56:59], v[84:85], off offset:1216
	global_load_dwordx4 v[112:115], v[86:87], off offset:1216
	global_load_dwordx4 v[60:63], v[84:85], off offset:1248
	global_load_dwordx4 v[116:119], v[86:87], off offset:1248
	s_waitcnt vmcnt(8)
	v_mfma_f32_32x32x16_bf16 v[0:15], v[16:19], v[32:35], v[0:15]
	v_mfma_f32_32x32x16_bf16 v[0:15], v[20:23], v[36:39], v[0:15]
	v_mfma_f32_32x32x16_bf16 v[0:15], v[24:27], v[40:43], v[0:15]
	v_mfma_f32_32x32x16_bf16 v[0:15], v[28:31], v[44:47], v[0:15]
	global_load_dwordx4 v[16:19], v[84:85], off offset:1280
	global_load_dwordx4 v[32:35], v[86:87], off offset:1280
	global_load_dwordx4 v[20:23], v[84:85], off offset:1312
	global_load_dwordx4 v[36:39], v[86:87], off offset:1312
	global_load_dwordx4 v[24:27], v[84:85], off offset:1344
	global_load_dwordx4 v[40:43], v[86:87], off offset:1344
	global_load_dwordx4 v[28:31], v[84:85], off offset:1376
	global_load_dwordx4 v[44:47], v[86:87], off offset:1376
	s_waitcnt vmcnt(8)
	v_mfma_f32_32x32x16_bf16 v[0:15], v[48:51], v[104:107], v[0:15]
	v_mfma_f32_32x32x16_bf16 v[0:15], v[52:55], v[108:111], v[0:15]
	v_mfma_f32_32x32x16_bf16 v[0:15], v[56:59], v[112:115], v[0:15]
	v_mfma_f32_32x32x16_bf16 v[0:15], v[60:63], v[116:119], v[0:15]
	global_load_dwordx4 v[48:51], v[84:85], off offset:1408
	global_load_dwordx4 v[104:107], v[86:87], off offset:1408
	global_load_dwordx4 v[52:55], v[84:85], off offset:1440
	global_load_dwordx4 v[108:111], v[86:87], off offset:1440
	global_load_dwordx4 v[56:59], v[84:85], off offset:1472
	global_load_dwordx4 v[112:115], v[86:87], off offset:1472
	global_load_dwordx4 v[60:63], v[84:85], off offset:1504
	global_load_dwordx4 v[116:119], v[86:87], off offset:1504
	s_waitcnt vmcnt(8)
	v_mfma_f32_32x32x16_bf16 v[0:15], v[16:19], v[32:35], v[0:15]
	v_mfma_f32_32x32x16_bf16 v[0:15], v[20:23], v[36:39], v[0:15]
	v_mfma_f32_32x32x16_bf16 v[0:15], v[24:27], v[40:43], v[0:15]
	v_mfma_f32_32x32x16_bf16 v[0:15], v[28:31], v[44:47], v[0:15]
	global_load_dwordx4 v[16:19], v[84:85], off offset:1536
	global_load_dwordx4 v[32:35], v[86:87], off offset:1536
	global_load_dwordx4 v[20:23], v[84:85], off offset:1568
	global_load_dwordx4 v[36:39], v[86:87], off offset:1568
	global_load_dwordx4 v[24:27], v[84:85], off offset:1600
	global_load_dwordx4 v[40:43], v[86:87], off offset:1600
	global_load_dwordx4 v[28:31], v[84:85], off offset:1632
	global_load_dwordx4 v[44:47], v[86:87], off offset:1632
	s_waitcnt vmcnt(8)
; DI int crow(int r, int h) { return (r & 3) + 8 * (r >> 2) + 4 * h; }
; DI void phase_gemm1(const Params& p, int g, char* smem, int bid, int nb) {
;     ...
;     } else {
;       if (wn == 0) {
; #pragma unroll
;         for (int mi = 0; mi < 2; ++mi)
; #pragma unroll
;           for (int r = 0; r < 16; ++r) (lrb + (size_t)row0 * 32)[(wm * 64 + mi * 32 + crow(r, h)) * 32 + l31] = acc[mi][0][r];
;       }
	v_mfma_f32_32x32x16_bf16 v[0:15], v[48:51], v[104:107], v[0:15]
	v_mfma_f32_32x32x16_bf16 v[0:15], v[52:55], v[108:111], v[0:15]
	v_mfma_f32_32x32x16_bf16 v[0:15], v[56:59], v[112:115], v[0:15]
	v_mfma_f32_32x32x16_bf16 v[0:15], v[60:63], v[116:119], v[0:15]
	global_load_dwordx4 v[48:51], v[84:85], off offset:1664
	global_load_dwordx4 v[104:107], v[86:87], off offset:1664
	global_load_dwordx4 v[52:55], v[84:85], off offset:1696
	global_load_dwordx4 v[108:111], v[86:87], off offset:1696
	global_load_dwordx4 v[56:59], v[84:85], off offset:1728
	global_load_dwordx4 v[112:115], v[86:87], off offset:1728
	global_load_dwordx4 v[60:63], v[84:85], off offset:1760
	global_load_dwordx4 v[116:119], v[86:87], off offset:1760
	s_waitcnt vmcnt(8)
	v_mfma_f32_32x32x16_bf16 v[0:15], v[16:19], v[32:35], v[0:15]
	v_mfma_f32_32x32x16_bf16 v[0:15], v[20:23], v[36:39], v[0:15]
	v_mfma_f32_32x32x16_bf16 v[0:15], v[24:27], v[40:43], v[0:15]
	v_mfma_f32_32x32x16_bf16 v[0:15], v[28:31], v[44:47], v[0:15]
	global_load_dwordx4 v[16:19], v[84:85], off offset:1792
	global_load_dwordx4 v[32:35], v[86:87], off offset:1792
	global_load_dwordx4 v[20:23], v[84:85], off offset:1824
	global_load_dwordx4 v[36:39], v[86:87], off offset:1824
	global_load_dwordx4 v[24:27], v[84:85], off offset:1856
	global_load_dwordx4 v[40:43], v[86:87], off offset:1856
	global_load_dwordx4 v[28:31], v[84:85], off offset:1888
	global_load_dwordx4 v[44:47], v[86:87], off offset:1888
	s_waitcnt vmcnt(8)
	v_mfma_f32_32x32x16_bf16 v[0:15], v[48:51], v[104:107], v[0:15]
	v_mfma_f32_32x32x16_bf16 v[0:15], v[52:55], v[108:111], v[0:15]
	v_mfma_f32_32x32x16_bf16 v[0:15], v[56:59], v[112:115], v[0:15]
	v_mfma_f32_32x32x16_bf16 v[0:15], v[60:63], v[116:119], v[0:15]
	global_load_dwordx4 v[48:51], v[84:85], off offset:1920
	global_load_dwordx4 v[104:107], v[86:87], off offset:1920
	global_load_dwordx4 v[52:55], v[84:85], off offset:1952
	global_load_dwordx4 v[108:111], v[86:87], off offset:1952
	global_load_dwordx4 v[56:59], v[84:85], off offset:1984
	global_load_dwordx4 v[112:115], v[86:87], off offset:1984
	global_load_dwordx4 v[60:63], v[84:85], off offset:2016
	global_load_dwordx4 v[116:119], v[86:87], off offset:2016
	s_waitcnt vmcnt(8)
	v_mfma_f32_32x32x16_bf16 v[0:15], v[16:19], v[32:35], v[0:15]
	v_mfma_f32_32x32x16_bf16 v[0:15], v[20:23], v[36:39], v[0:15]
	v_mfma_f32_32x32x16_bf16 v[0:15], v[24:27], v[40:43], v[0:15]
	v_mfma_f32_32x32x16_bf16 v[0:15], v[28:31], v[44:47], v[0:15]
	s_waitcnt vmcnt(0)
	v_mfma_f32_32x32x16_bf16 v[0:15], v[48:51], v[104:107], v[0:15]
	v_mfma_f32_32x32x16_bf16 v[0:15], v[52:55], v[108:111], v[0:15]
	v_mfma_f32_32x32x16_bf16 v[0:15], v[56:59], v[112:115], v[0:15]
	v_mfma_f32_32x32x16_bf16 v[0:15], v[60:63], v[116:119], v[0:15]
	s_nop 15
	s_nop 3
	global_store_dword v92, v0, s[8:9]
	global_store_dword v92, v1, s[8:9] offset:128
	global_store_dword v92, v2, s[8:9] offset:256
	global_store_dword v92, v3, s[8:9] offset:384
	global_store_dword v92, v4, s[8:9] offset:1024
	global_store_dword v92, v5, s[8:9] offset:1152
	global_store_dword v92, v6, s[8:9] offset:1280
	global_store_dword v92, v7, s[8:9] offset:1408
	global_store_dword v92, v8, s[8:9] offset:2048
	global_store_dword v92, v9, s[8:9] offset:2176
	global_store_dword v92, v10, s[8:9] offset:2304
	global_store_dword v92, v11, s[8:9] offset:2432
	global_store_dword v92, v12, s[8:9] offset:3072
	global_store_dword v92, v13, s[8:9] offset:3200
	global_store_dword v92, v14, s[8:9] offset:3328
	global_store_dword v92, v15, s[8:9] offset:3456
	s_branch .LBB0_354
.Llr_skip:
	s_cmp_lt_i32 s22, 32
	s_cbranch_scc1 .LBB0_365
	s_cmp_lg_u32 s22, 32
	s_mov_b64 s[8:9], -1
	s_cselect_b64 s[14:15], -1, 0
	s_cbranch_execz .LBB0_366
	s_branch .LBB0_367

; DI bf16_t f2bf(float x) { return (bf16_t)(pk_bf16(x, 0.f) & 0xffffu); }
; DI int crow(int r, int h) { return (r & 3) + 8 * (r >> 2) + 4 * h; }
; DI float sigmoidf_(float x) { return 1.f / (1.f + __expf(-x)); }
; DI void phase_gemm1(const Params& p, int g, char* smem, int bid, int nb) {
;     ...
;     } else if (nt < 64) {
;       const int coff = (nt < 32) ? nt * 128 - 2048 : nt * 128 - 3072;
;       const int mode = (nt < 32) ? 0 : (nt < 48 ? 1 : 2);
; #pragma unroll
;       for (int mi = 0; mi < 2; ++mi)
; #pragma unroll
;         for (int ni = 0; ni < 2; ++ni)
; #pragma unroll
;           for (int r = 0; r < 16; ++r) {
;             float v = acc[mi][ni][r];
;             if (mode == 1) v = v * sigmoidf_(v); else if (mode == 2) v = sigmoidf_(v);
;             projt[(wm * 64 + mi * 32 + crow(r, h)) * NPROJ + coff + wn * 64 + ni * 32 + l31] = f2bf(v);
;           }
.LBB0_378:
	s_andn2_b64 vcc, exec, s[0:1]
	s_cbranch_vccnz .LBB0_731
	s_lshl_b32 s11, s12, 7
	s_cmp_lt_u32 s12, 32
	s_movk_i32 s0, 0xf800
	s_cselect_b32 s13, s0, 0xfffff400
	s_add_i32 s13, s13, s11
	v_mul_u32_u24_e32 v66, 0x50000, v124
	v_mul_u32_u24_e32 v67, 0x5000, v119
	v_lshlrev_b32_e32 v65, 6, v118
	v_add_u32_e32 v66, v66, v67
	v_add3_u32 v65, s13, v65, v64
	v_add_u32_e32 v66, v66, v65
	v_ashrrev_i32_e32 v67, 31, v66
	v_lshl_add_u64 v[66:67], v[66:67], 1, s[8:9]
	s_mov_b64 s[14:15], 0x2800
	s_cmp_lt_u32 s12, 32
	s_cbranch_scc1 .Lep2_t0
	s_cmp_lt_u32 s12, 48
	s_cbranch_scc1 .Lep2_t1
	v_lshl_add_u64 v[70:71], v[66:67], 0, s[14:15]
	v_lshl_add_u64 v[72:73], v[70:71], 0, s[14:15]
	v_lshl_add_u64 v[74:75], v[72:73], 0, s[14:15]
	v_mul_f32_e32 v76, 0xbfb8aa3b, v48
	v_mul_f32_e32 v82, 0xbfb8aa3b, v32
	v_exp_f32_e32 v76, v76
	v_exp_f32_e32 v82, v82
	v_add_f32_e32 v76, 1.0, v76
	v_add_f32_e32 v82, 1.0, v82
	v_div_scale_f32 v77, s[0:1], v76, v76, 1.0
	v_div_scale_f32 v83, s[0:1], v82, v82, 1.0
	v_rcp_f32_e32 v78, v77
	v_rcp_f32_e32 v84, v83
	v_div_scale_f32 v79, vcc, 1.0, v76, 1.0
	v_fma_f32 v80, -v77, v78, 1.0
	v_fmac_f32_e32 v78, v80, v78
	v_mul_f32_e32 v80, v79, v78
	v_fma_f32 v81, -v77, v80, v79
	v_fmac_f32_e32 v80, v81, v78
	v_fma_f32 v77, -v77, v80, v79
	v_div_fmas_f32 v77, v77, v78, v80
	v_div_fixup_f32 v48, v77, v76, 1.0
	v_cvt_pk_bf16_f32 v48, v48, v48
	global_store_short v[66:67], v48, off
	v_div_scale_f32 v79, vcc, 1.0, v82, 1.0
	v_fma_f32 v80, -v83, v84, 1.0
	v_fmac_f32_e32 v84, v80, v84
	v_mul_f32_e32 v80, v79, v84
	v_fma_f32 v81, -v83, v80, v79
	v_fmac_f32_e32 v80, v81, v84
	v_fma_f32 v83, -v83, v80, v79
	v_div_fmas_f32 v83, v83, v84, v80
	v_div_fixup_f32 v32, v83, v82, 1.0
	v_cvt_pk_bf16_f32 v32, v32, v32
	global_store_short v[66:67], v32, off offset:64
	v_mul_f32_e32 v76, 0xbfb8aa3b, v49
	v_mul_f32_e32 v82, 0xbfb8aa3b, v33
	v_exp_f32_e32 v76, v76
	v_exp_f32_e32 v82, v82
	v_add_f32_e32 v76, 1.0, v76
	v_add_f32_e32 v82, 1.0, v82
	v_div_scale_f32 v77, s[0:1], v76, v76, 1.0
	v_div_scale_f32 v83, s[0:1], v82, v82, 1.0
	v_rcp_f32_e32 v78, v77
	v_rcp_f32_e32 v84, v83
	v_div_scale_f32 v79, vcc, 1.0, v76, 1.0
	v_fma_f32 v80, -v77, v78, 1.0
	v_fmac_f32_e32 v78, v80, v78
	v_mul_f32_e32 v80, v79, v78
	v_fma_f32 v81, -v77, v80, v79
	v_fmac_f32_e32 v80, v81, v78
	v_fma_f32 v77, -v77, v80, v79
	v_div_fmas_f32 v77, v77, v78, v80
	v_div_fixup_f32 v49, v77, v76, 1.0
	v_cvt_pk_bf16_f32 v49, v49, v49
	global_store_short v[70:71], v49, off
	v_div_scale_f32 v79, vcc, 1.0, v82, 1.0
	v_fma_f32 v80, -v83, v84, 1.0
	v_fmac_f32_e32 v84, v80, v84
	v_mul_f32_e32 v80, v79, v84
	v_fma_f32 v81, -v83, v80, v79
	v_fmac_f32_e32 v80, v81, v84
	v_fma_f32 v83, -v83, v80, v79
	v_div_fmas_f32 v83, v83, v84, v80
	v_div_fixup_f32 v33, v83, v82, 1.0
	v_cvt_pk_bf16_f32 v33, v33, v33
	global_store_short v[70:71], v33, off offset:64
	v_mul_f32_e32 v76, 0xbfb8aa3b, v50
	v_mul_f32_e32 v82, 0xbfb8aa3b, v34
	v_exp_f32_e32 v76, v76
	v_exp_f32_e32 v82, v82
	v_add_f32_e32 v76, 1.0, v76
	v_add_f32_e32 v82, 1.0, v82
	v_div_scale_f32 v77, s[0:1], v76, v76, 1.0
	v_div_scale_f32 v83, s[0:1], v82, v82, 1.0
	v_rcp_f32_e32 v78, v77
	v_rcp_f32_e32 v84, v83
	v_div_scale_f32 v79, vcc, 1.0, v76, 1.0
	v_fma_f32 v80, -v77, v78, 1.0
	v_fmac_f32_e32 v78, v80, v78
	v_mul_f32_e32 v80, v79, v78
	v_fma_f32 v81, -v77, v80, v79
	v_fmac_f32_e32 v80, v81, v78
	v_fma_f32 v77, -v77, v80, v79
	v_div_fmas_f32 v77, v77, v78, v80
	v_div_fixup_f32 v50, v77, v76, 1.0
	v_cvt_pk_bf16_f32 v50, v50, v50
	global_store_short v[72:73], v50, off
	v_div_scale_f32 v79, vcc, 1.0, v82, 1.0
	v_fma_f32 v80, -v83, v84, 1.0
	v_fmac_f32_e32 v84, v80, v84
	v_mul_f32_e32 v80, v79, v84
	v_fma_f32 v81, -v83, v80, v79
	v_fmac_f32_e32 v80, v81, v84
	v_fma_f32 v83, -v83, v80, v79
	v_div_fmas_f32 v83, v83, v84, v80
	v_div_fixup_f32 v34, v83, v82, 1.0
	v_cvt_pk_bf16_f32 v34, v34, v34
	global_store_short v[72:73], v34, off offset:64
	v_mul_f32_e32 v76, 0xbfb8aa3b, v51
	v_mul_f32_e32 v82, 0xbfb8aa3b, v35
	v_exp_f32_e32 v76, v76
	v_exp_f32_e32 v82, v82
	v_add_f32_e32 v76, 1.0, v76
	v_add_f32_e32 v82, 1.0, v82
	v_div_scale_f32 v77, s[0:1], v76, v76, 1.0
	v_div_scale_f32 v83, s[0:1], v82, v82, 1.0
	v_rcp_f32_e32 v78, v77
	v_rcp_f32_e32 v84, v83
	v_div_scale_f32 v79, vcc, 1.0, v76, 1.0
	v_fma_f32 v80, -v77, v78, 1.0
	v_fmac_f32_e32 v78, v80, v78
	v_mul_f32_e32 v80, v79, v78
	v_fma_f32 v81, -v77, v80, v79
	v_fmac_f32_e32 v80, v81, v78
	v_fma_f32 v77, -v77, v80, v79
	v_div_fmas_f32 v77, v77, v78, v80
	v_div_fixup_f32 v51, v77, v76, 1.0
	v_cvt_pk_bf16_f32 v51, v51, v51
	global_store_short v[74:75], v51, off
	v_div_scale_f32 v79, vcc, 1.0, v82, 1.0
	v_fma_f32 v80, -v83, v84, 1.0
	v_fmac_f32_e32 v84, v80, v84
	v_mul_f32_e32 v80, v79, v84
	v_fma_f32 v81, -v83, v80, v79
	v_fmac_f32_e32 v80, v81, v84
	v_fma_f32 v83, -v83, v80, v79
	v_div_fmas_f32 v83, v83, v84, v80
	v_div_fixup_f32 v35, v83, v82, 1.0
	v_cvt_pk_bf16_f32 v35, v35, v35
	global_store_short v[74:75], v35, off offset:64
	s_mov_b64 s[0:1], 0x14000
	v_lshl_add_u64 v[68:69], v[66:67], 0, s[0:1]
	v_lshl_add_u64 v[70:71], v[68:69], 0, s[14:15]
	v_lshl_add_u64 v[72:73], v[70:71], 0, s[14:15]
	v_lshl_add_u64 v[74:75], v[72:73], 0, s[14:15]
	v_mul_f32_e32 v76, 0xbfb8aa3b, v52
	v_mul_f32_e32 v82, 0xbfb8aa3b, v36
	v_exp_f32_e32 v76, v76
	v_exp_f32_e32 v82, v82
	v_add_f32_e32 v76, 1.0, v76
	v_add_f32_e32 v82, 1.0, v82
	v_div_scale_f32 v77, s[0:1], v76, v76, 1.0
	v_div_scale_f32 v83, s[0:1], v82, v82, 1.0
	v_rcp_f32_e32 v78, v77
	v_rcp_f32_e32 v84, v83
	v_div_scale_f32 v79, vcc, 1.0, v76, 1.0
	v_fma_f32 v80, -v77, v78, 1.0
	v_fmac_f32_e32 v78, v80, v78
	v_mul_f32_e32 v80, v79, v78
	v_fma_f32 v81, -v77, v80, v79
; DI bf16_t f2bf(float x) { return (bf16_t)(pk_bf16(x, 0.f) & 0xffffu); }
; DI int crow(int r, int h) { return (r & 3) + 8 * (r >> 2) + 4 * h; }
; DI float sigmoidf_(float x) { return 1.f / (1.f + __expf(-x)); }
; DI void phase_gemm1(const Params& p, int g, char* smem, int bid, int nb) {
;     ...
;     } else if (nt < 64) {
;       const int coff = (nt < 32) ? nt * 128 - 2048 : nt * 128 - 3072;
;       const int mode = (nt < 32) ? 0 : (nt < 48 ? 1 : 2);
; #pragma unroll
;       for (int mi = 0; mi < 2; ++mi)
; #pragma unroll
;         for (int ni = 0; ni < 2; ++ni)
; #pragma unroll
;           for (int r = 0; r < 16; ++r) {
;             float v = acc[mi][ni][r];
;             if (mode == 1) v = v * sigmoidf_(v); else if (mode == 2) v = sigmoidf_(v);
;             projt[(wm * 64 + mi * 32 + crow(r, h)) * NPROJ + coff + wn * 64 + ni * 32 + l31] = f2bf(v);
;           }
	v_fmac_f32_e32 v80, v81, v78
	v_fma_f32 v77, -v77, v80, v79
	v_div_fmas_f32 v77, v77, v78, v80
	v_div_fixup_f32 v52, v77, v76, 1.0
	v_cvt_pk_bf16_f32 v52, v52, v52
	global_store_short v[68:69], v52, off
	v_div_scale_f32 v79, vcc, 1.0, v82, 1.0
	v_fma_f32 v80, -v83, v84, 1.0
	v_fmac_f32_e32 v84, v80, v84
	v_mul_f32_e32 v80, v79, v84
	v_fma_f32 v81, -v83, v80, v79
	v_fmac_f32_e32 v80, v81, v84
	v_fma_f32 v83, -v83, v80, v79
	v_div_fmas_f32 v83, v83, v84, v80
	v_div_fixup_f32 v36, v83, v82, 1.0
	v_cvt_pk_bf16_f32 v36, v36, v36
	global_store_short v[68:69], v36, off offset:64
	v_mul_f32_e32 v76, 0xbfb8aa3b, v53
	v_mul_f32_e32 v82, 0xbfb8aa3b, v37
	v_exp_f32_e32 v76, v76
	v_exp_f32_e32 v82, v82
	v_add_f32_e32 v76, 1.0, v76
	v_add_f32_e32 v82, 1.0, v82
	v_div_scale_f32 v77, s[0:1], v76, v76, 1.0
	v_div_scale_f32 v83, s[0:1], v82, v82, 1.0
	v_rcp_f32_e32 v78, v77
	v_rcp_f32_e32 v84, v83
	v_div_scale_f32 v79, vcc, 1.0, v76, 1.0
	v_fma_f32 v80, -v77, v78, 1.0
	v_fmac_f32_e32 v78, v80, v78
	v_mul_f32_e32 v80, v79, v78
	v_fma_f32 v81, -v77, v80, v79
	v_fmac_f32_e32 v80, v81, v78
	v_fma_f32 v77, -v77, v80, v79
	v_div_fmas_f32 v77, v77, v78, v80
	v_div_fixup_f32 v53, v77, v76, 1.0
	v_cvt_pk_bf16_f32 v53, v53, v53
	global_store_short v[70:71], v53, off
	v_div_scale_f32 v79, vcc, 1.0, v82, 1.0
	v_fma_f32 v80, -v83, v84, 1.0
	v_fmac_f32_e32 v84, v80, v84
	v_mul_f32_e32 v80, v79, v84
	v_fma_f32 v81, -v83, v80, v79
	v_fmac_f32_e32 v80, v81, v84
	v_fma_f32 v83, -v83, v80, v79
	v_div_fmas_f32 v83, v83, v84, v80
	v_div_fixup_f32 v37, v83, v82, 1.0
	v_cvt_pk_bf16_f32 v37, v37, v37
	global_store_short v[70:71], v37, off offset:64
	v_mul_f32_e32 v76, 0xbfb8aa3b, v54
	v_mul_f32_e32 v82, 0xbfb8aa3b, v38
	v_exp_f32_e32 v76, v76
	v_exp_f32_e32 v82, v82
	v_add_f32_e32 v76, 1.0, v76
	v_add_f32_e32 v82, 1.0, v82
	v_div_scale_f32 v77, s[0:1], v76, v76, 1.0
	v_div_scale_f32 v83, s[0:1], v82, v82, 1.0
	v_rcp_f32_e32 v78, v77
	v_rcp_f32_e32 v84, v83
	v_div_scale_f32 v79, vcc, 1.0, v76, 1.0
	v_fma_f32 v80, -v77, v78, 1.0
	v_fmac_f32_e32 v78, v80, v78
	v_mul_f32_e32 v80, v79, v78
	v_fma_f32 v81, -v77, v80, v79
	v_fmac_f32_e32 v80, v81, v78
	v_fma_f32 v77, -v77, v80, v79
	v_div_fmas_f32 v77, v77, v78, v80
	v_div_fixup_f32 v54, v77, v76, 1.0
	v_cvt_pk_bf16_f32 v54, v54, v54
	global_store_short v[72:73], v54, off
	v_div_scale_f32 v79, vcc, 1.0, v82, 1.0
	v_fma_f32 v80, -v83, v84, 1.0
	v_fmac_f32_e32 v84, v80, v84
	v_mul_f32_e32 v80, v79, v84
	v_fma_f32 v81, -v83, v80, v79
	v_fmac_f32_e32 v80, v81, v84
	v_fma_f32 v83, -v83, v80, v79
	v_div_fmas_f32 v83, v83, v84, v80
	v_div_fixup_f32 v38, v83, v82, 1.0
	v_cvt_pk_bf16_f32 v38, v38, v38
	global_store_short v[72:73], v38, off offset:64
	v_mul_f32_e32 v76, 0xbfb8aa3b, v55
	v_mul_f32_e32 v82, 0xbfb8aa3b, v39
	v_exp_f32_e32 v76, v76
	v_exp_f32_e32 v82, v82
	v_add_f32_e32 v76, 1.0, v76
	v_add_f32_e32 v82, 1.0, v82
	v_div_scale_f32 v77, s[0:1], v76, v76, 1.0
	v_div_scale_f32 v83, s[0:1], v82, v82, 1.0
	v_rcp_f32_e32 v78, v77
	v_rcp_f32_e32 v84, v83
	v_div_scale_f32 v79, vcc, 1.0, v76, 1.0
	v_fma_f32 v80, -v77, v78, 1.0
	v_fmac_f32_e32 v78, v80, v78
	v_mul_f32_e32 v80, v79, v78
	v_fma_f32 v81, -v77, v80, v79
	v_fmac_f32_e32 v80, v81, v78
	v_fma_f32 v77, -v77, v80, v79
	v_div_fmas_f32 v77, v77, v78, v80
	v_div_fixup_f32 v55, v77, v76, 1.0
	v_cvt_pk_bf16_f32 v55, v55, v55
	global_store_short v[74:75], v55, off
	v_div_scale_f32 v79, vcc, 1.0, v82, 1.0
	v_fma_f32 v80, -v83, v84, 1.0
	v_fmac_f32_e32 v84, v80, v84
	v_mul_f32_e32 v80, v79, v84
	v_fma_f32 v81, -v83, v80, v79
	v_fmac_f32_e32 v80, v81, v84
	v_fma_f32 v83, -v83, v80, v79
	v_div_fmas_f32 v83, v83, v84, v80
	v_div_fixup_f32 v39, v83, v82, 1.0
	v_cvt_pk_bf16_f32 v39, v39, v39
	global_store_short v[74:75], v39, off offset:64
	s_mov_b64 s[0:1], 0x28000
	v_lshl_add_u64 v[68:69], v[66:67], 0, s[0:1]
	v_lshl_add_u64 v[70:71], v[68:69], 0, s[14:15]
	v_lshl_add_u64 v[72:73], v[70:71], 0, s[14:15]
	v_lshl_add_u64 v[74:75], v[72:73], 0, s[14:15]
	v_mul_f32_e32 v76, 0xbfb8aa3b, v56
	v_mul_f32_e32 v82, 0xbfb8aa3b, v40
	v_exp_f32_e32 v76, v76
	v_exp_f32_e32 v82, v82
	v_add_f32_e32 v76, 1.0, v76
	v_add_f32_e32 v82, 1.0, v82
	v_div_scale_f32 v77, s[0:1], v76, v76, 1.0
	v_div_scale_f32 v83, s[0:1], v82, v82, 1.0
	v_rcp_f32_e32 v78, v77
	v_rcp_f32_e32 v84, v83
	v_div_scale_f32 v79, vcc, 1.0, v76, 1.0
	v_fma_f32 v80, -v77, v78, 1.0
	v_fmac_f32_e32 v78, v80, v78
	v_mul_f32_e32 v80, v79, v78
	v_fma_f32 v81, -v77, v80, v79
	v_fmac_f32_e32 v80, v81, v78
	v_fma_f32 v77, -v77, v80, v79
	v_div_fmas_f32 v77, v77, v78, v80
	v_div_fixup_f32 v56, v77, v76, 1.0
	v_cvt_pk_bf16_f32 v56, v56, v56
	global_store_short v[68:69], v56, off
	v_div_scale_f32 v79, vcc, 1.0, v82, 1.0
	v_fma_f32 v80, -v83, v84, 1.0
	v_fmac_f32_e32 v84, v80, v84
	v_mul_f32_e32 v80, v79, v84
	v_fma_f32 v81, -v83, v80, v79
	v_fmac_f32_e32 v80, v81, v84
	v_fma_f32 v83, -v83, v80, v79
	v_div_fmas_f32 v83, v83, v84, v80
	v_div_fixup_f32 v40, v83, v82, 1.0
	v_cvt_pk_bf16_f32 v40, v40, v40
	global_store_short v[68:69], v40, off offset:64
	v_mul_f32_e32 v76, 0xbfb8aa3b, v57
	v_mul_f32_e32 v82, 0xbfb8aa3b, v41
	v_exp_f32_e32 v76, v76
	v_exp_f32_e32 v82, v82
	v_add_f32_e32 v76, 1.0, v76
	v_add_f32_e32 v82, 1.0, v82
	v_div_scale_f32 v77, s[0:1], v76, v76, 1.0
	v_div_scale_f32 v83, s[0:1], v82, v82, 1.0
	v_rcp_f32_e32 v78, v77
	v_rcp_f32_e32 v84, v83
	v_div_scale_f32 v79, vcc, 1.0, v76, 1.0
	v_fma_f32 v80, -v77, v78, 1.0
	v_fmac_f32_e32 v78, v80, v78
	v_mul_f32_e32 v80, v79, v78
	v_fma_f32 v81, -v77, v80, v79
	v_fmac_f32_e32 v80, v81, v78
	v_fma_f32 v77, -v77, v80, v79
	v_div_fmas_f32 v77, v77, v78, v80
	v_div_fixup_f32 v57, v77, v76, 1.0
; DI bf16_t f2bf(float x) { return (bf16_t)(pk_bf16(x, 0.f) & 0xffffu); }
; DI int crow(int r, int h) { return (r & 3) + 8 * (r >> 2) + 4 * h; }
; DI float sigmoidf_(float x) { return 1.f / (1.f + __expf(-x)); }
; DI void phase_gemm1(const Params& p, int g, char* smem, int bid, int nb) {
;     ...
;     } else if (nt < 64) {
;       const int coff = (nt < 32) ? nt * 128 - 2048 : nt * 128 - 3072;
;       const int mode = (nt < 32) ? 0 : (nt < 48 ? 1 : 2);
; #pragma unroll
;       for (int mi = 0; mi < 2; ++mi)
; #pragma unroll
;         for (int ni = 0; ni < 2; ++ni)
; #pragma unroll
;           for (int r = 0; r < 16; ++r) {
;             float v = acc[mi][ni][r];
;             if (mode == 1) v = v * sigmoidf_(v); else if (mode == 2) v = sigmoidf_(v);
;             projt[(wm * 64 + mi * 32 + crow(r, h)) * NPROJ + coff + wn * 64 + ni * 32 + l31] = f2bf(v);
;           }
	v_cvt_pk_bf16_f32 v57, v57, v57
	global_store_short v[70:71], v57, off
	v_div_scale_f32 v79, vcc, 1.0, v82, 1.0
	v_fma_f32 v80, -v83, v84, 1.0
	v_fmac_f32_e32 v84, v80, v84
	v_mul_f32_e32 v80, v79, v84
	v_fma_f32 v81, -v83, v80, v79
	v_fmac_f32_e32 v80, v81, v84
	v_fma_f32 v83, -v83, v80, v79
	v_div_fmas_f32 v83, v83, v84, v80
	v_div_fixup_f32 v41, v83, v82, 1.0
	v_cvt_pk_bf16_f32 v41, v41, v41
	global_store_short v[70:71], v41, off offset:64
	v_mul_f32_e32 v76, 0xbfb8aa3b, v58
	v_mul_f32_e32 v82, 0xbfb8aa3b, v42
	v_exp_f32_e32 v76, v76
	v_exp_f32_e32 v82, v82
	v_add_f32_e32 v76, 1.0, v76
	v_add_f32_e32 v82, 1.0, v82
	v_div_scale_f32 v77, s[0:1], v76, v76, 1.0
	v_div_scale_f32 v83, s[0:1], v82, v82, 1.0
	v_rcp_f32_e32 v78, v77
	v_rcp_f32_e32 v84, v83
	v_div_scale_f32 v79, vcc, 1.0, v76, 1.0
	v_fma_f32 v80, -v77, v78, 1.0
	v_fmac_f32_e32 v78, v80, v78
	v_mul_f32_e32 v80, v79, v78
	v_fma_f32 v81, -v77, v80, v79
	v_fmac_f32_e32 v80, v81, v78
	v_fma_f32 v77, -v77, v80, v79
	v_div_fmas_f32 v77, v77, v78, v80
	v_div_fixup_f32 v58, v77, v76, 1.0
	v_cvt_pk_bf16_f32 v58, v58, v58
	global_store_short v[72:73], v58, off
	v_div_scale_f32 v79, vcc, 1.0, v82, 1.0
	v_fma_f32 v80, -v83, v84, 1.0
	v_fmac_f32_e32 v84, v80, v84
	v_mul_f32_e32 v80, v79, v84
	v_fma_f32 v81, -v83, v80, v79
	v_fmac_f32_e32 v80, v81, v84
	v_fma_f32 v83, -v83, v80, v79
	v_div_fmas_f32 v83, v83, v84, v80
	v_div_fixup_f32 v42, v83, v82, 1.0
	v_cvt_pk_bf16_f32 v42, v42, v42
	global_store_short v[72:73], v42, off offset:64
	v_mul_f32_e32 v76, 0xbfb8aa3b, v59
	v_mul_f32_e32 v82, 0xbfb8aa3b, v43
	v_exp_f32_e32 v76, v76
	v_exp_f32_e32 v82, v82
	v_add_f32_e32 v76, 1.0, v76
	v_add_f32_e32 v82, 1.0, v82
	v_div_scale_f32 v77, s[0:1], v76, v76, 1.0
	v_div_scale_f32 v83, s[0:1], v82, v82, 1.0
	v_rcp_f32_e32 v78, v77
	v_rcp_f32_e32 v84, v83
	v_div_scale_f32 v79, vcc, 1.0, v76, 1.0
	v_fma_f32 v80, -v77, v78, 1.0
	v_fmac_f32_e32 v78, v80, v78
	v_mul_f32_e32 v80, v79, v78
	v_fma_f32 v81, -v77, v80, v79
	v_fmac_f32_e32 v80, v81, v78
	v_fma_f32 v77, -v77, v80, v79
	v_div_fmas_f32 v77, v77, v78, v80
	v_div_fixup_f32 v59, v77, v76, 1.0
	v_cvt_pk_bf16_f32 v59, v59, v59
	global_store_short v[74:75], v59, off
	v_div_scale_f32 v79, vcc, 1.0, v82, 1.0
	v_fma_f32 v80, -v83, v84, 1.0
	v_fmac_f32_e32 v84, v80, v84
	v_mul_f32_e32 v80, v79, v84
	v_fma_f32 v81, -v83, v80, v79
	v_fmac_f32_e32 v80, v81, v84
	v_fma_f32 v83, -v83, v80, v79
	v_div_fmas_f32 v83, v83, v84, v80
	v_div_fixup_f32 v43, v83, v82, 1.0
	v_cvt_pk_bf16_f32 v43, v43, v43
	global_store_short v[74:75], v43, off offset:64
	s_mov_b64 s[0:1], 0x3c000
	v_lshl_add_u64 v[68:69], v[66:67], 0, s[0:1]
	v_lshl_add_u64 v[70:71], v[68:69], 0, s[14:15]
	v_lshl_add_u64 v[72:73], v[70:71], 0, s[14:15]
	v_lshl_add_u64 v[74:75], v[72:73], 0, s[14:15]
	v_mul_f32_e32 v76, 0xbfb8aa3b, v60
	v_mul_f32_e32 v82, 0xbfb8aa3b, v44
	v_exp_f32_e32 v76, v76
	v_exp_f32_e32 v82, v82
	v_add_f32_e32 v76, 1.0, v76
	v_add_f32_e32 v82, 1.0, v82
	v_div_scale_f32 v77, s[0:1], v76, v76, 1.0
	v_div_scale_f32 v83, s[0:1], v82, v82, 1.0
	v_rcp_f32_e32 v78, v77
	v_rcp_f32_e32 v84, v83
	v_div_scale_f32 v79, vcc, 1.0, v76, 1.0
	v_fma_f32 v80, -v77, v78, 1.0
	v_fmac_f32_e32 v78, v80, v78
	v_mul_f32_e32 v80, v79, v78
	v_fma_f32 v81, -v77, v80, v79
	v_fmac_f32_e32 v80, v81, v78
	v_fma_f32 v77, -v77, v80, v79
	v_div_fmas_f32 v77, v77, v78, v80
	v_div_fixup_f32 v60, v77, v76, 1.0
	v_cvt_pk_bf16_f32 v60, v60, v60
	global_store_short v[68:69], v60, off
	v_div_scale_f32 v79, vcc, 1.0, v82, 1.0
	v_fma_f32 v80, -v83, v84, 1.0
	v_fmac_f32_e32 v84, v80, v84
	v_mul_f32_e32 v80, v79, v84
	v_fma_f32 v81, -v83, v80, v79
	v_fmac_f32_e32 v80, v81, v84
	v_fma_f32 v83, -v83, v80, v79
	v_div_fmas_f32 v83, v83, v84, v80
	v_div_fixup_f32 v44, v83, v82, 1.0
	v_cvt_pk_bf16_f32 v44, v44, v44
	global_store_short v[68:69], v44, off offset:64
	v_mul_f32_e32 v76, 0xbfb8aa3b, v61
	v_mul_f32_e32 v82, 0xbfb8aa3b, v45
	v_exp_f32_e32 v76, v76
	v_exp_f32_e32 v82, v82
	v_add_f32_e32 v76, 1.0, v76
	v_add_f32_e32 v82, 1.0, v82
	v_div_scale_f32 v77, s[0:1], v76, v76, 1.0
	v_div_scale_f32 v83, s[0:1], v82, v82, 1.0
	v_rcp_f32_e32 v78, v77
	v_rcp_f32_e32 v84, v83
	v_div_scale_f32 v79, vcc, 1.0, v76, 1.0
	v_fma_f32 v80, -v77, v78, 1.0
	v_fmac_f32_e32 v78, v80, v78
	v_mul_f32_e32 v80, v79, v78
	v_fma_f32 v81, -v77, v80, v79
	v_fmac_f32_e32 v80, v81, v78
	v_fma_f32 v77, -v77, v80, v79
	v_div_fmas_f32 v77, v77, v78, v80
	v_div_fixup_f32 v61, v77, v76, 1.0
	v_cvt_pk_bf16_f32 v61, v61, v61
	global_store_short v[70:71], v61, off
	v_div_scale_f32 v79, vcc, 1.0, v82, 1.0
	v_fma_f32 v80, -v83, v84, 1.0
	v_fmac_f32_e32 v84, v80, v84
	v_mul_f32_e32 v80, v79, v84
	v_fma_f32 v81, -v83, v80, v79
	v_fmac_f32_e32 v80, v81, v84
	v_fma_f32 v83, -v83, v80, v79
	v_div_fmas_f32 v83, v83, v84, v80
	v_div_fixup_f32 v45, v83, v82, 1.0
	v_cvt_pk_bf16_f32 v45, v45, v45
	global_store_short v[70:71], v45, off offset:64
	v_mul_f32_e32 v76, 0xbfb8aa3b, v62
	v_mul_f32_e32 v82, 0xbfb8aa3b, v46
	v_exp_f32_e32 v76, v76
	v_exp_f32_e32 v82, v82
	v_add_f32_e32 v76, 1.0, v76
	v_add_f32_e32 v82, 1.0, v82
	v_div_scale_f32 v77, s[0:1], v76, v76, 1.0
	v_div_scale_f32 v83, s[0:1], v82, v82, 1.0
	v_rcp_f32_e32 v78, v77
	v_rcp_f32_e32 v84, v83
	v_div_scale_f32 v79, vcc, 1.0, v76, 1.0
	v_fma_f32 v80, -v77, v78, 1.0
	v_fmac_f32_e32 v78, v80, v78
	v_mul_f32_e32 v80, v79, v78
	v_fma_f32 v81, -v77, v80, v79
	v_fmac_f32_e32 v80, v81, v78
	v_fma_f32 v77, -v77, v80, v79
	v_div_fmas_f32 v77, v77, v78, v80
	v_div_fixup_f32 v62, v77, v76, 1.0
	v_cvt_pk_bf16_f32 v62, v62, v62
	global_store_short v[72:73], v62, off
	v_div_scale_f32 v79, vcc, 1.0, v82, 1.0
	v_fma_f32 v80, -v83, v84, 1.0
; DI bf16_t f2bf(float x) { return (bf16_t)(pk_bf16(x, 0.f) & 0xffffu); }
; DI int crow(int r, int h) { return (r & 3) + 8 * (r >> 2) + 4 * h; }
; DI float sigmoidf_(float x) { return 1.f / (1.f + __expf(-x)); }
; DI void phase_gemm1(const Params& p, int g, char* smem, int bid, int nb) {
;     ...
;     } else if (nt < 64) {
;       const int coff = (nt < 32) ? nt * 128 - 2048 : nt * 128 - 3072;
;       const int mode = (nt < 32) ? 0 : (nt < 48 ? 1 : 2);
; #pragma unroll
;       for (int mi = 0; mi < 2; ++mi)
; #pragma unroll
;         for (int ni = 0; ni < 2; ++ni)
; #pragma unroll
;           for (int r = 0; r < 16; ++r) {
;             float v = acc[mi][ni][r];
;             if (mode == 1) v = v * sigmoidf_(v); else if (mode == 2) v = sigmoidf_(v);
;             projt[(wm * 64 + mi * 32 + crow(r, h)) * NPROJ + coff + wn * 64 + ni * 32 + l31] = f2bf(v);
;           }
	v_fmac_f32_e32 v84, v80, v84
	v_mul_f32_e32 v80, v79, v84
	v_fma_f32 v81, -v83, v80, v79
	v_fmac_f32_e32 v80, v81, v84
	v_fma_f32 v83, -v83, v80, v79
	v_div_fmas_f32 v83, v83, v84, v80
	v_div_fixup_f32 v46, v83, v82, 1.0
	v_cvt_pk_bf16_f32 v46, v46, v46
	global_store_short v[72:73], v46, off offset:64
	v_mul_f32_e32 v76, 0xbfb8aa3b, v63
	v_mul_f32_e32 v82, 0xbfb8aa3b, v47
	v_exp_f32_e32 v76, v76
	v_exp_f32_e32 v82, v82
	v_add_f32_e32 v76, 1.0, v76
	v_add_f32_e32 v82, 1.0, v82
	v_div_scale_f32 v77, s[0:1], v76, v76, 1.0
	v_div_scale_f32 v83, s[0:1], v82, v82, 1.0
	v_rcp_f32_e32 v78, v77
	v_rcp_f32_e32 v84, v83
	v_div_scale_f32 v79, vcc, 1.0, v76, 1.0
	v_fma_f32 v80, -v77, v78, 1.0
	v_fmac_f32_e32 v78, v80, v78
	v_mul_f32_e32 v80, v79, v78
	v_fma_f32 v81, -v77, v80, v79
	v_fmac_f32_e32 v80, v81, v78
	v_fma_f32 v77, -v77, v80, v79
	v_div_fmas_f32 v77, v77, v78, v80
	v_div_fixup_f32 v63, v77, v76, 1.0
	v_cvt_pk_bf16_f32 v63, v63, v63
	global_store_short v[74:75], v63, off
	v_div_scale_f32 v79, vcc, 1.0, v82, 1.0
	v_fma_f32 v80, -v83, v84, 1.0
	v_fmac_f32_e32 v84, v80, v84
	v_mul_f32_e32 v80, v79, v84
	v_fma_f32 v81, -v83, v80, v79
	v_fmac_f32_e32 v80, v81, v84
	v_fma_f32 v83, -v83, v80, v79
	v_div_fmas_f32 v83, v83, v84, v80
	v_div_fixup_f32 v47, v83, v82, 1.0
	v_cvt_pk_bf16_f32 v47, v47, v47
	global_store_short v[74:75], v47, off offset:64
	s_mov_b64 s[0:1], 0x50000
	v_lshl_add_u64 v[68:69], v[66:67], 0, s[0:1]
	v_lshl_add_u64 v[70:71], v[68:69], 0, s[14:15]
	v_lshl_add_u64 v[72:73], v[70:71], 0, s[14:15]
	v_lshl_add_u64 v[74:75], v[72:73], 0, s[14:15]
	v_mul_f32_e32 v76, 0xbfb8aa3b, v0
	v_mul_f32_e32 v82, 0xbfb8aa3b, v16
	v_exp_f32_e32 v76, v76
	v_exp_f32_e32 v82, v82
	v_add_f32_e32 v76, 1.0, v76
	v_add_f32_e32 v82, 1.0, v82
	v_div_scale_f32 v77, s[0:1], v76, v76, 1.0
	v_div_scale_f32 v83, s[0:1], v82, v82, 1.0
	v_rcp_f32_e32 v78, v77
	v_rcp_f32_e32 v84, v83
	v_div_scale_f32 v79, vcc, 1.0, v76, 1.0
	v_fma_f32 v80, -v77, v78, 1.0
	v_fmac_f32_e32 v78, v80, v78
	v_mul_f32_e32 v80, v79, v78
	v_fma_f32 v81, -v77, v80, v79
	v_fmac_f32_e32 v80, v81, v78
	v_fma_f32 v77, -v77, v80, v79
	v_div_fmas_f32 v77, v77, v78, v80
	v_div_fixup_f32 v0, v77, v76, 1.0
	v_cvt_pk_bf16_f32 v0, v0, v0
	global_store_short v[68:69], v0, off
	v_div_scale_f32 v79, vcc, 1.0, v82, 1.0
	v_fma_f32 v80, -v83, v84, 1.0
	v_fmac_f32_e32 v84, v80, v84
	v_mul_f32_e32 v80, v79, v84
	v_fma_f32 v81, -v83, v80, v79
	v_fmac_f32_e32 v80, v81, v84
	v_fma_f32 v83, -v83, v80, v79
	v_div_fmas_f32 v83, v83, v84, v80
	v_div_fixup_f32 v16, v83, v82, 1.0
	v_cvt_pk_bf16_f32 v16, v16, v16
	global_store_short v[68:69], v16, off offset:64
	v_mul_f32_e32 v76, 0xbfb8aa3b, v1
	v_mul_f32_e32 v82, 0xbfb8aa3b, v17
	v_exp_f32_e32 v76, v76
	v_exp_f32_e32 v82, v82
	v_add_f32_e32 v76, 1.0, v76
	v_add_f32_e32 v82, 1.0, v82
	v_div_scale_f32 v77, s[0:1], v76, v76, 1.0
	v_div_scale_f32 v83, s[0:1], v82, v82, 1.0
	v_rcp_f32_e32 v78, v77
	v_rcp_f32_e32 v84, v83
	v_div_scale_f32 v79, vcc, 1.0, v76, 1.0
	v_fma_f32 v80, -v77, v78, 1.0
	v_fmac_f32_e32 v78, v80, v78
	v_mul_f32_e32 v80, v79, v78
	v_fma_f32 v81, -v77, v80, v79
	v_fmac_f32_e32 v80, v81, v78
	v_fma_f32 v77, -v77, v80, v79
	v_div_fmas_f32 v77, v77, v78, v80
	v_div_fixup_f32 v1, v77, v76, 1.0
	v_cvt_pk_bf16_f32 v1, v1, v1
	global_store_short v[70:71], v1, off
	v_div_scale_f32 v79, vcc, 1.0, v82, 1.0
	v_fma_f32 v80, -v83, v84, 1.0
	v_fmac_f32_e32 v84, v80, v84
	v_mul_f32_e32 v80, v79, v84
	v_fma_f32 v81, -v83, v80, v79
	v_fmac_f32_e32 v80, v81, v84
	v_fma_f32 v83, -v83, v80, v79
	v_div_fmas_f32 v83, v83, v84, v80
	v_div_fixup_f32 v17, v83, v82, 1.0
	v_cvt_pk_bf16_f32 v17, v17, v17
	global_store_short v[70:71], v17, off offset:64
	v_mul_f32_e32 v76, 0xbfb8aa3b, v2
	v_mul_f32_e32 v82, 0xbfb8aa3b, v18
	v_exp_f32_e32 v76, v76
	v_exp_f32_e32 v82, v82
	v_add_f32_e32 v76, 1.0, v76
	v_add_f32_e32 v82, 1.0, v82
	v_div_scale_f32 v77, s[0:1], v76, v76, 1.0
	v_div_scale_f32 v83, s[0:1], v82, v82, 1.0
	v_rcp_f32_e32 v78, v77
	v_rcp_f32_e32 v84, v83
	v_div_scale_f32 v79, vcc, 1.0, v76, 1.0
	v_fma_f32 v80, -v77, v78, 1.0
	v_fmac_f32_e32 v78, v80, v78
	v_mul_f32_e32 v80, v79, v78
	v_fma_f32 v81, -v77, v80, v79
	v_fmac_f32_e32 v80, v81, v78
	v_fma_f32 v77, -v77, v80, v79
	v_div_fmas_f32 v77, v77, v78, v80
	v_div_fixup_f32 v2, v77, v76, 1.0
	v_cvt_pk_bf16_f32 v2, v2, v2
	global_store_short v[72:73], v2, off
	v_div_scale_f32 v79, vcc, 1.0, v82, 1.0
	v_fma_f32 v80, -v83, v84, 1.0
	v_fmac_f32_e32 v84, v80, v84
	v_mul_f32_e32 v80, v79, v84
	v_fma_f32 v81, -v83, v80, v79
	v_fmac_f32_e32 v80, v81, v84
	v_fma_f32 v83, -v83, v80, v79
	v_div_fmas_f32 v83, v83, v84, v80
	v_div_fixup_f32 v18, v83, v82, 1.0
	v_cvt_pk_bf16_f32 v18, v18, v18
	global_store_short v[72:73], v18, off offset:64
	v_mul_f32_e32 v76, 0xbfb8aa3b, v3
	v_mul_f32_e32 v82, 0xbfb8aa3b, v19
	v_exp_f32_e32 v76, v76
	v_exp_f32_e32 v82, v82
	v_add_f32_e32 v76, 1.0, v76
	v_add_f32_e32 v82, 1.0, v82
	v_div_scale_f32 v77, s[0:1], v76, v76, 1.0
	v_div_scale_f32 v83, s[0:1], v82, v82, 1.0
	v_rcp_f32_e32 v78, v77
	v_rcp_f32_e32 v84, v83
	v_div_scale_f32 v79, vcc, 1.0, v76, 1.0
	v_fma_f32 v80, -v77, v78, 1.0
	v_fmac_f32_e32 v78, v80, v78
	v_mul_f32_e32 v80, v79, v78
	v_fma_f32 v81, -v77, v80, v79
	v_fmac_f32_e32 v80, v81, v78
	v_fma_f32 v77, -v77, v80, v79
	v_div_fmas_f32 v77, v77, v78, v80
	v_div_fixup_f32 v3, v77, v76, 1.0
	v_cvt_pk_bf16_f32 v3, v3, v3
	global_store_short v[74:75], v3, off
	v_div_scale_f32 v79, vcc, 1.0, v82, 1.0
	v_fma_f32 v80, -v83, v84, 1.0
	v_fmac_f32_e32 v84, v80, v84
	v_mul_f32_e32 v80, v79, v84
	v_fma_f32 v81, -v83, v80, v79
	v_fmac_f32_e32 v80, v81, v84
	v_fma_f32 v83, -v83, v80, v79
; DI bf16_t f2bf(float x) { return (bf16_t)(pk_bf16(x, 0.f) & 0xffffu); }
; DI int crow(int r, int h) { return (r & 3) + 8 * (r >> 2) + 4 * h; }
; DI float sigmoidf_(float x) { return 1.f / (1.f + __expf(-x)); }
; DI void phase_gemm1(const Params& p, int g, char* smem, int bid, int nb) {
;     ...
;     } else if (nt < 64) {
;       const int coff = (nt < 32) ? nt * 128 - 2048 : nt * 128 - 3072;
;       const int mode = (nt < 32) ? 0 : (nt < 48 ? 1 : 2);
; #pragma unroll
;       for (int mi = 0; mi < 2; ++mi)
; #pragma unroll
;         for (int ni = 0; ni < 2; ++ni)
; #pragma unroll
;           for (int r = 0; r < 16; ++r) {
;             float v = acc[mi][ni][r];
;             if (mode == 1) v = v * sigmoidf_(v); else if (mode == 2) v = sigmoidf_(v);
;             projt[(wm * 64 + mi * 32 + crow(r, h)) * NPROJ + coff + wn * 64 + ni * 32 + l31] = f2bf(v);
;           }
	v_div_fmas_f32 v83, v83, v84, v80
	v_div_fixup_f32 v19, v83, v82, 1.0
	v_cvt_pk_bf16_f32 v19, v19, v19
	global_store_short v[74:75], v19, off offset:64
	s_mov_b64 s[0:1], 0x64000
	v_lshl_add_u64 v[68:69], v[66:67], 0, s[0:1]
	v_lshl_add_u64 v[70:71], v[68:69], 0, s[14:15]
	v_lshl_add_u64 v[72:73], v[70:71], 0, s[14:15]
	v_lshl_add_u64 v[74:75], v[72:73], 0, s[14:15]
	v_mul_f32_e32 v76, 0xbfb8aa3b, v4
	v_mul_f32_e32 v82, 0xbfb8aa3b, v20
	v_exp_f32_e32 v76, v76
	v_exp_f32_e32 v82, v82
	v_add_f32_e32 v76, 1.0, v76
	v_add_f32_e32 v82, 1.0, v82
	v_div_scale_f32 v77, s[0:1], v76, v76, 1.0
	v_div_scale_f32 v83, s[0:1], v82, v82, 1.0
	v_rcp_f32_e32 v78, v77
	v_rcp_f32_e32 v84, v83
	v_div_scale_f32 v79, vcc, 1.0, v76, 1.0
	v_fma_f32 v80, -v77, v78, 1.0
	v_fmac_f32_e32 v78, v80, v78
	v_mul_f32_e32 v80, v79, v78
	v_fma_f32 v81, -v77, v80, v79
	v_fmac_f32_e32 v80, v81, v78
	v_fma_f32 v77, -v77, v80, v79
	v_div_fmas_f32 v77, v77, v78, v80
	v_div_fixup_f32 v4, v77, v76, 1.0
	v_cvt_pk_bf16_f32 v4, v4, v4
	global_store_short v[68:69], v4, off
	v_div_scale_f32 v79, vcc, 1.0, v82, 1.0
	v_fma_f32 v80, -v83, v84, 1.0
	v_fmac_f32_e32 v84, v80, v84
	v_mul_f32_e32 v80, v79, v84
	v_fma_f32 v81, -v83, v80, v79
	v_fmac_f32_e32 v80, v81, v84
	v_fma_f32 v83, -v83, v80, v79
	v_div_fmas_f32 v83, v83, v84, v80
	v_div_fixup_f32 v20, v83, v82, 1.0
	v_cvt_pk_bf16_f32 v20, v20, v20
	global_store_short v[68:69], v20, off offset:64
	v_mul_f32_e32 v76, 0xbfb8aa3b, v5
	v_mul_f32_e32 v82, 0xbfb8aa3b, v21
	v_exp_f32_e32 v76, v76
	v_exp_f32_e32 v82, v82
	v_add_f32_e32 v76, 1.0, v76
	v_add_f32_e32 v82, 1.0, v82
	v_div_scale_f32 v77, s[0:1], v76, v76, 1.0
	v_div_scale_f32 v83, s[0:1], v82, v82, 1.0
	v_rcp_f32_e32 v78, v77
	v_rcp_f32_e32 v84, v83
	v_div_scale_f32 v79, vcc, 1.0, v76, 1.0
	v_fma_f32 v80, -v77, v78, 1.0
	v_fmac_f32_e32 v78, v80, v78
	v_mul_f32_e32 v80, v79, v78
	v_fma_f32 v81, -v77, v80, v79
	v_fmac_f32_e32 v80, v81, v78
	v_fma_f32 v77, -v77, v80, v79
	v_div_fmas_f32 v77, v77, v78, v80
	v_div_fixup_f32 v5, v77, v76, 1.0
	v_cvt_pk_bf16_f32 v5, v5, v5
	global_store_short v[70:71], v5, off
	v_div_scale_f32 v79, vcc, 1.0, v82, 1.0
	v_fma_f32 v80, -v83, v84, 1.0
	v_fmac_f32_e32 v84, v80, v84
	v_mul_f32_e32 v80, v79, v84
	v_fma_f32 v81, -v83, v80, v79
	v_fmac_f32_e32 v80, v81, v84
	v_fma_f32 v83, -v83, v80, v79
	v_div_fmas_f32 v83, v83, v84, v80
	v_div_fixup_f32 v21, v83, v82, 1.0
	v_cvt_pk_bf16_f32 v21, v21, v21
	global_store_short v[70:71], v21, off offset:64
	v_mul_f32_e32 v76, 0xbfb8aa3b, v6
	v_mul_f32_e32 v82, 0xbfb8aa3b, v22
	v_exp_f32_e32 v76, v76
	v_exp_f32_e32 v82, v82
	v_add_f32_e32 v76, 1.0, v76
	v_add_f32_e32 v82, 1.0, v82
	v_div_scale_f32 v77, s[0:1], v76, v76, 1.0
	v_div_scale_f32 v83, s[0:1], v82, v82, 1.0
	v_rcp_f32_e32 v78, v77
	v_rcp_f32_e32 v84, v83
	v_div_scale_f32 v79, vcc, 1.0, v76, 1.0
	v_fma_f32 v80, -v77, v78, 1.0
	v_fmac_f32_e32 v78, v80, v78
	v_mul_f32_e32 v80, v79, v78
	v_fma_f32 v81, -v77, v80, v79
	v_fmac_f32_e32 v80, v81, v78
	v_fma_f32 v77, -v77, v80, v79
	v_div_fmas_f32 v77, v77, v78, v80
	v_div_fixup_f32 v6, v77, v76, 1.0
	v_cvt_pk_bf16_f32 v6, v6, v6
	global_store_short v[72:73], v6, off
	v_div_scale_f32 v79, vcc, 1.0, v82, 1.0
	v_fma_f32 v80, -v83, v84, 1.0
	v_fmac_f32_e32 v84, v80, v84
	v_mul_f32_e32 v80, v79, v84
	v_fma_f32 v81, -v83, v80, v79
	v_fmac_f32_e32 v80, v81, v84
	v_fma_f32 v83, -v83, v80, v79
	v_div_fmas_f32 v83, v83, v84, v80
	v_div_fixup_f32 v22, v83, v82, 1.0
	v_cvt_pk_bf16_f32 v22, v22, v22
	global_store_short v[72:73], v22, off offset:64
	v_mul_f32_e32 v76, 0xbfb8aa3b, v7
	v_mul_f32_e32 v82, 0xbfb8aa3b, v23
	v_exp_f32_e32 v76, v76
	v_exp_f32_e32 v82, v82
	v_add_f32_e32 v76, 1.0, v76
	v_add_f32_e32 v82, 1.0, v82
	v_div_scale_f32 v77, s[0:1], v76, v76, 1.0
	v_div_scale_f32 v83, s[0:1], v82, v82, 1.0
	v_rcp_f32_e32 v78, v77
	v_rcp_f32_e32 v84, v83
	v_div_scale_f32 v79, vcc, 1.0, v76, 1.0
	v_fma_f32 v80, -v77, v78, 1.0
	v_fmac_f32_e32 v78, v80, v78
	v_mul_f32_e32 v80, v79, v78
	v_fma_f32 v81, -v77, v80, v79
	v_fmac_f32_e32 v80, v81, v78
	v_fma_f32 v77, -v77, v80, v79
	v_div_fmas_f32 v77, v77, v78, v80
	v_div_fixup_f32 v7, v77, v76, 1.0
	v_cvt_pk_bf16_f32 v7, v7, v7
	global_store_short v[74:75], v7, off
	v_div_scale_f32 v79, vcc, 1.0, v82, 1.0
	v_fma_f32 v80, -v83, v84, 1.0
	v_fmac_f32_e32 v84, v80, v84
	v_mul_f32_e32 v80, v79, v84
	v_fma_f32 v81, -v83, v80, v79
	v_fmac_f32_e32 v80, v81, v84
	v_fma_f32 v83, -v83, v80, v79
	v_div_fmas_f32 v83, v83, v84, v80
	v_div_fixup_f32 v23, v83, v82, 1.0
	v_cvt_pk_bf16_f32 v23, v23, v23
	global_store_short v[74:75], v23, off offset:64
	s_mov_b64 s[0:1], 0x78000
	v_lshl_add_u64 v[68:69], v[66:67], 0, s[0:1]
	v_lshl_add_u64 v[70:71], v[68:69], 0, s[14:15]
	v_lshl_add_u64 v[72:73], v[70:71], 0, s[14:15]
	v_lshl_add_u64 v[74:75], v[72:73], 0, s[14:15]
	v_mul_f32_e32 v76, 0xbfb8aa3b, v8
	v_mul_f32_e32 v82, 0xbfb8aa3b, v24
	v_exp_f32_e32 v76, v76
	v_exp_f32_e32 v82, v82
	v_add_f32_e32 v76, 1.0, v76
	v_add_f32_e32 v82, 1.0, v82
	v_div_scale_f32 v77, s[0:1], v76, v76, 1.0
	v_div_scale_f32 v83, s[0:1], v82, v82, 1.0
	v_rcp_f32_e32 v78, v77
	v_rcp_f32_e32 v84, v83
	v_div_scale_f32 v79, vcc, 1.0, v76, 1.0
	v_fma_f32 v80, -v77, v78, 1.0
	v_fmac_f32_e32 v78, v80, v78
	v_mul_f32_e32 v80, v79, v78
	v_fma_f32 v81, -v77, v80, v79
	v_fmac_f32_e32 v80, v81, v78
	v_fma_f32 v77, -v77, v80, v79
	v_div_fmas_f32 v77, v77, v78, v80
	v_div_fixup_f32 v8, v77, v76, 1.0
	v_cvt_pk_bf16_f32 v8, v8, v8
	global_store_short v[68:69], v8, off
	v_div_scale_f32 v79, vcc, 1.0, v82, 1.0
	v_fma_f32 v80, -v83, v84, 1.0
	v_fmac_f32_e32 v84, v80, v84
	v_mul_f32_e32 v80, v79, v84
	v_fma_f32 v81, -v83, v80, v79
	v_fmac_f32_e32 v80, v81, v84
; DI bf16_t f2bf(float x) { return (bf16_t)(pk_bf16(x, 0.f) & 0xffffu); }
; DI int crow(int r, int h) { return (r & 3) + 8 * (r >> 2) + 4 * h; }
; DI float sigmoidf_(float x) { return 1.f / (1.f + __expf(-x)); }
; DI void phase_gemm1(const Params& p, int g, char* smem, int bid, int nb) {
;     ...
;     } else if (nt < 64) {
;       const int coff = (nt < 32) ? nt * 128 - 2048 : nt * 128 - 3072;
;       const int mode = (nt < 32) ? 0 : (nt < 48 ? 1 : 2);
; #pragma unroll
;       for (int mi = 0; mi < 2; ++mi)
; #pragma unroll
;         for (int ni = 0; ni < 2; ++ni)
; #pragma unroll
;           for (int r = 0; r < 16; ++r) {
;             float v = acc[mi][ni][r];
;             if (mode == 1) v = v * sigmoidf_(v); else if (mode == 2) v = sigmoidf_(v);
;             projt[(wm * 64 + mi * 32 + crow(r, h)) * NPROJ + coff + wn * 64 + ni * 32 + l31] = f2bf(v);
;           }
	v_fma_f32 v83, -v83, v80, v79
	v_div_fmas_f32 v83, v83, v84, v80
	v_div_fixup_f32 v24, v83, v82, 1.0
	v_cvt_pk_bf16_f32 v24, v24, v24
	global_store_short v[68:69], v24, off offset:64
	v_mul_f32_e32 v76, 0xbfb8aa3b, v9
	v_mul_f32_e32 v82, 0xbfb8aa3b, v25
	v_exp_f32_e32 v76, v76
	v_exp_f32_e32 v82, v82
	v_add_f32_e32 v76, 1.0, v76
	v_add_f32_e32 v82, 1.0, v82
	v_div_scale_f32 v77, s[0:1], v76, v76, 1.0
	v_div_scale_f32 v83, s[0:1], v82, v82, 1.0
	v_rcp_f32_e32 v78, v77
	v_rcp_f32_e32 v84, v83
	v_div_scale_f32 v79, vcc, 1.0, v76, 1.0
	v_fma_f32 v80, -v77, v78, 1.0
	v_fmac_f32_e32 v78, v80, v78
	v_mul_f32_e32 v80, v79, v78
	v_fma_f32 v81, -v77, v80, v79
	v_fmac_f32_e32 v80, v81, v78
	v_fma_f32 v77, -v77, v80, v79
	v_div_fmas_f32 v77, v77, v78, v80
	v_div_fixup_f32 v9, v77, v76, 1.0
	v_cvt_pk_bf16_f32 v9, v9, v9
	global_store_short v[70:71], v9, off
	v_div_scale_f32 v79, vcc, 1.0, v82, 1.0
	v_fma_f32 v80, -v83, v84, 1.0
	v_fmac_f32_e32 v84, v80, v84
	v_mul_f32_e32 v80, v79, v84
	v_fma_f32 v81, -v83, v80, v79
	v_fmac_f32_e32 v80, v81, v84
	v_fma_f32 v83, -v83, v80, v79
	v_div_fmas_f32 v83, v83, v84, v80
	v_div_fixup_f32 v25, v83, v82, 1.0
	v_cvt_pk_bf16_f32 v25, v25, v25
	global_store_short v[70:71], v25, off offset:64
	v_mul_f32_e32 v76, 0xbfb8aa3b, v10
	v_mul_f32_e32 v82, 0xbfb8aa3b, v26
	v_exp_f32_e32 v76, v76
	v_exp_f32_e32 v82, v82
	v_add_f32_e32 v76, 1.0, v76
	v_add_f32_e32 v82, 1.0, v82
	v_div_scale_f32 v77, s[0:1], v76, v76, 1.0
	v_div_scale_f32 v83, s[0:1], v82, v82, 1.0
	v_rcp_f32_e32 v78, v77
	v_rcp_f32_e32 v84, v83
	v_div_scale_f32 v79, vcc, 1.0, v76, 1.0
	v_fma_f32 v80, -v77, v78, 1.0
	v_fmac_f32_e32 v78, v80, v78
	v_mul_f32_e32 v80, v79, v78
	v_fma_f32 v81, -v77, v80, v79
	v_fmac_f32_e32 v80, v81, v78
	v_fma_f32 v77, -v77, v80, v79
	v_div_fmas_f32 v77, v77, v78, v80
	v_div_fixup_f32 v10, v77, v76, 1.0
	v_cvt_pk_bf16_f32 v10, v10, v10
	global_store_short v[72:73], v10, off
	v_div_scale_f32 v79, vcc, 1.0, v82, 1.0
	v_fma_f32 v80, -v83, v84, 1.0
	v_fmac_f32_e32 v84, v80, v84
	v_mul_f32_e32 v80, v79, v84
	v_fma_f32 v81, -v83, v80, v79
	v_fmac_f32_e32 v80, v81, v84
	v_fma_f32 v83, -v83, v80, v79
	v_div_fmas_f32 v83, v83, v84, v80
	v_div_fixup_f32 v26, v83, v82, 1.0
	v_cvt_pk_bf16_f32 v26, v26, v26
	global_store_short v[72:73], v26, off offset:64
	v_mul_f32_e32 v76, 0xbfb8aa3b, v11
	v_mul_f32_e32 v82, 0xbfb8aa3b, v27
	v_exp_f32_e32 v76, v76
	v_exp_f32_e32 v82, v82
	v_add_f32_e32 v76, 1.0, v76
	v_add_f32_e32 v82, 1.0, v82
	v_div_scale_f32 v77, s[0:1], v76, v76, 1.0
	v_div_scale_f32 v83, s[0:1], v82, v82, 1.0
	v_rcp_f32_e32 v78, v77
	v_rcp_f32_e32 v84, v83
	v_div_scale_f32 v79, vcc, 1.0, v76, 1.0
	v_fma_f32 v80, -v77, v78, 1.0
	v_fmac_f32_e32 v78, v80, v78
	v_mul_f32_e32 v80, v79, v78
	v_fma_f32 v81, -v77, v80, v79
	v_fmac_f32_e32 v80, v81, v78
	v_fma_f32 v77, -v77, v80, v79
	v_div_fmas_f32 v77, v77, v78, v80
	v_div_fixup_f32 v11, v77, v76, 1.0
	v_cvt_pk_bf16_f32 v11, v11, v11
	global_store_short v[74:75], v11, off
	v_div_scale_f32 v79, vcc, 1.0, v82, 1.0
	v_fma_f32 v80, -v83, v84, 1.0
	v_fmac_f32_e32 v84, v80, v84
	v_mul_f32_e32 v80, v79, v84
	v_fma_f32 v81, -v83, v80, v79
	v_fmac_f32_e32 v80, v81, v84
	v_fma_f32 v83, -v83, v80, v79
	v_div_fmas_f32 v83, v83, v84, v80
	v_div_fixup_f32 v27, v83, v82, 1.0
	v_cvt_pk_bf16_f32 v27, v27, v27
	global_store_short v[74:75], v27, off offset:64
	s_mov_b64 s[0:1], 0x8c000
	v_lshl_add_u64 v[68:69], v[66:67], 0, s[0:1]
	v_lshl_add_u64 v[70:71], v[68:69], 0, s[14:15]
	v_lshl_add_u64 v[72:73], v[70:71], 0, s[14:15]
	v_lshl_add_u64 v[74:75], v[72:73], 0, s[14:15]
	v_mul_f32_e32 v76, 0xbfb8aa3b, v12
	v_mul_f32_e32 v82, 0xbfb8aa3b, v28
	v_exp_f32_e32 v76, v76
	v_exp_f32_e32 v82, v82
	v_add_f32_e32 v76, 1.0, v76
	v_add_f32_e32 v82, 1.0, v82
	v_div_scale_f32 v77, s[0:1], v76, v76, 1.0
	v_div_scale_f32 v83, s[0:1], v82, v82, 1.0
	v_rcp_f32_e32 v78, v77
	v_rcp_f32_e32 v84, v83
	v_div_scale_f32 v79, vcc, 1.0, v76, 1.0
	v_fma_f32 v80, -v77, v78, 1.0
	v_fmac_f32_e32 v78, v80, v78
	v_mul_f32_e32 v80, v79, v78
	v_fma_f32 v81, -v77, v80, v79
	v_fmac_f32_e32 v80, v81, v78
	v_fma_f32 v77, -v77, v80, v79
	v_div_fmas_f32 v77, v77, v78, v80
	v_div_fixup_f32 v12, v77, v76, 1.0
	v_cvt_pk_bf16_f32 v12, v12, v12
	global_store_short v[68:69], v12, off
	v_div_scale_f32 v79, vcc, 1.0, v82, 1.0
	v_fma_f32 v80, -v83, v84, 1.0
	v_fmac_f32_e32 v84, v80, v84
	v_mul_f32_e32 v80, v79, v84
	v_fma_f32 v81, -v83, v80, v79
	v_fmac_f32_e32 v80, v81, v84
	v_fma_f32 v83, -v83, v80, v79
	v_div_fmas_f32 v83, v83, v84, v80
	v_div_fixup_f32 v28, v83, v82, 1.0
	v_cvt_pk_bf16_f32 v28, v28, v28
	global_store_short v[68:69], v28, off offset:64
	v_mul_f32_e32 v76, 0xbfb8aa3b, v13
	v_mul_f32_e32 v82, 0xbfb8aa3b, v29
	v_exp_f32_e32 v76, v76
	v_exp_f32_e32 v82, v82
	v_add_f32_e32 v76, 1.0, v76
	v_add_f32_e32 v82, 1.0, v82
	v_div_scale_f32 v77, s[0:1], v76, v76, 1.0
	v_div_scale_f32 v83, s[0:1], v82, v82, 1.0
	v_rcp_f32_e32 v78, v77
	v_rcp_f32_e32 v84, v83
	v_div_scale_f32 v79, vcc, 1.0, v76, 1.0
	v_fma_f32 v80, -v77, v78, 1.0
	v_fmac_f32_e32 v78, v80, v78
	v_mul_f32_e32 v80, v79, v78
	v_fma_f32 v81, -v77, v80, v79
	v_fmac_f32_e32 v80, v81, v78
	v_fma_f32 v77, -v77, v80, v79
	v_div_fmas_f32 v77, v77, v78, v80
	v_div_fixup_f32 v13, v77, v76, 1.0
	v_cvt_pk_bf16_f32 v13, v13, v13
	global_store_short v[70:71], v13, off
	v_div_scale_f32 v79, vcc, 1.0, v82, 1.0
	v_fma_f32 v80, -v83, v84, 1.0
	v_fmac_f32_e32 v84, v80, v84
	v_mul_f32_e32 v80, v79, v84
	v_fma_f32 v81, -v83, v80, v79
	v_fmac_f32_e32 v80, v81, v84
	v_fma_f32 v83, -v83, v80, v79
	v_div_fmas_f32 v83, v83, v84, v80
	v_div_fixup_f32 v29, v83, v82, 1.0
	v_cvt_pk_bf16_f32 v29, v29, v29
; DI bf16_t f2bf(float x) { return (bf16_t)(pk_bf16(x, 0.f) & 0xffffu); }
; DI int crow(int r, int h) { return (r & 3) + 8 * (r >> 2) + 4 * h; }
; DI float sigmoidf_(float x) { return 1.f / (1.f + __expf(-x)); }
; DI void phase_gemm1(const Params& p, int g, char* smem, int bid, int nb) {
;     ...
;     } else if (nt < 64) {
;       const int coff = (nt < 32) ? nt * 128 - 2048 : nt * 128 - 3072;
;       const int mode = (nt < 32) ? 0 : (nt < 48 ? 1 : 2);
; #pragma unroll
;       for (int mi = 0; mi < 2; ++mi)
; #pragma unroll
;         for (int ni = 0; ni < 2; ++ni)
; #pragma unroll
;           for (int r = 0; r < 16; ++r) {
;             float v = acc[mi][ni][r];
;             if (mode == 1) v = v * sigmoidf_(v); else if (mode == 2) v = sigmoidf_(v);
;             projt[(wm * 64 + mi * 32 + crow(r, h)) * NPROJ + coff + wn * 64 + ni * 32 + l31] = f2bf(v);
;           }
	global_store_short v[70:71], v29, off offset:64
	v_mul_f32_e32 v76, 0xbfb8aa3b, v14
	v_mul_f32_e32 v82, 0xbfb8aa3b, v30
	v_exp_f32_e32 v76, v76
	v_exp_f32_e32 v82, v82
	v_add_f32_e32 v76, 1.0, v76
	v_add_f32_e32 v82, 1.0, v82
	v_div_scale_f32 v77, s[0:1], v76, v76, 1.0
	v_div_scale_f32 v83, s[0:1], v82, v82, 1.0
	v_rcp_f32_e32 v78, v77
	v_rcp_f32_e32 v84, v83
	v_div_scale_f32 v79, vcc, 1.0, v76, 1.0
	v_fma_f32 v80, -v77, v78, 1.0
	v_fmac_f32_e32 v78, v80, v78
	v_mul_f32_e32 v80, v79, v78
	v_fma_f32 v81, -v77, v80, v79
	v_fmac_f32_e32 v80, v81, v78
	v_fma_f32 v77, -v77, v80, v79
	v_div_fmas_f32 v77, v77, v78, v80
	v_div_fixup_f32 v14, v77, v76, 1.0
	v_cvt_pk_bf16_f32 v14, v14, v14
	global_store_short v[72:73], v14, off
	v_div_scale_f32 v79, vcc, 1.0, v82, 1.0
	v_fma_f32 v80, -v83, v84, 1.0
	v_fmac_f32_e32 v84, v80, v84
	v_mul_f32_e32 v80, v79, v84
	v_fma_f32 v81, -v83, v80, v79
	v_fmac_f32_e32 v80, v81, v84
	v_fma_f32 v83, -v83, v80, v79
	v_div_fmas_f32 v83, v83, v84, v80
	v_div_fixup_f32 v30, v83, v82, 1.0
	v_cvt_pk_bf16_f32 v30, v30, v30
	global_store_short v[72:73], v30, off offset:64
	v_mul_f32_e32 v76, 0xbfb8aa3b, v15
	v_mul_f32_e32 v82, 0xbfb8aa3b, v31
	v_exp_f32_e32 v76, v76
	v_exp_f32_e32 v82, v82
	v_add_f32_e32 v76, 1.0, v76
	v_add_f32_e32 v82, 1.0, v82
	v_div_scale_f32 v77, s[0:1], v76, v76, 1.0
	v_div_scale_f32 v83, s[0:1], v82, v82, 1.0
	v_rcp_f32_e32 v78, v77
	v_rcp_f32_e32 v84, v83
	v_div_scale_f32 v79, vcc, 1.0, v76, 1.0
	v_fma_f32 v80, -v77, v78, 1.0
	v_fmac_f32_e32 v78, v80, v78
	v_mul_f32_e32 v80, v79, v78
	v_fma_f32 v81, -v77, v80, v79
	v_fmac_f32_e32 v80, v81, v78
	v_fma_f32 v77, -v77, v80, v79
	v_div_fmas_f32 v77, v77, v78, v80
	v_div_fixup_f32 v15, v77, v76, 1.0
	v_cvt_pk_bf16_f32 v15, v15, v15
	global_store_short v[74:75], v15, off
	v_div_scale_f32 v79, vcc, 1.0, v82, 1.0
	v_fma_f32 v80, -v83, v84, 1.0
	v_fmac_f32_e32 v84, v80, v84
	v_mul_f32_e32 v80, v79, v84
	v_fma_f32 v81, -v83, v80, v79
	v_fmac_f32_e32 v80, v81, v84
	v_fma_f32 v83, -v83, v80, v79
	v_div_fmas_f32 v83, v83, v84, v80
	v_div_fixup_f32 v31, v83, v82, 1.0
	v_cvt_pk_bf16_f32 v31, v31, v31
	global_store_short v[74:75], v31, off offset:64
	s_branch .Lep2_done
.Lep2_t1:
	v_lshl_add_u64 v[70:71], v[66:67], 0, s[14:15]
	v_lshl_add_u64 v[72:73], v[70:71], 0, s[14:15]
	v_lshl_add_u64 v[74:75], v[72:73], 0, s[14:15]
	v_mul_f32_e32 v76, 0xbfb8aa3b, v48
	v_mul_f32_e32 v82, 0xbfb8aa3b, v32
	v_exp_f32_e32 v76, v76
	v_exp_f32_e32 v82, v82
	v_add_f32_e32 v76, 1.0, v76
	v_add_f32_e32 v82, 1.0, v82
	v_div_scale_f32 v77, s[0:1], v76, v76, 1.0
	v_div_scale_f32 v83, s[0:1], v82, v82, 1.0
	v_rcp_f32_e32 v78, v77
	v_rcp_f32_e32 v84, v83
	v_div_scale_f32 v79, vcc, 1.0, v76, 1.0
	v_fma_f32 v80, -v77, v78, 1.0
	v_fmac_f32_e32 v78, v80, v78
	v_mul_f32_e32 v80, v79, v78
	v_fma_f32 v81, -v77, v80, v79
	v_fmac_f32_e32 v80, v81, v78
	v_fma_f32 v77, -v77, v80, v79
	v_div_fmas_f32 v77, v77, v78, v80
	v_div_fixup_f32 v77, v77, v76, 1.0
	v_mul_f32_e32 v48, v48, v77
	v_cvt_pk_bf16_f32 v48, v48, v48
	global_store_short v[66:67], v48, off
	v_div_scale_f32 v79, vcc, 1.0, v82, 1.0
	v_fma_f32 v80, -v83, v84, 1.0
	v_fmac_f32_e32 v84, v80, v84
	v_mul_f32_e32 v80, v79, v84
	v_fma_f32 v81, -v83, v80, v79
	v_fmac_f32_e32 v80, v81, v84
	v_fma_f32 v83, -v83, v80, v79
	v_div_fmas_f32 v83, v83, v84, v80
	v_div_fixup_f32 v83, v83, v82, 1.0
	v_mul_f32_e32 v32, v32, v83
	v_cvt_pk_bf16_f32 v32, v32, v32
	global_store_short v[66:67], v32, off offset:64
	v_mul_f32_e32 v76, 0xbfb8aa3b, v49
	v_mul_f32_e32 v82, 0xbfb8aa3b, v33
	v_exp_f32_e32 v76, v76
	v_exp_f32_e32 v82, v82
	v_add_f32_e32 v76, 1.0, v76
	v_add_f32_e32 v82, 1.0, v82
	v_div_scale_f32 v77, s[0:1], v76, v76, 1.0
	v_div_scale_f32 v83, s[0:1], v82, v82, 1.0
	v_rcp_f32_e32 v78, v77
	v_rcp_f32_e32 v84, v83
	v_div_scale_f32 v79, vcc, 1.0, v76, 1.0
	v_fma_f32 v80, -v77, v78, 1.0
	v_fmac_f32_e32 v78, v80, v78
	v_mul_f32_e32 v80, v79, v78
	v_fma_f32 v81, -v77, v80, v79
	v_fmac_f32_e32 v80, v81, v78
	v_fma_f32 v77, -v77, v80, v79
	v_div_fmas_f32 v77, v77, v78, v80
	v_div_fixup_f32 v77, v77, v76, 1.0
	v_mul_f32_e32 v49, v49, v77
	v_cvt_pk_bf16_f32 v49, v49, v49
	global_store_short v[70:71], v49, off
	v_div_scale_f32 v79, vcc, 1.0, v82, 1.0
	v_fma_f32 v80, -v83, v84, 1.0
	v_fmac_f32_e32 v84, v80, v84
	v_mul_f32_e32 v80, v79, v84
	v_fma_f32 v81, -v83, v80, v79
	v_fmac_f32_e32 v80, v81, v84
	v_fma_f32 v83, -v83, v80, v79
	v_div_fmas_f32 v83, v83, v84, v80
	v_div_fixup_f32 v83, v83, v82, 1.0
	v_mul_f32_e32 v33, v33, v83
	v_cvt_pk_bf16_f32 v33, v33, v33
	global_store_short v[70:71], v33, off offset:64
	v_mul_f32_e32 v76, 0xbfb8aa3b, v50
	v_mul_f32_e32 v82, 0xbfb8aa3b, v34
	v_exp_f32_e32 v76, v76
	v_exp_f32_e32 v82, v82
	v_add_f32_e32 v76, 1.0, v76
	v_add_f32_e32 v82, 1.0, v82
	v_div_scale_f32 v77, s[0:1], v76, v76, 1.0
	v_div_scale_f32 v83, s[0:1], v82, v82, 1.0
	v_rcp_f32_e32 v78, v77
	v_rcp_f32_e32 v84, v83
	v_div_scale_f32 v79, vcc, 1.0, v76, 1.0
	v_fma_f32 v80, -v77, v78, 1.0
	v_fmac_f32_e32 v78, v80, v78
	v_mul_f32_e32 v80, v79, v78
	v_fma_f32 v81, -v77, v80, v79
	v_fmac_f32_e32 v80, v81, v78
	v_fma_f32 v77, -v77, v80, v79
	v_div_fmas_f32 v77, v77, v78, v80
	v_div_fixup_f32 v77, v77, v76, 1.0
	v_mul_f32_e32 v50, v50, v77
	v_cvt_pk_bf16_f32 v50, v50, v50
	global_store_short v[72:73], v50, off
	v_div_scale_f32 v79, vcc, 1.0, v82, 1.0
	v_fma_f32 v80, -v83, v84, 1.0
	v_fmac_f32_e32 v84, v80, v84
	v_mul_f32_e32 v80, v79, v84
	v_fma_f32 v81, -v83, v80, v79
	v_fmac_f32_e32 v80, v81, v84
	v_fma_f32 v83, -v83, v80, v79
	v_div_fmas_f32 v83, v83, v84, v80
	v_div_fixup_f32 v83, v83, v82, 1.0
	v_mul_f32_e32 v34, v34, v83
	v_cvt_pk_bf16_f32 v34, v34, v34
; DI bf16_t f2bf(float x) { return (bf16_t)(pk_bf16(x, 0.f) & 0xffffu); }
; DI int crow(int r, int h) { return (r & 3) + 8 * (r >> 2) + 4 * h; }
; DI float sigmoidf_(float x) { return 1.f / (1.f + __expf(-x)); }
; DI void phase_gemm1(const Params& p, int g, char* smem, int bid, int nb) {
;     ...
;     } else if (nt < 64) {
;       const int coff = (nt < 32) ? nt * 128 - 2048 : nt * 128 - 3072;
;       const int mode = (nt < 32) ? 0 : (nt < 48 ? 1 : 2);
; #pragma unroll
;       for (int mi = 0; mi < 2; ++mi)
; #pragma unroll
;         for (int ni = 0; ni < 2; ++ni)
; #pragma unroll
;           for (int r = 0; r < 16; ++r) {
;             float v = acc[mi][ni][r];
;             if (mode == 1) v = v * sigmoidf_(v); else if (mode == 2) v = sigmoidf_(v);
;             projt[(wm * 64 + mi * 32 + crow(r, h)) * NPROJ + coff + wn * 64 + ni * 32 + l31] = f2bf(v);
;           }
	global_store_short v[72:73], v34, off offset:64
	v_mul_f32_e32 v76, 0xbfb8aa3b, v51
	v_mul_f32_e32 v82, 0xbfb8aa3b, v35
	v_exp_f32_e32 v76, v76
	v_exp_f32_e32 v82, v82
	v_add_f32_e32 v76, 1.0, v76
	v_add_f32_e32 v82, 1.0, v82
	v_div_scale_f32 v77, s[0:1], v76, v76, 1.0
	v_div_scale_f32 v83, s[0:1], v82, v82, 1.0
	v_rcp_f32_e32 v78, v77
	v_rcp_f32_e32 v84, v83
	v_div_scale_f32 v79, vcc, 1.0, v76, 1.0
	v_fma_f32 v80, -v77, v78, 1.0
	v_fmac_f32_e32 v78, v80, v78
	v_mul_f32_e32 v80, v79, v78
	v_fma_f32 v81, -v77, v80, v79
	v_fmac_f32_e32 v80, v81, v78
	v_fma_f32 v77, -v77, v80, v79
	v_div_fmas_f32 v77, v77, v78, v80
	v_div_fixup_f32 v77, v77, v76, 1.0
	v_mul_f32_e32 v51, v51, v77
	v_cvt_pk_bf16_f32 v51, v51, v51
	global_store_short v[74:75], v51, off
	v_div_scale_f32 v79, vcc, 1.0, v82, 1.0
	v_fma_f32 v80, -v83, v84, 1.0
	v_fmac_f32_e32 v84, v80, v84
	v_mul_f32_e32 v80, v79, v84
	v_fma_f32 v81, -v83, v80, v79
	v_fmac_f32_e32 v80, v81, v84
	v_fma_f32 v83, -v83, v80, v79
	v_div_fmas_f32 v83, v83, v84, v80
	v_div_fixup_f32 v83, v83, v82, 1.0
	v_mul_f32_e32 v35, v35, v83
	v_cvt_pk_bf16_f32 v35, v35, v35
	global_store_short v[74:75], v35, off offset:64
	s_mov_b64 s[0:1], 0x14000
	v_lshl_add_u64 v[68:69], v[66:67], 0, s[0:1]
	v_lshl_add_u64 v[70:71], v[68:69], 0, s[14:15]
	v_lshl_add_u64 v[72:73], v[70:71], 0, s[14:15]
	v_lshl_add_u64 v[74:75], v[72:73], 0, s[14:15]
	v_mul_f32_e32 v76, 0xbfb8aa3b, v52
	v_mul_f32_e32 v82, 0xbfb8aa3b, v36
	v_exp_f32_e32 v76, v76
	v_exp_f32_e32 v82, v82
	v_add_f32_e32 v76, 1.0, v76
	v_add_f32_e32 v82, 1.0, v82
	v_div_scale_f32 v77, s[0:1], v76, v76, 1.0
	v_div_scale_f32 v83, s[0:1], v82, v82, 1.0
	v_rcp_f32_e32 v78, v77
	v_rcp_f32_e32 v84, v83
	v_div_scale_f32 v79, vcc, 1.0, v76, 1.0
	v_fma_f32 v80, -v77, v78, 1.0
	v_fmac_f32_e32 v78, v80, v78
	v_mul_f32_e32 v80, v79, v78
	v_fma_f32 v81, -v77, v80, v79
	v_fmac_f32_e32 v80, v81, v78
	v_fma_f32 v77, -v77, v80, v79
	v_div_fmas_f32 v77, v77, v78, v80
	v_div_fixup_f32 v77, v77, v76, 1.0
	v_mul_f32_e32 v52, v52, v77
	v_cvt_pk_bf16_f32 v52, v52, v52
	global_store_short v[68:69], v52, off
	v_div_scale_f32 v79, vcc, 1.0, v82, 1.0
	v_fma_f32 v80, -v83, v84, 1.0
	v_fmac_f32_e32 v84, v80, v84
	v_mul_f32_e32 v80, v79, v84
	v_fma_f32 v81, -v83, v80, v79
	v_fmac_f32_e32 v80, v81, v84
	v_fma_f32 v83, -v83, v80, v79
	v_div_fmas_f32 v83, v83, v84, v80
	v_div_fixup_f32 v83, v83, v82, 1.0
	v_mul_f32_e32 v36, v36, v83
	v_cvt_pk_bf16_f32 v36, v36, v36
	global_store_short v[68:69], v36, off offset:64
	v_mul_f32_e32 v76, 0xbfb8aa3b, v53
	v_mul_f32_e32 v82, 0xbfb8aa3b, v37
	v_exp_f32_e32 v76, v76
	v_exp_f32_e32 v82, v82
	v_add_f32_e32 v76, 1.0, v76
	v_add_f32_e32 v82, 1.0, v82
	v_div_scale_f32 v77, s[0:1], v76, v76, 1.0
	v_div_scale_f32 v83, s[0:1], v82, v82, 1.0
	v_rcp_f32_e32 v78, v77
	v_rcp_f32_e32 v84, v83
	v_div_scale_f32 v79, vcc, 1.0, v76, 1.0
	v_fma_f32 v80, -v77, v78, 1.0
	v_fmac_f32_e32 v78, v80, v78
	v_mul_f32_e32 v80, v79, v78
	v_fma_f32 v81, -v77, v80, v79
	v_fmac_f32_e32 v80, v81, v78
	v_fma_f32 v77, -v77, v80, v79
	v_div_fmas_f32 v77, v77, v78, v80
	v_div_fixup_f32 v77, v77, v76, 1.0
	v_mul_f32_e32 v53, v53, v77
	v_cvt_pk_bf16_f32 v53, v53, v53
	global_store_short v[70:71], v53, off
	v_div_scale_f32 v79, vcc, 1.0, v82, 1.0
	v_fma_f32 v80, -v83, v84, 1.0
	v_fmac_f32_e32 v84, v80, v84
	v_mul_f32_e32 v80, v79, v84
	v_fma_f32 v81, -v83, v80, v79
	v_fmac_f32_e32 v80, v81, v84
	v_fma_f32 v83, -v83, v80, v79
	v_div_fmas_f32 v83, v83, v84, v80
	v_div_fixup_f32 v83, v83, v82, 1.0
	v_mul_f32_e32 v37, v37, v83
	v_cvt_pk_bf16_f32 v37, v37, v37
	global_store_short v[70:71], v37, off offset:64
	v_mul_f32_e32 v76, 0xbfb8aa3b, v54
	v_mul_f32_e32 v82, 0xbfb8aa3b, v38
	v_exp_f32_e32 v76, v76
	v_exp_f32_e32 v82, v82
	v_add_f32_e32 v76, 1.0, v76
	v_add_f32_e32 v82, 1.0, v82
	v_div_scale_f32 v77, s[0:1], v76, v76, 1.0
	v_div_scale_f32 v83, s[0:1], v82, v82, 1.0
	v_rcp_f32_e32 v78, v77
	v_rcp_f32_e32 v84, v83
	v_div_scale_f32 v79, vcc, 1.0, v76, 1.0
	v_fma_f32 v80, -v77, v78, 1.0
	v_fmac_f32_e32 v78, v80, v78
	v_mul_f32_e32 v80, v79, v78
	v_fma_f32 v81, -v77, v80, v79
	v_fmac_f32_e32 v80, v81, v78
	v_fma_f32 v77, -v77, v80, v79
	v_div_fmas_f32 v77, v77, v78, v80
	v_div_fixup_f32 v77, v77, v76, 1.0
	v_mul_f32_e32 v54, v54, v77
	v_cvt_pk_bf16_f32 v54, v54, v54
	global_store_short v[72:73], v54, off
	v_div_scale_f32 v79, vcc, 1.0, v82, 1.0
	v_fma_f32 v80, -v83, v84, 1.0
	v_fmac_f32_e32 v84, v80, v84
	v_mul_f32_e32 v80, v79, v84
	v_fma_f32 v81, -v83, v80, v79
	v_fmac_f32_e32 v80, v81, v84
	v_fma_f32 v83, -v83, v80, v79
	v_div_fmas_f32 v83, v83, v84, v80
	v_div_fixup_f32 v83, v83, v82, 1.0
	v_mul_f32_e32 v38, v38, v83
	v_cvt_pk_bf16_f32 v38, v38, v38
	global_store_short v[72:73], v38, off offset:64
	v_mul_f32_e32 v76, 0xbfb8aa3b, v55
	v_mul_f32_e32 v82, 0xbfb8aa3b, v39
	v_exp_f32_e32 v76, v76
	v_exp_f32_e32 v82, v82
	v_add_f32_e32 v76, 1.0, v76
	v_add_f32_e32 v82, 1.0, v82
	v_div_scale_f32 v77, s[0:1], v76, v76, 1.0
	v_div_scale_f32 v83, s[0:1], v82, v82, 1.0
	v_rcp_f32_e32 v78, v77
	v_rcp_f32_e32 v84, v83
	v_div_scale_f32 v79, vcc, 1.0, v76, 1.0
	v_fma_f32 v80, -v77, v78, 1.0
	v_fmac_f32_e32 v78, v80, v78
	v_mul_f32_e32 v80, v79, v78
	v_fma_f32 v81, -v77, v80, v79
	v_fmac_f32_e32 v80, v81, v78
	v_fma_f32 v77, -v77, v80, v79
	v_div_fmas_f32 v77, v77, v78, v80
	v_div_fixup_f32 v77, v77, v76, 1.0
	v_mul_f32_e32 v55, v55, v77
	v_cvt_pk_bf16_f32 v55, v55, v55
	global_store_short v[74:75], v55, off
	v_div_scale_f32 v79, vcc, 1.0, v82, 1.0
	v_fma_f32 v80, -v83, v84, 1.0
	v_fmac_f32_e32 v84, v80, v84
	v_mul_f32_e32 v80, v79, v84
	v_fma_f32 v81, -v83, v80, v79
	v_fmac_f32_e32 v80, v81, v84
	v_fma_f32 v83, -v83, v80, v79
; DI bf16_t f2bf(float x) { return (bf16_t)(pk_bf16(x, 0.f) & 0xffffu); }
; DI int crow(int r, int h) { return (r & 3) + 8 * (r >> 2) + 4 * h; }
; DI float sigmoidf_(float x) { return 1.f / (1.f + __expf(-x)); }
; DI void phase_gemm1(const Params& p, int g, char* smem, int bid, int nb) {
;     ...
;           for (int r = 0; r < 16; ++r) {
;             float v = acc[mi][ni][r];
;             if (mode == 1) v = v * sigmoidf_(v); else if (mode == 2) v = sigmoidf_(v);
;             projt[(wm * 64 + mi * 32 + crow(r, h)) * NPROJ + coff + wn * 64 + ni * 32 + l31] = f2bf(v);
	v_div_fmas_f32 v83, v83, v84, v80
	v_div_fixup_f32 v83, v83, v82, 1.0
	v_mul_f32_e32 v39, v39, v83
	v_cvt_pk_bf16_f32 v39, v39, v39
	global_store_short v[74:75], v39, off offset:64
	s_mov_b64 s[0:1], 0x28000
	v_lshl_add_u64 v[68:69], v[66:67], 0, s[0:1]
	v_lshl_add_u64 v[70:71], v[68:69], 0, s[14:15]
	v_lshl_add_u64 v[72:73], v[70:71], 0, s[14:15]
	v_lshl_add_u64 v[74:75], v[72:73], 0, s[14:15]
	v_mul_f32_e32 v76, 0xbfb8aa3b, v56
	v_mul_f32_e32 v82, 0xbfb8aa3b, v40
	v_exp_f32_e32 v76, v76
	v_exp_f32_e32 v82, v82
	v_add_f32_e32 v76, 1.0, v76
	v_add_f32_e32 v82, 1.0, v82
	v_div_scale_f32 v77, s[0:1], v76, v76, 1.0
	v_div_scale_f32 v83, s[0:1], v82, v82, 1.0
	v_rcp_f32_e32 v78, v77
	v_rcp_f32_e32 v84, v83
	v_div_scale_f32 v79, vcc, 1.0, v76, 1.0
	v_fma_f32 v80, -v77, v78, 1.0
	v_fmac_f32_e32 v78, v80, v78
	v_mul_f32_e32 v80, v79, v78
	v_fma_f32 v81, -v77, v80, v79
	v_fmac_f32_e32 v80, v81, v78
	v_fma_f32 v77, -v77, v80, v79
	v_div_fmas_f32 v77, v77, v78, v80
	v_div_fixup_f32 v77, v77, v76, 1.0
	v_mul_f32_e32 v56, v56, v77
	v_cvt_pk_bf16_f32 v56, v56, v56
	global_store_short v[68:69], v56, off
	v_div_scale_f32 v79, vcc, 1.0, v82, 1.0
	v_fma_f32 v80, -v83, v84, 1.0
	v_fmac_f32_e32 v84, v80, v84
	v_mul_f32_e32 v80, v79, v84
	v_fma_f32 v81, -v83, v80, v79
	v_fmac_f32_e32 v80, v81, v84
	v_fma_f32 v83, -v83, v80, v79
	v_div_fmas_f32 v83, v83, v84, v80
	v_div_fixup_f32 v83, v83, v82, 1.0
	v_mul_f32_e32 v40, v40, v83
	v_cvt_pk_bf16_f32 v40, v40, v40
	global_store_short v[68:69], v40, off offset:64
	v_mul_f32_e32 v76, 0xbfb8aa3b, v57
	v_mul_f32_e32 v82, 0xbfb8aa3b, v41
	v_exp_f32_e32 v76, v76
	v_exp_f32_e32 v82, v82
	v_add_f32_e32 v76, 1.0, v76
	v_add_f32_e32 v82, 1.0, v82
	v_div_scale_f32 v77, s[0:1], v76, v76, 1.0
	v_div_scale_f32 v83, s[0:1], v82, v82, 1.0
	v_rcp_f32_e32 v78, v77
	v_rcp_f32_e32 v84, v83
	v_div_scale_f32 v79, vcc, 1.0, v76, 1.0
	v_fma_f32 v80, -v77, v78, 1.0
	v_fmac_f32_e32 v78, v80, v78
	v_mul_f32_e32 v80, v79, v78
	v_fma_f32 v81, -v77, v80, v79
	v_fmac_f32_e32 v80, v81, v78
	v_fma_f32 v77, -v77, v80, v79
	v_div_fmas_f32 v77, v77, v78, v80
	v_div_fixup_f32 v77, v77, v76, 1.0
	v_mul_f32_e32 v57, v57, v77
	v_cvt_pk_bf16_f32 v57, v57, v57
	global_store_short v[70:71], v57, off
	v_div_scale_f32 v79, vcc, 1.0, v82, 1.0
	v_fma_f32 v80, -v83, v84, 1.0
	v_fmac_f32_e32 v84, v80, v84
	v_mul_f32_e32 v80, v79, v84
	v_fma_f32 v81, -v83, v80, v79
	v_fmac_f32_e32 v80, v81, v84
	v_fma_f32 v83, -v83, v80, v79
	v_div_fmas_f32 v83, v83, v84, v80
	v_div_fixup_f32 v83, v83, v82, 1.0
	v_mul_f32_e32 v41, v41, v83
	v_cvt_pk_bf16_f32 v41, v41, v41
	global_store_short v[70:71], v41, off offset:64
	v_mul_f32_e32 v76, 0xbfb8aa3b, v58
	v_mul_f32_e32 v82, 0xbfb8aa3b, v42
	v_exp_f32_e32 v76, v76
	v_exp_f32_e32 v82, v82
	v_add_f32_e32 v76, 1.0, v76
	v_add_f32_e32 v82, 1.0, v82
	v_div_scale_f32 v77, s[0:1], v76, v76, 1.0
	v_div_scale_f32 v83, s[0:1], v82, v82, 1.0
	v_rcp_f32_e32 v78, v77
	v_rcp_f32_e32 v84, v83
	v_div_scale_f32 v79, vcc, 1.0, v76, 1.0
	v_fma_f32 v80, -v77, v78, 1.0
	v_fmac_f32_e32 v78, v80, v78
	v_mul_f32_e32 v80, v79, v78
	v_fma_f32 v81, -v77, v80, v79
	v_fmac_f32_e32 v80, v81, v78
	v_fma_f32 v77, -v77, v80, v79
	v_div_fmas_f32 v77, v77, v78, v80
	v_div_fixup_f32 v77, v77, v76, 1.0
	v_mul_f32_e32 v58, v58, v77
	v_cvt_pk_bf16_f32 v58, v58, v58
	global_store_short v[72:73], v58, off
	v_div_scale_f32 v79, vcc, 1.0, v82, 1.0
	v_fma_f32 v80, -v83, v84, 1.0
	v_fmac_f32_e32 v84, v80, v84
	v_mul_f32_e32 v80, v79, v84
	v_fma_f32 v81, -v83, v80, v79
	v_fmac_f32_e32 v80, v81, v84
	v_fma_f32 v83, -v83, v80, v79
	v_div_fmas_f32 v83, v83, v84, v80
	v_div_fixup_f32 v83, v83, v82, 1.0
	v_mul_f32_e32 v42, v42, v83
	v_cvt_pk_bf16_f32 v42, v42, v42
	global_store_short v[72:73], v42, off offset:64
	v_mul_f32_e32 v76, 0xbfb8aa3b, v59
	v_mul_f32_e32 v82, 0xbfb8aa3b, v43
	v_exp_f32_e32 v76, v76
	v_exp_f32_e32 v82, v82
	v_add_f32_e32 v76, 1.0, v76
	v_add_f32_e32 v82, 1.0, v82
	v_div_scale_f32 v77, s[0:1], v76, v76, 1.0
	v_div_scale_f32 v83, s[0:1], v82, v82, 1.0
	v_rcp_f32_e32 v78, v77
	v_rcp_f32_e32 v84, v83
	v_div_scale_f32 v79, vcc, 1.0, v76, 1.0
	v_fma_f32 v80, -v77, v78, 1.0
	v_fmac_f32_e32 v78, v80, v78
	v_mul_f32_e32 v80, v79, v78
	v_fma_f32 v81, -v77, v80, v79
	v_fmac_f32_e32 v80, v81, v78
	v_fma_f32 v77, -v77, v80, v79
	v_div_fmas_f32 v77, v77, v78, v80
	v_div_fixup_f32 v77, v77, v76, 1.0
	v_mul_f32_e32 v59, v59, v77
	v_cvt_pk_bf16_f32 v59, v59, v59
	global_store_short v[74:75], v59, off
	v_div_scale_f32 v79, vcc, 1.0, v82, 1.0
	v_fma_f32 v80, -v83, v84, 1.0
	v_fmac_f32_e32 v84, v80, v84
	v_mul_f32_e32 v80, v79, v84
	v_fma_f32 v81, -v83, v80, v79
	v_fmac_f32_e32 v80, v81, v84
	v_fma_f32 v83, -v83, v80, v79
	v_div_fmas_f32 v83, v83, v84, v80
	v_div_fixup_f32 v83, v83, v82, 1.0
	v_mul_f32_e32 v43, v43, v83
	v_cvt_pk_bf16_f32 v43, v43, v43
	global_store_short v[74:75], v43, off offset:64
	s_mov_b64 s[0:1], 0x3c000
	v_lshl_add_u64 v[68:69], v[66:67], 0, s[0:1]
	v_lshl_add_u64 v[70:71], v[68:69], 0, s[14:15]
	v_lshl_add_u64 v[72:73], v[70:71], 0, s[14:15]
	v_lshl_add_u64 v[74:75], v[72:73], 0, s[14:15]
	v_mul_f32_e32 v76, 0xbfb8aa3b, v60
	v_mul_f32_e32 v82, 0xbfb8aa3b, v44
	v_exp_f32_e32 v76, v76
	v_exp_f32_e32 v82, v82
	v_add_f32_e32 v76, 1.0, v76
	v_add_f32_e32 v82, 1.0, v82
	v_div_scale_f32 v77, s[0:1], v76, v76, 1.0
	v_div_scale_f32 v83, s[0:1], v82, v82, 1.0
	v_rcp_f32_e32 v78, v77
	v_rcp_f32_e32 v84, v83
	v_div_scale_f32 v79, vcc, 1.0, v76, 1.0
	v_fma_f32 v80, -v77, v78, 1.0
	v_fmac_f32_e32 v78, v80, v78
	v_mul_f32_e32 v80, v79, v78
	v_fma_f32 v81, -v77, v80, v79
	v_fmac_f32_e32 v80, v81, v78
	v_fma_f32 v77, -v77, v80, v79
	v_div_fmas_f32 v77, v77, v78, v80
; DI bf16_t f2bf(float x) { return (bf16_t)(pk_bf16(x, 0.f) & 0xffffu); }
; DI int crow(int r, int h) { return (r & 3) + 8 * (r >> 2) + 4 * h; }
; DI float sigmoidf_(float x) { return 1.f / (1.f + __expf(-x)); }
; DI void phase_gemm1(const Params& p, int g, char* smem, int bid, int nb) {
;     ...
;           for (int r = 0; r < 16; ++r) {
;             float v = acc[mi][ni][r];
;             if (mode == 1) v = v * sigmoidf_(v); else if (mode == 2) v = sigmoidf_(v);
;             projt[(wm * 64 + mi * 32 + crow(r, h)) * NPROJ + coff + wn * 64 + ni * 32 + l31] = f2bf(v);
	v_div_fixup_f32 v77, v77, v76, 1.0
	v_mul_f32_e32 v60, v60, v77
	v_cvt_pk_bf16_f32 v60, v60, v60
	global_store_short v[68:69], v60, off
	v_div_scale_f32 v79, vcc, 1.0, v82, 1.0
	v_fma_f32 v80, -v83, v84, 1.0
	v_fmac_f32_e32 v84, v80, v84
	v_mul_f32_e32 v80, v79, v84
	v_fma_f32 v81, -v83, v80, v79
	v_fmac_f32_e32 v80, v81, v84
	v_fma_f32 v83, -v83, v80, v79
	v_div_fmas_f32 v83, v83, v84, v80
	v_div_fixup_f32 v83, v83, v82, 1.0
	v_mul_f32_e32 v44, v44, v83
	v_cvt_pk_bf16_f32 v44, v44, v44
	global_store_short v[68:69], v44, off offset:64
	v_mul_f32_e32 v76, 0xbfb8aa3b, v61
	v_mul_f32_e32 v82, 0xbfb8aa3b, v45
	v_exp_f32_e32 v76, v76
	v_exp_f32_e32 v82, v82
	v_add_f32_e32 v76, 1.0, v76
	v_add_f32_e32 v82, 1.0, v82
	v_div_scale_f32 v77, s[0:1], v76, v76, 1.0
	v_div_scale_f32 v83, s[0:1], v82, v82, 1.0
	v_rcp_f32_e32 v78, v77
	v_rcp_f32_e32 v84, v83
	v_div_scale_f32 v79, vcc, 1.0, v76, 1.0
	v_fma_f32 v80, -v77, v78, 1.0
	v_fmac_f32_e32 v78, v80, v78
	v_mul_f32_e32 v80, v79, v78
	v_fma_f32 v81, -v77, v80, v79
	v_fmac_f32_e32 v80, v81, v78
	v_fma_f32 v77, -v77, v80, v79
	v_div_fmas_f32 v77, v77, v78, v80
	v_div_fixup_f32 v77, v77, v76, 1.0
	v_mul_f32_e32 v61, v61, v77
	v_cvt_pk_bf16_f32 v61, v61, v61
	global_store_short v[70:71], v61, off
	v_div_scale_f32 v79, vcc, 1.0, v82, 1.0
	v_fma_f32 v80, -v83, v84, 1.0
	v_fmac_f32_e32 v84, v80, v84
	v_mul_f32_e32 v80, v79, v84
	v_fma_f32 v81, -v83, v80, v79
	v_fmac_f32_e32 v80, v81, v84
	v_fma_f32 v83, -v83, v80, v79
	v_div_fmas_f32 v83, v83, v84, v80
	v_div_fixup_f32 v83, v83, v82, 1.0
	v_mul_f32_e32 v45, v45, v83
	v_cvt_pk_bf16_f32 v45, v45, v45
	global_store_short v[70:71], v45, off offset:64
	v_mul_f32_e32 v76, 0xbfb8aa3b, v62
	v_mul_f32_e32 v82, 0xbfb8aa3b, v46
	v_exp_f32_e32 v76, v76
	v_exp_f32_e32 v82, v82
	v_add_f32_e32 v76, 1.0, v76
	v_add_f32_e32 v82, 1.0, v82
	v_div_scale_f32 v77, s[0:1], v76, v76, 1.0
	v_div_scale_f32 v83, s[0:1], v82, v82, 1.0
	v_rcp_f32_e32 v78, v77
	v_rcp_f32_e32 v84, v83
	v_div_scale_f32 v79, vcc, 1.0, v76, 1.0
	v_fma_f32 v80, -v77, v78, 1.0
	v_fmac_f32_e32 v78, v80, v78
	v_mul_f32_e32 v80, v79, v78
	v_fma_f32 v81, -v77, v80, v79
	v_fmac_f32_e32 v80, v81, v78
	v_fma_f32 v77, -v77, v80, v79
	v_div_fmas_f32 v77, v77, v78, v80
	v_div_fixup_f32 v77, v77, v76, 1.0
	v_mul_f32_e32 v62, v62, v77
	v_cvt_pk_bf16_f32 v62, v62, v62
	global_store_short v[72:73], v62, off
	v_div_scale_f32 v79, vcc, 1.0, v82, 1.0
	v_fma_f32 v80, -v83, v84, 1.0
	v_fmac_f32_e32 v84, v80, v84
	v_mul_f32_e32 v80, v79, v84
	v_fma_f32 v81, -v83, v80, v79
	v_fmac_f32_e32 v80, v81, v84
	v_fma_f32 v83, -v83, v80, v79
	v_div_fmas_f32 v83, v83, v84, v80
	v_div_fixup_f32 v83, v83, v82, 1.0
	v_mul_f32_e32 v46, v46, v83
	v_cvt_pk_bf16_f32 v46, v46, v46
	global_store_short v[72:73], v46, off offset:64
	v_mul_f32_e32 v76, 0xbfb8aa3b, v63
	v_mul_f32_e32 v82, 0xbfb8aa3b, v47
	v_exp_f32_e32 v76, v76
	v_exp_f32_e32 v82, v82
	v_add_f32_e32 v76, 1.0, v76
	v_add_f32_e32 v82, 1.0, v82
	v_div_scale_f32 v77, s[0:1], v76, v76, 1.0
	v_div_scale_f32 v83, s[0:1], v82, v82, 1.0
	v_rcp_f32_e32 v78, v77
	v_rcp_f32_e32 v84, v83
	v_div_scale_f32 v79, vcc, 1.0, v76, 1.0
	v_fma_f32 v80, -v77, v78, 1.0
	v_fmac_f32_e32 v78, v80, v78
	v_mul_f32_e32 v80, v79, v78
	v_fma_f32 v81, -v77, v80, v79
	v_fmac_f32_e32 v80, v81, v78
	v_fma_f32 v77, -v77, v80, v79
	v_div_fmas_f32 v77, v77, v78, v80
	v_div_fixup_f32 v77, v77, v76, 1.0
	v_mul_f32_e32 v63, v63, v77
	v_cvt_pk_bf16_f32 v63, v63, v63
	global_store_short v[74:75], v63, off
	v_div_scale_f32 v79, vcc, 1.0, v82, 1.0
	v_fma_f32 v80, -v83, v84, 1.0
	v_fmac_f32_e32 v84, v80, v84
	v_mul_f32_e32 v80, v79, v84
	v_fma_f32 v81, -v83, v80, v79
	v_fmac_f32_e32 v80, v81, v84
	v_fma_f32 v83, -v83, v80, v79
	v_div_fmas_f32 v83, v83, v84, v80
	v_div_fixup_f32 v83, v83, v82, 1.0
	v_mul_f32_e32 v47, v47, v83
	v_cvt_pk_bf16_f32 v47, v47, v47
	global_store_short v[74:75], v47, off offset:64
	s_mov_b64 s[0:1], 0x50000
	v_lshl_add_u64 v[68:69], v[66:67], 0, s[0:1]
	v_lshl_add_u64 v[70:71], v[68:69], 0, s[14:15]
	v_lshl_add_u64 v[72:73], v[70:71], 0, s[14:15]
	v_lshl_add_u64 v[74:75], v[72:73], 0, s[14:15]
	v_mul_f32_e32 v76, 0xbfb8aa3b, v0
	v_mul_f32_e32 v82, 0xbfb8aa3b, v16
	v_exp_f32_e32 v76, v76
	v_exp_f32_e32 v82, v82
	v_add_f32_e32 v76, 1.0, v76
	v_add_f32_e32 v82, 1.0, v82
	v_div_scale_f32 v77, s[0:1], v76, v76, 1.0
	v_div_scale_f32 v83, s[0:1], v82, v82, 1.0
	v_rcp_f32_e32 v78, v77
	v_rcp_f32_e32 v84, v83
	v_div_scale_f32 v79, vcc, 1.0, v76, 1.0
	v_fma_f32 v80, -v77, v78, 1.0
	v_fmac_f32_e32 v78, v80, v78
	v_mul_f32_e32 v80, v79, v78
	v_fma_f32 v81, -v77, v80, v79
	v_fmac_f32_e32 v80, v81, v78
	v_fma_f32 v77, -v77, v80, v79
	v_div_fmas_f32 v77, v77, v78, v80
	v_div_fixup_f32 v77, v77, v76, 1.0
	v_mul_f32_e32 v0, v0, v77
	v_cvt_pk_bf16_f32 v0, v0, v0
	global_store_short v[68:69], v0, off
	v_div_scale_f32 v79, vcc, 1.0, v82, 1.0
	v_fma_f32 v80, -v83, v84, 1.0
	v_fmac_f32_e32 v84, v80, v84
	v_mul_f32_e32 v80, v79, v84
	v_fma_f32 v81, -v83, v80, v79
	v_fmac_f32_e32 v80, v81, v84
	v_fma_f32 v83, -v83, v80, v79
	v_div_fmas_f32 v83, v83, v84, v80
	v_div_fixup_f32 v83, v83, v82, 1.0
	v_mul_f32_e32 v16, v16, v83
	v_cvt_pk_bf16_f32 v16, v16, v16
	global_store_short v[68:69], v16, off offset:64
	v_mul_f32_e32 v76, 0xbfb8aa3b, v1
	v_mul_f32_e32 v82, 0xbfb8aa3b, v17
	v_exp_f32_e32 v76, v76
	v_exp_f32_e32 v82, v82
	v_add_f32_e32 v76, 1.0, v76
	v_add_f32_e32 v82, 1.0, v82
	v_div_scale_f32 v77, s[0:1], v76, v76, 1.0
	v_div_scale_f32 v83, s[0:1], v82, v82, 1.0
	v_rcp_f32_e32 v78, v77
	v_rcp_f32_e32 v84, v83
	v_div_scale_f32 v79, vcc, 1.0, v76, 1.0
	v_fma_f32 v80, -v77, v78, 1.0
	v_fmac_f32_e32 v78, v80, v78
	v_mul_f32_e32 v80, v79, v78
; DI bf16_t f2bf(float x) { return (bf16_t)(pk_bf16(x, 0.f) & 0xffffu); }
; DI int crow(int r, int h) { return (r & 3) + 8 * (r >> 2) + 4 * h; }
; DI float sigmoidf_(float x) { return 1.f / (1.f + __expf(-x)); }
; DI void phase_gemm1(const Params& p, int g, char* smem, int bid, int nb) {
;     ...
;           for (int r = 0; r < 16; ++r) {
;             float v = acc[mi][ni][r];
;             if (mode == 1) v = v * sigmoidf_(v); else if (mode == 2) v = sigmoidf_(v);
;             projt[(wm * 64 + mi * 32 + crow(r, h)) * NPROJ + coff + wn * 64 + ni * 32 + l31] = f2bf(v);
	v_fma_f32 v81, -v77, v80, v79
	v_fmac_f32_e32 v80, v81, v78
	v_fma_f32 v77, -v77, v80, v79
	v_div_fmas_f32 v77, v77, v78, v80
	v_div_fixup_f32 v77, v77, v76, 1.0
	v_mul_f32_e32 v1, v1, v77
	v_cvt_pk_bf16_f32 v1, v1, v1
	global_store_short v[70:71], v1, off
	v_div_scale_f32 v79, vcc, 1.0, v82, 1.0
	v_fma_f32 v80, -v83, v84, 1.0
	v_fmac_f32_e32 v84, v80, v84
	v_mul_f32_e32 v80, v79, v84
	v_fma_f32 v81, -v83, v80, v79
	v_fmac_f32_e32 v80, v81, v84
	v_fma_f32 v83, -v83, v80, v79
	v_div_fmas_f32 v83, v83, v84, v80
	v_div_fixup_f32 v83, v83, v82, 1.0
	v_mul_f32_e32 v17, v17, v83
	v_cvt_pk_bf16_f32 v17, v17, v17
	global_store_short v[70:71], v17, off offset:64
	v_mul_f32_e32 v76, 0xbfb8aa3b, v2
	v_mul_f32_e32 v82, 0xbfb8aa3b, v18
	v_exp_f32_e32 v76, v76
	v_exp_f32_e32 v82, v82
	v_add_f32_e32 v76, 1.0, v76
	v_add_f32_e32 v82, 1.0, v82
	v_div_scale_f32 v77, s[0:1], v76, v76, 1.0
	v_div_scale_f32 v83, s[0:1], v82, v82, 1.0
	v_rcp_f32_e32 v78, v77
	v_rcp_f32_e32 v84, v83
	v_div_scale_f32 v79, vcc, 1.0, v76, 1.0
	v_fma_f32 v80, -v77, v78, 1.0
	v_fmac_f32_e32 v78, v80, v78
	v_mul_f32_e32 v80, v79, v78
	v_fma_f32 v81, -v77, v80, v79
	v_fmac_f32_e32 v80, v81, v78
	v_fma_f32 v77, -v77, v80, v79
	v_div_fmas_f32 v77, v77, v78, v80
	v_div_fixup_f32 v77, v77, v76, 1.0
	v_mul_f32_e32 v2, v2, v77
	v_cvt_pk_bf16_f32 v2, v2, v2
	global_store_short v[72:73], v2, off
	v_div_scale_f32 v79, vcc, 1.0, v82, 1.0
	v_fma_f32 v80, -v83, v84, 1.0
	v_fmac_f32_e32 v84, v80, v84
	v_mul_f32_e32 v80, v79, v84
	v_fma_f32 v81, -v83, v80, v79
	v_fmac_f32_e32 v80, v81, v84
	v_fma_f32 v83, -v83, v80, v79
	v_div_fmas_f32 v83, v83, v84, v80
	v_div_fixup_f32 v83, v83, v82, 1.0
	v_mul_f32_e32 v18, v18, v83
	v_cvt_pk_bf16_f32 v18, v18, v18
	global_store_short v[72:73], v18, off offset:64
	v_mul_f32_e32 v76, 0xbfb8aa3b, v3
	v_mul_f32_e32 v82, 0xbfb8aa3b, v19
	v_exp_f32_e32 v76, v76
	v_exp_f32_e32 v82, v82
	v_add_f32_e32 v76, 1.0, v76
	v_add_f32_e32 v82, 1.0, v82
	v_div_scale_f32 v77, s[0:1], v76, v76, 1.0
	v_div_scale_f32 v83, s[0:1], v82, v82, 1.0
	v_rcp_f32_e32 v78, v77
	v_rcp_f32_e32 v84, v83
	v_div_scale_f32 v79, vcc, 1.0, v76, 1.0
	v_fma_f32 v80, -v77, v78, 1.0
	v_fmac_f32_e32 v78, v80, v78
	v_mul_f32_e32 v80, v79, v78
	v_fma_f32 v81, -v77, v80, v79
	v_fmac_f32_e32 v80, v81, v78
	v_fma_f32 v77, -v77, v80, v79
	v_div_fmas_f32 v77, v77, v78, v80
	v_div_fixup_f32 v77, v77, v76, 1.0
	v_mul_f32_e32 v3, v3, v77
	v_cvt_pk_bf16_f32 v3, v3, v3
	global_store_short v[74:75], v3, off
	v_div_scale_f32 v79, vcc, 1.0, v82, 1.0
	v_fma_f32 v80, -v83, v84, 1.0
	v_fmac_f32_e32 v84, v80, v84
	v_mul_f32_e32 v80, v79, v84
	v_fma_f32 v81, -v83, v80, v79
	v_fmac_f32_e32 v80, v81, v84
	v_fma_f32 v83, -v83, v80, v79
	v_div_fmas_f32 v83, v83, v84, v80
	v_div_fixup_f32 v83, v83, v82, 1.0
	v_mul_f32_e32 v19, v19, v83
	v_cvt_pk_bf16_f32 v19, v19, v19
	global_store_short v[74:75], v19, off offset:64
	s_mov_b64 s[0:1], 0x64000
	v_lshl_add_u64 v[68:69], v[66:67], 0, s[0:1]
	v_lshl_add_u64 v[70:71], v[68:69], 0, s[14:15]
	v_lshl_add_u64 v[72:73], v[70:71], 0, s[14:15]
	v_lshl_add_u64 v[74:75], v[72:73], 0, s[14:15]
	v_mul_f32_e32 v76, 0xbfb8aa3b, v4
	v_mul_f32_e32 v82, 0xbfb8aa3b, v20
	v_exp_f32_e32 v76, v76
	v_exp_f32_e32 v82, v82
	v_add_f32_e32 v76, 1.0, v76
	v_add_f32_e32 v82, 1.0, v82
	v_div_scale_f32 v77, s[0:1], v76, v76, 1.0
	v_div_scale_f32 v83, s[0:1], v82, v82, 1.0
	v_rcp_f32_e32 v78, v77
	v_rcp_f32_e32 v84, v83
	v_div_scale_f32 v79, vcc, 1.0, v76, 1.0
	v_fma_f32 v80, -v77, v78, 1.0
	v_fmac_f32_e32 v78, v80, v78
	v_mul_f32_e32 v80, v79, v78
	v_fma_f32 v81, -v77, v80, v79
	v_fmac_f32_e32 v80, v81, v78
	v_fma_f32 v77, -v77, v80, v79
	v_div_fmas_f32 v77, v77, v78, v80
	v_div_fixup_f32 v77, v77, v76, 1.0
	v_mul_f32_e32 v4, v4, v77
	v_cvt_pk_bf16_f32 v4, v4, v4
	global_store_short v[68:69], v4, off
	v_div_scale_f32 v79, vcc, 1.0, v82, 1.0
	v_fma_f32 v80, -v83, v84, 1.0
	v_fmac_f32_e32 v84, v80, v84
	v_mul_f32_e32 v80, v79, v84
	v_fma_f32 v81, -v83, v80, v79
	v_fmac_f32_e32 v80, v81, v84
	v_fma_f32 v83, -v83, v80, v79
	v_div_fmas_f32 v83, v83, v84, v80
	v_div_fixup_f32 v83, v83, v82, 1.0
	v_mul_f32_e32 v20, v20, v83
	v_cvt_pk_bf16_f32 v20, v20, v20
	global_store_short v[68:69], v20, off offset:64
	v_mul_f32_e32 v76, 0xbfb8aa3b, v5
	v_mul_f32_e32 v82, 0xbfb8aa3b, v21
	v_exp_f32_e32 v76, v76
	v_exp_f32_e32 v82, v82
	v_add_f32_e32 v76, 1.0, v76
	v_add_f32_e32 v82, 1.0, v82
	v_div_scale_f32 v77, s[0:1], v76, v76, 1.0
	v_div_scale_f32 v83, s[0:1], v82, v82, 1.0
	v_rcp_f32_e32 v78, v77
	v_rcp_f32_e32 v84, v83
	v_div_scale_f32 v79, vcc, 1.0, v76, 1.0
	v_fma_f32 v80, -v77, v78, 1.0
	v_fmac_f32_e32 v78, v80, v78
	v_mul_f32_e32 v80, v79, v78
	v_fma_f32 v81, -v77, v80, v79
	v_fmac_f32_e32 v80, v81, v78
	v_fma_f32 v77, -v77, v80, v79
	v_div_fmas_f32 v77, v77, v78, v80
	v_div_fixup_f32 v77, v77, v76, 1.0
	v_mul_f32_e32 v5, v5, v77
	v_cvt_pk_bf16_f32 v5, v5, v5
	global_store_short v[70:71], v5, off
	v_div_scale_f32 v79, vcc, 1.0, v82, 1.0
	v_fma_f32 v80, -v83, v84, 1.0
	v_fmac_f32_e32 v84, v80, v84
	v_mul_f32_e32 v80, v79, v84
	v_fma_f32 v81, -v83, v80, v79
	v_fmac_f32_e32 v80, v81, v84
	v_fma_f32 v83, -v83, v80, v79
	v_div_fmas_f32 v83, v83, v84, v80
	v_div_fixup_f32 v83, v83, v82, 1.0
	v_mul_f32_e32 v21, v21, v83
	v_cvt_pk_bf16_f32 v21, v21, v21
	global_store_short v[70:71], v21, off offset:64
	v_mul_f32_e32 v76, 0xbfb8aa3b, v6
	v_mul_f32_e32 v82, 0xbfb8aa3b, v22
	v_exp_f32_e32 v76, v76
	v_exp_f32_e32 v82, v82
	v_add_f32_e32 v76, 1.0, v76
	v_add_f32_e32 v82, 1.0, v82
	v_div_scale_f32 v77, s[0:1], v76, v76, 1.0
	v_div_scale_f32 v83, s[0:1], v82, v82, 1.0
	v_rcp_f32_e32 v78, v77
	v_rcp_f32_e32 v84, v83
; DI bf16_t f2bf(float x) { return (bf16_t)(pk_bf16(x, 0.f) & 0xffffu); }
; DI int crow(int r, int h) { return (r & 3) + 8 * (r >> 2) + 4 * h; }
; DI float sigmoidf_(float x) { return 1.f / (1.f + __expf(-x)); }
; DI void phase_gemm1(const Params& p, int g, char* smem, int bid, int nb) {
;     ...
;           for (int r = 0; r < 16; ++r) {
;             float v = acc[mi][ni][r];
;             if (mode == 1) v = v * sigmoidf_(v); else if (mode == 2) v = sigmoidf_(v);
;             projt[(wm * 64 + mi * 32 + crow(r, h)) * NPROJ + coff + wn * 64 + ni * 32 + l31] = f2bf(v);
	v_div_scale_f32 v79, vcc, 1.0, v76, 1.0
	v_fma_f32 v80, -v77, v78, 1.0
	v_fmac_f32_e32 v78, v80, v78
	v_mul_f32_e32 v80, v79, v78
	v_fma_f32 v81, -v77, v80, v79
	v_fmac_f32_e32 v80, v81, v78
	v_fma_f32 v77, -v77, v80, v79
	v_div_fmas_f32 v77, v77, v78, v80
	v_div_fixup_f32 v77, v77, v76, 1.0
	v_mul_f32_e32 v6, v6, v77
	v_cvt_pk_bf16_f32 v6, v6, v6
	global_store_short v[72:73], v6, off
	v_div_scale_f32 v79, vcc, 1.0, v82, 1.0
	v_fma_f32 v80, -v83, v84, 1.0
	v_fmac_f32_e32 v84, v80, v84
	v_mul_f32_e32 v80, v79, v84
	v_fma_f32 v81, -v83, v80, v79
	v_fmac_f32_e32 v80, v81, v84
	v_fma_f32 v83, -v83, v80, v79
	v_div_fmas_f32 v83, v83, v84, v80
	v_div_fixup_f32 v83, v83, v82, 1.0
	v_mul_f32_e32 v22, v22, v83
	v_cvt_pk_bf16_f32 v22, v22, v22
	global_store_short v[72:73], v22, off offset:64
	v_mul_f32_e32 v76, 0xbfb8aa3b, v7
	v_mul_f32_e32 v82, 0xbfb8aa3b, v23
	v_exp_f32_e32 v76, v76
	v_exp_f32_e32 v82, v82
	v_add_f32_e32 v76, 1.0, v76
	v_add_f32_e32 v82, 1.0, v82
	v_div_scale_f32 v77, s[0:1], v76, v76, 1.0
	v_div_scale_f32 v83, s[0:1], v82, v82, 1.0
	v_rcp_f32_e32 v78, v77
	v_rcp_f32_e32 v84, v83
	v_div_scale_f32 v79, vcc, 1.0, v76, 1.0
	v_fma_f32 v80, -v77, v78, 1.0
	v_fmac_f32_e32 v78, v80, v78
	v_mul_f32_e32 v80, v79, v78
	v_fma_f32 v81, -v77, v80, v79
	v_fmac_f32_e32 v80, v81, v78
	v_fma_f32 v77, -v77, v80, v79
	v_div_fmas_f32 v77, v77, v78, v80
	v_div_fixup_f32 v77, v77, v76, 1.0
	v_mul_f32_e32 v7, v7, v77
	v_cvt_pk_bf16_f32 v7, v7, v7
	global_store_short v[74:75], v7, off
	v_div_scale_f32 v79, vcc, 1.0, v82, 1.0
	v_fma_f32 v80, -v83, v84, 1.0
	v_fmac_f32_e32 v84, v80, v84
	v_mul_f32_e32 v80, v79, v84
	v_fma_f32 v81, -v83, v80, v79
	v_fmac_f32_e32 v80, v81, v84
	v_fma_f32 v83, -v83, v80, v79
	v_div_fmas_f32 v83, v83, v84, v80
	v_div_fixup_f32 v83, v83, v82, 1.0
	v_mul_f32_e32 v23, v23, v83
	v_cvt_pk_bf16_f32 v23, v23, v23
	global_store_short v[74:75], v23, off offset:64
	s_mov_b64 s[0:1], 0x78000
	v_lshl_add_u64 v[68:69], v[66:67], 0, s[0:1]
	v_lshl_add_u64 v[70:71], v[68:69], 0, s[14:15]
	v_lshl_add_u64 v[72:73], v[70:71], 0, s[14:15]
	v_lshl_add_u64 v[74:75], v[72:73], 0, s[14:15]
	v_mul_f32_e32 v76, 0xbfb8aa3b, v8
	v_mul_f32_e32 v82, 0xbfb8aa3b, v24
	v_exp_f32_e32 v76, v76
	v_exp_f32_e32 v82, v82
	v_add_f32_e32 v76, 1.0, v76
	v_add_f32_e32 v82, 1.0, v82
	v_div_scale_f32 v77, s[0:1], v76, v76, 1.0
	v_div_scale_f32 v83, s[0:1], v82, v82, 1.0
	v_rcp_f32_e32 v78, v77
	v_rcp_f32_e32 v84, v83
	v_div_scale_f32 v79, vcc, 1.0, v76, 1.0
	v_fma_f32 v80, -v77, v78, 1.0
	v_fmac_f32_e32 v78, v80, v78
	v_mul_f32_e32 v80, v79, v78
	v_fma_f32 v81, -v77, v80, v79
	v_fmac_f32_e32 v80, v81, v78
	v_fma_f32 v77, -v77, v80, v79
	v_div_fmas_f32 v77, v77, v78, v80
	v_div_fixup_f32 v77, v77, v76, 1.0
	v_mul_f32_e32 v8, v8, v77
	v_cvt_pk_bf16_f32 v8, v8, v8
	global_store_short v[68:69], v8, off
	v_div_scale_f32 v79, vcc, 1.0, v82, 1.0
	v_fma_f32 v80, -v83, v84, 1.0
	v_fmac_f32_e32 v84, v80, v84
	v_mul_f32_e32 v80, v79, v84
	v_fma_f32 v81, -v83, v80, v79
	v_fmac_f32_e32 v80, v81, v84
	v_fma_f32 v83, -v83, v80, v79
	v_div_fmas_f32 v83, v83, v84, v80
	v_div_fixup_f32 v83, v83, v82, 1.0
	v_mul_f32_e32 v24, v24, v83
	v_cvt_pk_bf16_f32 v24, v24, v24
	global_store_short v[68:69], v24, off offset:64
	v_mul_f32_e32 v76, 0xbfb8aa3b, v9
	v_mul_f32_e32 v82, 0xbfb8aa3b, v25
	v_exp_f32_e32 v76, v76
	v_exp_f32_e32 v82, v82
	v_add_f32_e32 v76, 1.0, v76
	v_add_f32_e32 v82, 1.0, v82
	v_div_scale_f32 v77, s[0:1], v76, v76, 1.0
	v_div_scale_f32 v83, s[0:1], v82, v82, 1.0
	v_rcp_f32_e32 v78, v77
	v_rcp_f32_e32 v84, v83
	v_div_scale_f32 v79, vcc, 1.0, v76, 1.0
	v_fma_f32 v80, -v77, v78, 1.0
	v_fmac_f32_e32 v78, v80, v78
	v_mul_f32_e32 v80, v79, v78
	v_fma_f32 v81, -v77, v80, v79
	v_fmac_f32_e32 v80, v81, v78
	v_fma_f32 v77, -v77, v80, v79
	v_div_fmas_f32 v77, v77, v78, v80
	v_div_fixup_f32 v77, v77, v76, 1.0
	v_mul_f32_e32 v9, v9, v77
	v_cvt_pk_bf16_f32 v9, v9, v9
	global_store_short v[70:71], v9, off
	v_div_scale_f32 v79, vcc, 1.0, v82, 1.0
	v_fma_f32 v80, -v83, v84, 1.0
	v_fmac_f32_e32 v84, v80, v84
	v_mul_f32_e32 v80, v79, v84
	v_fma_f32 v81, -v83, v80, v79
	v_fmac_f32_e32 v80, v81, v84
	v_fma_f32 v83, -v83, v80, v79
	v_div_fmas_f32 v83, v83, v84, v80
	v_div_fixup_f32 v83, v83, v82, 1.0
	v_mul_f32_e32 v25, v25, v83
	v_cvt_pk_bf16_f32 v25, v25, v25
	global_store_short v[70:71], v25, off offset:64
	v_mul_f32_e32 v76, 0xbfb8aa3b, v10
	v_mul_f32_e32 v82, 0xbfb8aa3b, v26
	v_exp_f32_e32 v76, v76
	v_exp_f32_e32 v82, v82
	v_add_f32_e32 v76, 1.0, v76
	v_add_f32_e32 v82, 1.0, v82
	v_div_scale_f32 v77, s[0:1], v76, v76, 1.0
	v_div_scale_f32 v83, s[0:1], v82, v82, 1.0
	v_rcp_f32_e32 v78, v77
	v_rcp_f32_e32 v84, v83
	v_div_scale_f32 v79, vcc, 1.0, v76, 1.0
	v_fma_f32 v80, -v77, v78, 1.0
	v_fmac_f32_e32 v78, v80, v78
	v_mul_f32_e32 v80, v79, v78
	v_fma_f32 v81, -v77, v80, v79
	v_fmac_f32_e32 v80, v81, v78
	v_fma_f32 v77, -v77, v80, v79
	v_div_fmas_f32 v77, v77, v78, v80
	v_div_fixup_f32 v77, v77, v76, 1.0
	v_mul_f32_e32 v10, v10, v77
	v_cvt_pk_bf16_f32 v10, v10, v10
	global_store_short v[72:73], v10, off
	v_div_scale_f32 v79, vcc, 1.0, v82, 1.0
	v_fma_f32 v80, -v83, v84, 1.0
	v_fmac_f32_e32 v84, v80, v84
	v_mul_f32_e32 v80, v79, v84
	v_fma_f32 v81, -v83, v80, v79
	v_fmac_f32_e32 v80, v81, v84
	v_fma_f32 v83, -v83, v80, v79
	v_div_fmas_f32 v83, v83, v84, v80
	v_div_fixup_f32 v83, v83, v82, 1.0
	v_mul_f32_e32 v26, v26, v83
	v_cvt_pk_bf16_f32 v26, v26, v26
	global_store_short v[72:73], v26, off offset:64
	v_mul_f32_e32 v76, 0xbfb8aa3b, v11
	v_mul_f32_e32 v82, 0xbfb8aa3b, v27
	v_exp_f32_e32 v76, v76
	v_exp_f32_e32 v82, v82
	v_add_f32_e32 v76, 1.0, v76
	v_add_f32_e32 v82, 1.0, v82
; DI bf16_t f2bf(float x) { return (bf16_t)(pk_bf16(x, 0.f) & 0xffffu); }
; DI int crow(int r, int h) { return (r & 3) + 8 * (r >> 2) + 4 * h; }
; DI float sigmoidf_(float x) { return 1.f / (1.f + __expf(-x)); }
; DI void phase_gemm1(const Params& p, int g, char* smem, int bid, int nb) {
;     ...
;           for (int r = 0; r < 16; ++r) {
;             float v = acc[mi][ni][r];
;             if (mode == 1) v = v * sigmoidf_(v); else if (mode == 2) v = sigmoidf_(v);
;             projt[(wm * 64 + mi * 32 + crow(r, h)) * NPROJ + coff + wn * 64 + ni * 32 + l31] = f2bf(v);
	v_div_scale_f32 v77, s[0:1], v76, v76, 1.0
	v_div_scale_f32 v83, s[0:1], v82, v82, 1.0
	v_rcp_f32_e32 v78, v77
	v_rcp_f32_e32 v84, v83
	v_div_scale_f32 v79, vcc, 1.0, v76, 1.0
	v_fma_f32 v80, -v77, v78, 1.0
	v_fmac_f32_e32 v78, v80, v78
	v_mul_f32_e32 v80, v79, v78
	v_fma_f32 v81, -v77, v80, v79
	v_fmac_f32_e32 v80, v81, v78
	v_fma_f32 v77, -v77, v80, v79
	v_div_fmas_f32 v77, v77, v78, v80
	v_div_fixup_f32 v77, v77, v76, 1.0
	v_mul_f32_e32 v11, v11, v77
	v_cvt_pk_bf16_f32 v11, v11, v11
	global_store_short v[74:75], v11, off
	v_div_scale_f32 v79, vcc, 1.0, v82, 1.0
	v_fma_f32 v80, -v83, v84, 1.0
	v_fmac_f32_e32 v84, v80, v84
	v_mul_f32_e32 v80, v79, v84
	v_fma_f32 v81, -v83, v80, v79
	v_fmac_f32_e32 v80, v81, v84
	v_fma_f32 v83, -v83, v80, v79
	v_div_fmas_f32 v83, v83, v84, v80
	v_div_fixup_f32 v83, v83, v82, 1.0
	v_mul_f32_e32 v27, v27, v83
	v_cvt_pk_bf16_f32 v27, v27, v27
	global_store_short v[74:75], v27, off offset:64
	s_mov_b64 s[0:1], 0x8c000
	v_lshl_add_u64 v[68:69], v[66:67], 0, s[0:1]
	v_lshl_add_u64 v[70:71], v[68:69], 0, s[14:15]
	v_lshl_add_u64 v[72:73], v[70:71], 0, s[14:15]
	v_lshl_add_u64 v[74:75], v[72:73], 0, s[14:15]
	v_mul_f32_e32 v76, 0xbfb8aa3b, v12
	v_mul_f32_e32 v82, 0xbfb8aa3b, v28
	v_exp_f32_e32 v76, v76
	v_exp_f32_e32 v82, v82
	v_add_f32_e32 v76, 1.0, v76
	v_add_f32_e32 v82, 1.0, v82
	v_div_scale_f32 v77, s[0:1], v76, v76, 1.0
	v_div_scale_f32 v83, s[0:1], v82, v82, 1.0
	v_rcp_f32_e32 v78, v77
	v_rcp_f32_e32 v84, v83
	v_div_scale_f32 v79, vcc, 1.0, v76, 1.0
	v_fma_f32 v80, -v77, v78, 1.0
	v_fmac_f32_e32 v78, v80, v78
	v_mul_f32_e32 v80, v79, v78
	v_fma_f32 v81, -v77, v80, v79
	v_fmac_f32_e32 v80, v81, v78
	v_fma_f32 v77, -v77, v80, v79
	v_div_fmas_f32 v77, v77, v78, v80
	v_div_fixup_f32 v77, v77, v76, 1.0
	v_mul_f32_e32 v12, v12, v77
	v_cvt_pk_bf16_f32 v12, v12, v12
	global_store_short v[68:69], v12, off
	v_div_scale_f32 v79, vcc, 1.0, v82, 1.0
	v_fma_f32 v80, -v83, v84, 1.0
	v_fmac_f32_e32 v84, v80, v84
	v_mul_f32_e32 v80, v79, v84
	v_fma_f32 v81, -v83, v80, v79
	v_fmac_f32_e32 v80, v81, v84
	v_fma_f32 v83, -v83, v80, v79
	v_div_fmas_f32 v83, v83, v84, v80
	v_div_fixup_f32 v83, v83, v82, 1.0
	v_mul_f32_e32 v28, v28, v83
	v_cvt_pk_bf16_f32 v28, v28, v28
	global_store_short v[68:69], v28, off offset:64
	v_mul_f32_e32 v76, 0xbfb8aa3b, v13
	v_mul_f32_e32 v82, 0xbfb8aa3b, v29
	v_exp_f32_e32 v76, v76
	v_exp_f32_e32 v82, v82
	v_add_f32_e32 v76, 1.0, v76
	v_add_f32_e32 v82, 1.0, v82
	v_div_scale_f32 v77, s[0:1], v76, v76, 1.0
	v_div_scale_f32 v83, s[0:1], v82, v82, 1.0
	v_rcp_f32_e32 v78, v77
	v_rcp_f32_e32 v84, v83
	v_div_scale_f32 v79, vcc, 1.0, v76, 1.0
	v_fma_f32 v80, -v77, v78, 1.0
	v_fmac_f32_e32 v78, v80, v78
	v_mul_f32_e32 v80, v79, v78
	v_fma_f32 v81, -v77, v80, v79
	v_fmac_f32_e32 v80, v81, v78
	v_fma_f32 v77, -v77, v80, v79
	v_div_fmas_f32 v77, v77, v78, v80
	v_div_fixup_f32 v77, v77, v76, 1.0
	v_mul_f32_e32 v13, v13, v77
	v_cvt_pk_bf16_f32 v13, v13, v13
	global_store_short v[70:71], v13, off
	v_div_scale_f32 v79, vcc, 1.0, v82, 1.0
	v_fma_f32 v80, -v83, v84, 1.0
	v_fmac_f32_e32 v84, v80, v84
	v_mul_f32_e32 v80, v79, v84
	v_fma_f32 v81, -v83, v80, v79
	v_fmac_f32_e32 v80, v81, v84
	v_fma_f32 v83, -v83, v80, v79
	v_div_fmas_f32 v83, v83, v84, v80
	v_div_fixup_f32 v83, v83, v82, 1.0
	v_mul_f32_e32 v29, v29, v83
	v_cvt_pk_bf16_f32 v29, v29, v29
	global_store_short v[70:71], v29, off offset:64
	v_mul_f32_e32 v76, 0xbfb8aa3b, v14
	v_mul_f32_e32 v82, 0xbfb8aa3b, v30
	v_exp_f32_e32 v76, v76
	v_exp_f32_e32 v82, v82
	v_add_f32_e32 v76, 1.0, v76
	v_add_f32_e32 v82, 1.0, v82
	v_div_scale_f32 v77, s[0:1], v76, v76, 1.0
	v_div_scale_f32 v83, s[0:1], v82, v82, 1.0
	v_rcp_f32_e32 v78, v77
	v_rcp_f32_e32 v84, v83
	v_div_scale_f32 v79, vcc, 1.0, v76, 1.0
	v_fma_f32 v80, -v77, v78, 1.0
	v_fmac_f32_e32 v78, v80, v78
	v_mul_f32_e32 v80, v79, v78
	v_fma_f32 v81, -v77, v80, v79
	v_fmac_f32_e32 v80, v81, v78
	v_fma_f32 v77, -v77, v80, v79
	v_div_fmas_f32 v77, v77, v78, v80
	v_div_fixup_f32 v77, v77, v76, 1.0
	v_mul_f32_e32 v14, v14, v77
	v_cvt_pk_bf16_f32 v14, v14, v14
	global_store_short v[72:73], v14, off
	v_div_scale_f32 v79, vcc, 1.0, v82, 1.0
	v_fma_f32 v80, -v83, v84, 1.0
	v_fmac_f32_e32 v84, v80, v84
	v_mul_f32_e32 v80, v79, v84
	v_fma_f32 v81, -v83, v80, v79
	v_fmac_f32_e32 v80, v81, v84
	v_fma_f32 v83, -v83, v80, v79
	v_div_fmas_f32 v83, v83, v84, v80
	v_div_fixup_f32 v83, v83, v82, 1.0
	v_mul_f32_e32 v30, v30, v83
	v_cvt_pk_bf16_f32 v30, v30, v30
	global_store_short v[72:73], v30, off offset:64
	v_mul_f32_e32 v76, 0xbfb8aa3b, v15
	v_mul_f32_e32 v82, 0xbfb8aa3b, v31
	v_exp_f32_e32 v76, v76
	v_exp_f32_e32 v82, v82
	v_add_f32_e32 v76, 1.0, v76
	v_add_f32_e32 v82, 1.0, v82
	v_div_scale_f32 v77, s[0:1], v76, v76, 1.0
	v_div_scale_f32 v83, s[0:1], v82, v82, 1.0
	v_rcp_f32_e32 v78, v77
	v_rcp_f32_e32 v84, v83
	v_div_scale_f32 v79, vcc, 1.0, v76, 1.0
	v_fma_f32 v80, -v77, v78, 1.0
	v_fmac_f32_e32 v78, v80, v78
	v_mul_f32_e32 v80, v79, v78
	v_fma_f32 v81, -v77, v80, v79
	v_fmac_f32_e32 v80, v81, v78
	v_fma_f32 v77, -v77, v80, v79
	v_div_fmas_f32 v77, v77, v78, v80
	v_div_fixup_f32 v77, v77, v76, 1.0
	v_mul_f32_e32 v15, v15, v77
	v_cvt_pk_bf16_f32 v15, v15, v15
	global_store_short v[74:75], v15, off
	v_div_scale_f32 v79, vcc, 1.0, v82, 1.0
	v_fma_f32 v80, -v83, v84, 1.0
	v_fmac_f32_e32 v84, v80, v84
	v_mul_f32_e32 v80, v79, v84
	v_fma_f32 v81, -v83, v80, v79
	v_fmac_f32_e32 v80, v81, v84
	v_fma_f32 v83, -v83, v80, v79
	v_div_fmas_f32 v83, v83, v84, v80
	v_div_fixup_f32 v83, v83, v82, 1.0
	v_mul_f32_e32 v31, v31, v83
	v_cvt_pk_bf16_f32 v31, v31, v31
	global_store_short v[74:75], v31, off offset:64
	s_branch .Lep2_done
; DI int crow(int r, int h) { return (r & 3) + 8 * (r >> 2) + 4 * h; }
; DI float sigmoidf_(float x) { return 1.f / (1.f + __expf(-x)); }
; DI unsigned pk_bf16(float lo, float hi) { f32x2 v = {lo, hi}; bf16v2 b = __builtin_convertvector(v, bf16v2); return __builtin_bit_cast(unsigned, b); }
; DI bf16_t f2bf(float x) { return (bf16_t)(pk_bf16(x, 0.f) & 0xffffu); }
; DI void phase_gemm1(const Params& p, int g, char* smem, int bid, int nb) {
;     ...
; #pragma unroll
;       for (int mi = 0; mi < 2; ++mi)
; #pragma unroll
;         for (int ni = 0; ni < 2; ++ni)
; #pragma unroll
;           for (int r = 0; r < 16; ++r) {
;             float v = acc[mi][ni][r];
;             if (mode == 1) v = v * sigmoidf_(v); else if (mode == 2) v = sigmoidf_(v);
;             projt[(wm * 64 + mi * 32 + crow(r, h)) * NPROJ + coff + wn * 64 + ni * 32 + l31] = f2bf(v);
.Lep2_t0:
	v_lshl_add_u64 v[70:71], v[66:67], 0, s[14:15]
	v_lshl_add_u64 v[72:73], v[70:71], 0, s[14:15]
	v_lshl_add_u64 v[74:75], v[72:73], 0, s[14:15]
	v_cvt_pk_bf16_f32 v48, v48, v48
	v_cvt_pk_bf16_f32 v32, v32, v32
	global_store_short v[66:67], v48, off
	global_store_short v[66:67], v32, off offset:64
	v_cvt_pk_bf16_f32 v49, v49, v49
	v_cvt_pk_bf16_f32 v33, v33, v33
	global_store_short v[70:71], v49, off
	global_store_short v[70:71], v33, off offset:64
	v_cvt_pk_bf16_f32 v50, v50, v50
	v_cvt_pk_bf16_f32 v34, v34, v34
	global_store_short v[72:73], v50, off
	global_store_short v[72:73], v34, off offset:64
	v_cvt_pk_bf16_f32 v51, v51, v51
	v_cvt_pk_bf16_f32 v35, v35, v35
	global_store_short v[74:75], v51, off
	global_store_short v[74:75], v35, off offset:64
	s_mov_b64 s[0:1], 0x14000
	v_lshl_add_u64 v[68:69], v[66:67], 0, s[0:1]
	v_lshl_add_u64 v[70:71], v[68:69], 0, s[14:15]
	v_lshl_add_u64 v[72:73], v[70:71], 0, s[14:15]
	v_lshl_add_u64 v[74:75], v[72:73], 0, s[14:15]
	v_cvt_pk_bf16_f32 v52, v52, v52
	v_cvt_pk_bf16_f32 v36, v36, v36
	global_store_short v[68:69], v52, off
	global_store_short v[68:69], v36, off offset:64
	v_cvt_pk_bf16_f32 v53, v53, v53
	v_cvt_pk_bf16_f32 v37, v37, v37
	global_store_short v[70:71], v53, off
	global_store_short v[70:71], v37, off offset:64
	v_cvt_pk_bf16_f32 v54, v54, v54
	v_cvt_pk_bf16_f32 v38, v38, v38
	global_store_short v[72:73], v54, off
	global_store_short v[72:73], v38, off offset:64
	v_cvt_pk_bf16_f32 v55, v55, v55
	v_cvt_pk_bf16_f32 v39, v39, v39
	global_store_short v[74:75], v55, off
	global_store_short v[74:75], v39, off offset:64
	s_mov_b64 s[0:1], 0x28000
	v_lshl_add_u64 v[68:69], v[66:67], 0, s[0:1]
	v_lshl_add_u64 v[70:71], v[68:69], 0, s[14:15]
	v_lshl_add_u64 v[72:73], v[70:71], 0, s[14:15]
	v_lshl_add_u64 v[74:75], v[72:73], 0, s[14:15]
	v_cvt_pk_bf16_f32 v56, v56, v56
	v_cvt_pk_bf16_f32 v40, v40, v40
	global_store_short v[68:69], v56, off
	global_store_short v[68:69], v40, off offset:64
	v_cvt_pk_bf16_f32 v57, v57, v57
	v_cvt_pk_bf16_f32 v41, v41, v41
	global_store_short v[70:71], v57, off
	global_store_short v[70:71], v41, off offset:64
	v_cvt_pk_bf16_f32 v58, v58, v58
	v_cvt_pk_bf16_f32 v42, v42, v42
	global_store_short v[72:73], v58, off
	global_store_short v[72:73], v42, off offset:64
	v_cvt_pk_bf16_f32 v59, v59, v59
	v_cvt_pk_bf16_f32 v43, v43, v43
	global_store_short v[74:75], v59, off
	global_store_short v[74:75], v43, off offset:64
	s_mov_b64 s[0:1], 0x3c000
	v_lshl_add_u64 v[68:69], v[66:67], 0, s[0:1]
	v_lshl_add_u64 v[70:71], v[68:69], 0, s[14:15]
	v_lshl_add_u64 v[72:73], v[70:71], 0, s[14:15]
	v_lshl_add_u64 v[74:75], v[72:73], 0, s[14:15]
	v_cvt_pk_bf16_f32 v60, v60, v60
	v_cvt_pk_bf16_f32 v44, v44, v44
	global_store_short v[68:69], v60, off
	global_store_short v[68:69], v44, off offset:64
	v_cvt_pk_bf16_f32 v61, v61, v61
	v_cvt_pk_bf16_f32 v45, v45, v45
	global_store_short v[70:71], v61, off
	global_store_short v[70:71], v45, off offset:64
	v_cvt_pk_bf16_f32 v62, v62, v62
	v_cvt_pk_bf16_f32 v46, v46, v46
	global_store_short v[72:73], v62, off
	global_store_short v[72:73], v46, off offset:64
	v_cvt_pk_bf16_f32 v63, v63, v63
	v_cvt_pk_bf16_f32 v47, v47, v47
	global_store_short v[74:75], v63, off
	global_store_short v[74:75], v47, off offset:64
	s_mov_b64 s[0:1], 0x50000
	v_lshl_add_u64 v[68:69], v[66:67], 0, s[0:1]
	v_lshl_add_u64 v[70:71], v[68:69], 0, s[14:15]
	v_lshl_add_u64 v[72:73], v[70:71], 0, s[14:15]
	v_lshl_add_u64 v[74:75], v[72:73], 0, s[14:15]
	v_cvt_pk_bf16_f32 v0, v0, v0
	v_cvt_pk_bf16_f32 v16, v16, v16
	global_store_short v[68:69], v0, off
	global_store_short v[68:69], v16, off offset:64
	v_cvt_pk_bf16_f32 v1, v1, v1
	v_cvt_pk_bf16_f32 v17, v17, v17
	global_store_short v[70:71], v1, off
	global_store_short v[70:71], v17, off offset:64
	v_cvt_pk_bf16_f32 v2, v2, v2
	v_cvt_pk_bf16_f32 v18, v18, v18
	global_store_short v[72:73], v2, off
	global_store_short v[72:73], v18, off offset:64
	v_cvt_pk_bf16_f32 v3, v3, v3
	v_cvt_pk_bf16_f32 v19, v19, v19
	global_store_short v[74:75], v3, off
	global_store_short v[74:75], v19, off offset:64
	s_mov_b64 s[0:1], 0x64000
	v_lshl_add_u64 v[68:69], v[66:67], 0, s[0:1]
	v_lshl_add_u64 v[70:71], v[68:69], 0, s[14:15]
	v_lshl_add_u64 v[72:73], v[70:71], 0, s[14:15]
	v_lshl_add_u64 v[74:75], v[72:73], 0, s[14:15]
	v_cvt_pk_bf16_f32 v4, v4, v4
	v_cvt_pk_bf16_f32 v20, v20, v20
	global_store_short v[68:69], v4, off
	global_store_short v[68:69], v20, off offset:64
	v_cvt_pk_bf16_f32 v5, v5, v5
	v_cvt_pk_bf16_f32 v21, v21, v21
	global_store_short v[70:71], v5, off
	global_store_short v[70:71], v21, off offset:64
	v_cvt_pk_bf16_f32 v6, v6, v6
	v_cvt_pk_bf16_f32 v22, v22, v22
	global_store_short v[72:73], v6, off
	global_store_short v[72:73], v22, off offset:64
	v_cvt_pk_bf16_f32 v7, v7, v7
	v_cvt_pk_bf16_f32 v23, v23, v23
	global_store_short v[74:75], v7, off
	global_store_short v[74:75], v23, off offset:64
	s_mov_b64 s[0:1], 0x78000
	v_lshl_add_u64 v[68:69], v[66:67], 0, s[0:1]
	v_lshl_add_u64 v[70:71], v[68:69], 0, s[14:15]
	v_lshl_add_u64 v[72:73], v[70:71], 0, s[14:15]
	v_lshl_add_u64 v[74:75], v[72:73], 0, s[14:15]
	v_cvt_pk_bf16_f32 v8, v8, v8
	v_cvt_pk_bf16_f32 v24, v24, v24
	global_store_short v[68:69], v8, off
	global_store_short v[68:69], v24, off offset:64
	v_cvt_pk_bf16_f32 v9, v9, v9
	v_cvt_pk_bf16_f32 v25, v25, v25
	global_store_short v[70:71], v9, off
	global_store_short v[70:71], v25, off offset:64
	v_cvt_pk_bf16_f32 v10, v10, v10
	v_cvt_pk_bf16_f32 v26, v26, v26
	global_store_short v[72:73], v10, off
	global_store_short v[72:73], v26, off offset:64
	v_cvt_pk_bf16_f32 v11, v11, v11
	v_cvt_pk_bf16_f32 v27, v27, v27
	global_store_short v[74:75], v11, off
	global_store_short v[74:75], v27, off offset:64
	s_mov_b64 s[0:1], 0x8c000
	v_lshl_add_u64 v[68:69], v[66:67], 0, s[0:1]
	v_lshl_add_u64 v[70:71], v[68:69], 0, s[14:15]
	v_lshl_add_u64 v[72:73], v[70:71], 0, s[14:15]
	v_lshl_add_u64 v[74:75], v[72:73], 0, s[14:15]
	v_cvt_pk_bf16_f32 v12, v12, v12
	v_cvt_pk_bf16_f32 v28, v28, v28
	global_store_short v[68:69], v12, off
	global_store_short v[68:69], v28, off offset:64
	v_cvt_pk_bf16_f32 v13, v13, v13
	v_cvt_pk_bf16_f32 v29, v29, v29
	global_store_short v[70:71], v13, off
	global_store_short v[70:71], v29, off offset:64
	v_cvt_pk_bf16_f32 v14, v14, v14
	v_cvt_pk_bf16_f32 v30, v30, v30
	global_store_short v[72:73], v14, off
	global_store_short v[72:73], v30, off offset:64
	v_cvt_pk_bf16_f32 v15, v15, v15
	v_cvt_pk_bf16_f32 v31, v31, v31
	global_store_short v[74:75], v15, off
	global_store_short v[74:75], v31, off offset:64
